# speedup vs baseline: 1.1064x; 1.0177x over previous
; DEV int otid() { int t = threadIdx.x; asm volatile("" : "+v"(t)); return t; }
; template <bool SWAP, class RowA, class Epi>
; DEV void gemm_tile(unsigned char* smem, RowA rowA, const bf16_t* Bt, int K, Epi epi) {
;   const int tid = otid(), lane = tid & 63, wid = tid >> 6, wr = wid >> 1, wc = wid & 1, fr = lane & 15, fq = lane >> 4;
;   const int r0 = tid >> 2;
;   const int a_w = (r0 >> 2) & 3, g_w = (((a_w ^ (a_w >> 1)) & 1) << 1) | (a_w >> 1);
;   const int cc = ((tid & 3) ^ g_w) * 8;
;   const int a_r = (fr >> 2) & 3, g_r = (((a_r ^ (a_r >> 1)) & 1) << 1) | (a_r >> 1);
;   const int rdoff = fr * 64 + ((fq ^ g_r) * 16);
;   const bf16_t* a0 = rowA(r0) + cc;
;   const bf16_t* a1 = rowA(r0 + 64) + cc;
;   const bf16_t* b0 = Bt + (size_t)r0 * K + cc;
;   const bf16_t* b1 = Bt + (size_t)(r0 + 64) * K + cc;
;   f32x4 acc[4][4];
; #pragma unroll
;   for (int m = 0; m < 4; ++m)
; #pragma unroll
;     for (int n = 0; n < 4; ++n) acc[m][n] = f32x4{0.f, 0.f, 0.f, 0.f};
;   const int nk = K / 32;
;   auto stage = [&](int kt, int buf) {
;     unsigned char* SA = smem + buf * 16384 + tid * 16;
;     unsigned char* SB = SA + 8192;
;     const int ko = kt * 32;
;     glds16(a0 + ko, SA); glds16(a1 + ko, SA + 4096);
;     glds16(b0 + ko, SB); glds16(b1 + ko, SB + 4096);
;   };
;   stage(0, 0);
; DEV void phase_qkv(const Params& p, unsigned char* smem) {
;     ...
;   for (int t = blockIdx.x; t < ntile; t += gridDim.x) {
;     int nt = t % 12, mt = t / 12;
;     const bf16_t* A = p.hbuf + (size_t)mt * 128 * 1024;
;     if (nt < 10) {
.LBB0_174:
	s_mul_hi_i32 s0, s8, 0x2aaaaaab
	s_lshr_b32 s1, s0, 31
	s_ashr_i32 s0, s0, 1
	s_add_i32 s0, s0, s1
	s_mul_i32 s1, s0, 12
	s_sub_i32 s34, s8, s1
	s_ashr_i32 s1, s0, 31
	v_readlane_b32 s44, v165, 23
	s_lshl_b64 s[36:37], s[0:1], 18
	v_readlane_b32 s54, v165, 33
	v_readlane_b32 s55, v165, 34
	v_readlane_b32 s56, v165, 35
	v_readlane_b32 s57, v165, 36
	v_readlane_b32 s58, v165, 37
	v_readlane_b32 s59, v165, 38
	s_add_u32 s36, s54, s36
	v_readlane_b32 s56, v165, 39
	s_addc_u32 s37, s55, s37
	v_readlane_b32 s57, v165, 40
	v_readlane_b32 s58, v165, 41
	v_readlane_b32 s59, v165, 42
	v_readlane_b32 s60, v165, 43
	v_readlane_b32 s61, v165, 44
	v_readlane_b32 s62, v165, 45
	v_readlane_b32 s63, v165, 46
	v_readlane_b32 s64, v165, 47
	v_readlane_b32 s65, v165, 48
	v_readlane_b32 s66, v165, 49
	v_readlane_b32 s67, v165, 50
	v_readlane_b32 s68, v165, 51
	v_readlane_b32 s69, v165, 52
	v_readlane_b32 s70, v165, 53
	v_readlane_b32 s71, v165, 54
	s_cmp_gt_i32 s34, 9
	s_mov_b64 s[38:39], -1
	v_readlane_b32 s45, v165, 24
	v_readlane_b32 s46, v165, 25
	v_readlane_b32 s47, v165, 26
	v_readlane_b32 s48, v165, 27
	v_readlane_b32 s49, v165, 28
	v_readlane_b32 s50, v165, 29
	v_readlane_b32 s51, v165, 30
	v_readlane_b32 s52, v165, 31
	v_readlane_b32 s53, v165, 32
	s_cbranch_scc0 .LBB0_194
	v_mov_b32_e32 v8, v122
	s_mov_b32 s35, s9
	v_lshrrev_b32_e32 v1, 4, v8
	v_lshrrev_b32_e32 v2, 5, v8
	v_xor_b32_e32 v1, v1, v2
	v_lshlrev_b32_e32 v1, 1, v1
	v_readlane_b32 s72, v165, 7
	v_ashrrev_i32_e32 v0, 2, v8
	v_bfe_u32 v3, v8, 5, 1
	v_and_b32_e32 v1, 2, v1
	v_and_b32_e32 v2, 3, v8
	s_lshl_b64 s[38:39], s[34:35], 18
	v_readlane_b32 s80, v165, 15
	v_bitop3_b32 v9, v1, v2, v3 bitop3:0x36
	v_ashrrev_i32_e32 v1, 31, v0
	v_readlane_b32 s81, v165, 16
	s_add_u32 s38, s80, s38
	v_lshlrev_b64 v[0:1], 11, v[0:1]
	s_addc_u32 s39, s81, s39
	v_lshl_add_u64 v[2:3], v[0:1], 0, s[22:23]
	v_lshl_add_u64 v[4:5], s[36:37], 0, v[2:3]
	v_lshl_add_u64 v[6:7], s[38:39], 0, v[0:1]
	v_lshl_add_u64 v[0:1], s[36:37], 0, v[0:1]
	v_lshlrev_b32_e32 v80, 4, v9
	v_lshlrev_b32_e32 v68, 4, v8
	v_lshl_add_u64 v[64:65], v[0:1], 0, v[80:81]
	v_lshl_add_u64 v[0:1], v[4:5], 0, v[80:81]
	v_readfirstlane_b32 s1, v68
	v_add_u32_e32 v5, 0x1000, v68
	s_mov_b32 m0, s1
	v_readfirstlane_b32 s1, v5
	v_add_u32_e32 v4, 0x2000, v68
	s_mov_b32 m0, s1
	v_readfirstlane_b32 s1, v4
	v_add_u32_e32 v0, 0x3000, v68
	v_lshl_add_u64 v[2:3], s[38:39], 0, v[2:3]
	v_lshl_add_u64 v[66:67], v[6:7], 0, v[80:81]
	s_mov_b32 m0, s1
	v_readfirstlane_b32 s1, v0
	v_lshl_add_u64 v[2:3], v[2:3], 0, v[80:81]
	s_mov_b32 m0, s1
	v_lshrrev_b32_e32 v0, 2, v8
	v_lshrrev_b32_e32 v1, 3, v8
	v_xor_b32_e32 v0, v0, v1
	v_lshlrev_b32_e32 v0, 1, v0
	v_bfe_u32 v85, v8, 4, 2
	v_bfe_u32 v2, v8, 3, 1
	v_and_b32_e32 v0, 2, v0
	v_and_b32_e32 v95, 15, v8
	v_bitop3_b32 v0, v0, v85, v2 bitop3:0x36
	v_lshlrev_b32_e32 v1, 6, v95
	v_bfe_u32 v82, v8, 6, 1
	v_ashrrev_i32_e32 v83, 7, v8
	v_lshl_or_b32 v69, v0, 4, v1
	v_mov_b32_e32 v0, 0
	v_lshlrev_b32_e32 v71, 12, v83
	v_lshlrev_b32_e32 v70, 12, v82
	s_mov_b32 s1, 0
	s_mov_b64 s[38:39], 0
	v_mov_b32_e32 v1, v0
	v_mov_b32_e32 v2, v0
	v_mov_b32_e32 v3, v0
	v_mov_b32_e32 v4, v0
	v_mov_b32_e32 v5, v0
	v_mov_b32_e32 v6, v0
	v_mov_b32_e32 v7, v0
	v_mov_b32_e32 v8, v0
	v_mov_b32_e32 v9, v0
	v_mov_b32_e32 v10, v0
	v_mov_b32_e32 v11, v0
	v_mov_b32_e32 v12, v0
	v_mov_b32_e32 v13, v0
	v_mov_b32_e32 v14, v0
	v_mov_b32_e32 v15, v0
	v_mov_b32_e32 v16, v0
	v_mov_b32_e32 v17, v0
	v_mov_b32_e32 v18, v0
	v_mov_b32_e32 v19, v0
	v_mov_b32_e32 v20, v0
	v_mov_b32_e32 v21, v0
	v_mov_b32_e32 v22, v0
	v_mov_b32_e32 v23, v0
	v_mov_b32_e32 v24, v0
	v_mov_b32_e32 v25, v0
	v_mov_b32_e32 v26, v0
	v_mov_b32_e32 v27, v0
	v_mov_b32_e32 v28, v0
	v_mov_b32_e32 v29, v0
	v_mov_b32_e32 v30, v0
	v_mov_b32_e32 v31, v0
	v_mov_b32_e32 v32, v0
	v_mov_b32_e32 v33, v0
	v_mov_b32_e32 v34, v0
	v_mov_b32_e32 v35, v0
	v_mov_b32_e32 v36, v0
	v_mov_b32_e32 v37, v0
	v_mov_b32_e32 v38, v0
	v_mov_b32_e32 v39, v0
	v_mov_b32_e32 v40, v0
	v_mov_b32_e32 v41, v0
	v_mov_b32_e32 v42, v0
	v_mov_b32_e32 v43, v0
	v_mov_b32_e32 v44, v0
	v_mov_b32_e32 v45, v0
	v_mov_b32_e32 v46, v0
	v_mov_b32_e32 v47, v0
	v_mov_b32_e32 v48, v0
	v_mov_b32_e32 v49, v0
	v_mov_b32_e32 v50, v0
	v_mov_b32_e32 v51, v0
	v_mov_b32_e32 v52, v0
	v_mov_b32_e32 v53, v0
	v_mov_b32_e32 v54, v0
	v_mov_b32_e32 v55, v0
	v_mov_b32_e32 v56, v0
	v_mov_b32_e32 v57, v0
	v_mov_b32_e32 v58, v0
	v_mov_b32_e32 v59, v0
	v_mov_b32_e32 v60, v0
	v_mov_b32_e32 v61, v0
	v_mov_b32_e32 v62, v0
	v_mov_b32_e32 v63, v0
	v_readlane_b32 s73, v165, 8
	v_readlane_b32 s74, v165, 9
	v_readlane_b32 s75, v165, 10
	v_readlane_b32 s76, v165, 11
	v_readlane_b32 s77, v165, 12
	v_readlane_b32 s78, v165, 13
	v_readlane_b32 s79, v165, 14
	v_readlane_b32 s82, v165, 17
	v_readlane_b32 s83, v165, 18
	v_readlane_b32 s84, v165, 19
	v_readlane_b32 s85, v165, 20
	v_readlane_b32 s86, v165, 21
	v_readlane_b32 s87, v165, 22
	v_and_b32_e32 v72, 15, v122
	v_bfe_u32 v73, v122, 4, 2
	v_bfe_u32 v74, v122, 1, 3
	v_xor_b32_e32 v73, v73, v74
	v_lshlrev_b32_e32 v73, 4, v73
	v_lshl_or_b32 v69, v72, 7, v73
	v_lshlrev_b32_e32 v71, 1, v71
	v_lshlrev_b32_e32 v70, 1, v70
	v_and_b32_e32 v72, 7, v122
	v_bfe_u32 v73, v122, 4, 3
	v_xor_b32_e32 v72, v72, v73
	v_lshlrev_b32_e32 v72, 4, v72
	v_lshrrev_b32_e32 v73, 3, v122
	v_lshl_or_b32 v72, v73, 11, v72
	v_bfe_u32 v73, v122, 4, 2
	v_lshrrev_b32_e32 v74, 1, v73
	v_xor_b32_e32 v75, v73, v74
	v_and_b32_e32 v75, 1, v75
	v_lshl_or_b32 v74, v75, 1, v74
	v_and_b32_e32 v73, 3, v122
	v_xor_b32_e32 v73, v73, v74
	v_lshlrev_b32_e32 v73, 4, v73
	v_lshrrev_b32_e32 v74, 2, v122
	v_lshl_or_b32 v73, v74, 11, v73
	v_sub_u32_e32 v72, v72, v73
	v_ashrrev_i32_e32 v73, 31, v72
	v_lshl_add_u64 v[64:65], v[64:65], 0, v[72:73]
	v_lshl_add_u64 v[66:67], v[66:67], 0, v[72:73]
	v_mov_b32_e32 v144, 0x10000
	v_mov_b32_e32 v145, 0
; template <bool SWAP, class RowA, class Epi>
; DEV void gemm_tile(unsigned char* smem, RowA rowA, const bf16_t* Bt, int K, Epi epi) {
;     ...
;   for (int t = 0; t < nk; ++t) {
;     asm volatile("s_waitcnt vmcnt(0)" ::: "memory");
;     __syncthreads();
;     if (t + 1 < nk) stage(t + 1, (t + 1) & 1);
;     const unsigned char* SA = smem + (t & 1) * 16384;
;     const unsigned char* SB = SA + 8192;
;     bf16x8 At[4], Bl[4];
; #pragma unroll
;     for (int m = 0; m < 4; ++m) At[m] = *reinterpret_cast<const bf16x8*>(SA + (wr * 64 + m * 16) * 64 + rdoff);
; #pragma unroll
;     for (int n = 0; n < 4; ++n) Bl[n] = *reinterpret_cast<const bf16x8*>(SB + (wc * 64 + n * 16) * 64 + rdoff);
; #pragma unroll
;     for (int m = 0; m < 4; ++m)
; #pragma unroll
;       for (int n = 0; n < 4; ++n)
;         acc[m][n] = SWAP ? __builtin_amdgcn_mfma_f32_16x16x32_bf16(Bl[n], At[m], acc[m][n], 0, 0, 0)
;                          : __builtin_amdgcn_mfma_f32_16x16x32_bf16(At[m], Bl[n], acc[m][n], 0, 0, 0);
; DEV void phase_qkv(const Params& p, unsigned char* smem) {
;     ...
;           const int c0 = nt * 128 + wc * 64;
;           const int kvh = (c0 - 1280) >> 6;
;           float bias[4];
; #pragma unroll
;           for (int n = 0; n < 4; ++n) bias[n] = p.b_qkv[c0 + n * 16 + fr];
; #pragma unroll
;           for (int m = 0; m < 4; ++m) {
;             const int rbase = mt * 128 + wr * 64 + m * 16 + fq * 4;
; #pragma unroll
;             for (int n = 0; n < 4; ++n) {
;               int d = n * 16 + fr;
;               bf16_t* dst;
;               if (rbase < NLAT) { int b = rbase >> 13, tt = rbase & 8191; dst = p.vtl + ((size_t)((b * 4 + kvh) * 64 + d)) * 8192 + tt; }
;               else { int rr = rbase - NLAT, b = rr >> 8, tt = rr & 255; dst = p.vtc + ((size_t)((b * 4 + kvh) * 64 + d)) * 256 + tt; }
.LBB0_176:
	s_bitcmp1_b32 s38, 6
	s_cbranch_scc1 .Lpair_odd_176
	s_waitcnt lgkmcnt(0)
	s_barrier
	v_readfirstlane_b32 s42, v68
	s_mov_b32 m0, s42
	v_lshl_add_u64 v[72:73], v[64:65], 0, s[38:39]
	global_load_lds_dwordx4 v[72:73], off
	s_add_i32 m0, m0, 0x1000
	v_lshl_add_u64 v[74:75], v[72:73], 0, v[144:145]
	global_load_lds_dwordx4 v[74:75], off
	s_add_i32 m0, m0, 0x1000
	v_lshl_add_u64 v[72:73], v[74:75], 0, v[144:145]
	global_load_lds_dwordx4 v[72:73], off
	s_add_i32 m0, m0, 0x1000
	v_lshl_add_u64 v[74:75], v[72:73], 0, v[144:145]
	global_load_lds_dwordx4 v[74:75], off
	s_add_i32 m0, m0, 0x1000
	v_lshl_add_u64 v[72:73], v[66:67], 0, s[38:39]
	global_load_lds_dwordx4 v[72:73], off
	s_add_i32 m0, m0, 0x1000
	v_lshl_add_u64 v[74:75], v[72:73], 0, v[144:145]
	global_load_lds_dwordx4 v[74:75], off
	s_add_i32 m0, m0, 0x1000
	v_lshl_add_u64 v[72:73], v[74:75], 0, v[144:145]
	global_load_lds_dwordx4 v[72:73], off
	s_add_i32 m0, m0, 0x1000
	v_lshl_add_u64 v[74:75], v[72:73], 0, v[144:145]
	global_load_lds_dwordx4 v[74:75], off
	s_waitcnt vmcnt(0)
	s_barrier
.Lpair_odd_176:
	s_and_b32 s1, s38, 64
	v_xor_b32_e32 v80, s1, v69
	v_add_u32_e32 v94, v80, v71
	v_add_u32_e32 v80, v80, v70
	ds_read_b128 v[72:75], v94
	ds_read_b128 v[76:79], v80 offset:16384
	ds_read_b128 v[86:89], v80 offset:18432
	ds_read_b128 v[90:93], v80 offset:20480
	ds_read_b128 v[96:99], v80 offset:22528
	s_waitcnt lgkmcnt(0)
	v_mfma_f32_16x16x32_bf16 v[60:63], v[72:75], v[76:79], v[60:63]
	s_add_u32 s38, s38, 64
	s_addc_u32 s39, s39, 0
	s_cmpk_eq_i32 s38, 0x7c0
	v_mfma_f32_16x16x32_bf16 v[56:59], v[72:75], v[86:89], v[56:59]
	v_mfma_f32_16x16x32_bf16 v[52:55], v[72:75], v[90:93], v[52:55]
	v_mfma_f32_16x16x32_bf16 v[48:51], v[72:75], v[96:99], v[48:51]
	ds_read_b128 v[72:75], v94 offset:2048
	s_waitcnt lgkmcnt(0)
	v_mfma_f32_16x16x32_bf16 v[44:47], v[72:75], v[76:79], v[44:47]
	v_mfma_f32_16x16x32_bf16 v[40:43], v[72:75], v[86:89], v[40:43]
	v_mfma_f32_16x16x32_bf16 v[36:39], v[72:75], v[90:93], v[36:39]
	v_mfma_f32_16x16x32_bf16 v[32:35], v[72:75], v[96:99], v[32:35]
	ds_read_b128 v[72:75], v94 offset:4096
	s_waitcnt lgkmcnt(0)
	v_mfma_f32_16x16x32_bf16 v[28:31], v[72:75], v[76:79], v[28:31]
	v_mfma_f32_16x16x32_bf16 v[24:27], v[72:75], v[86:89], v[24:27]
	v_mfma_f32_16x16x32_bf16 v[20:23], v[72:75], v[90:93], v[20:23]
	v_mfma_f32_16x16x32_bf16 v[16:19], v[72:75], v[96:99], v[16:19]
	ds_read_b128 v[72:75], v94 offset:6144
	s_waitcnt lgkmcnt(0)
	v_mfma_f32_16x16x32_bf16 v[12:15], v[72:75], v[76:79], v[12:15]
	v_mfma_f32_16x16x32_bf16 v[8:11], v[72:75], v[86:89], v[8:11]
	v_mfma_f32_16x16x32_bf16 v[4:7], v[72:75], v[90:93], v[4:7]
	v_mfma_f32_16x16x32_bf16 v[0:3], v[72:75], v[96:99], v[0:3]
	s_cbranch_scc0 .LBB0_176
	v_xor_b32_e32 v146, 64, v69
	v_add_u32_e32 v94, v146, v71
	s_waitcnt vmcnt(0)
	s_waitcnt vmcnt(0)
	s_barrier
	ds_read_b128 v[86:89], v94
	v_add_u32_e32 v64, v146, v70
	ds_read_b128 v[76:79], v64 offset:16384
	ds_read_b128 v[72:75], v64 offset:18432
	ds_read_b128 v[68:71], v64 offset:20480
	ds_read_b128 v[64:67], v64 offset:22528
	s_lshl_b32 s1, s34, 7
	s_waitcnt lgkmcnt(3)
	v_mfma_f32_16x16x32_bf16 v[60:63], v[86:89], v[76:79], v[60:63]
	v_readlane_b32 s72, v166, 39
	v_readlane_b32 s74, v166, 41
	v_readlane_b32 s75, v166, 42
	s_waitcnt lgkmcnt(2)
	v_mfma_f32_16x16x32_bf16 v[56:59], v[86:89], v[72:75], v[56:59]
	ds_read_b128 v[90:93], v94 offset:2048
	v_mov_b32_e32 v103, s56
	v_mov_b64_e32 v[98:99], 9
	s_waitcnt lgkmcnt(2)
	v_mfma_f32_16x16x32_bf16 v[52:55], v[86:89], v[68:71], v[52:55]
	v_readlane_b32 s73, v166, 40
	v_readlane_b32 s76, v166, 43
	v_readlane_b32 s77, v166, 44
	s_waitcnt lgkmcnt(1)
	v_mfma_f32_16x16x32_bf16 v[48:51], v[86:89], v[64:67], v[48:51]
	v_lshl_or_b32 v87, v82, 6, s1
	v_or_b32_e32 v80, v87, v95
	v_lshl_add_u64 v[96:97], v[80:81], 2, s[74:75]
	global_load_dword v88, v[96:97], off
	global_load_dword v86, v[96:97], off offset:64
	global_load_dword v84, v[96:97], off offset:128
	global_load_dword v82, v[96:97], off offset:192
	ds_read_b128 v[104:107], v94 offset:4096
	ds_read_b128 v[110:113], v94 offset:6144
	s_lshl_b32 s1, s0, 7
	v_lshlrev_b32_e32 v80, 2, v85
	v_lshl_add_u32 v83, v83, 6, s1
	s_movk_i32 s1, 0xcc
	s_waitcnt lgkmcnt(2)
	v_mfma_f32_16x16x32_bf16 v[44:47], v[90:93], v[76:79], v[44:47]
	v_or_b32_e32 v102, v83, v80
	v_cmp_gt_i32_e32 vcc, s2, v102
	v_mov_b32_e32 v85, s59
	v_mfma_f32_16x16x32_bf16 v[40:43], v[90:93], v[72:75], v[40:43]
	v_mov_b32_e32 v89, s57
	v_mov_b64_e32 v[96:97], s[58:59]
	v_readlane_b32 s78, v166, 45
	v_mfma_f32_16x16x32_bf16 v[36:39], v[90:93], v[68:71], v[36:39]
	v_readlane_b32 s79, v166, 46
	v_readlane_b32 s80, v166, 47
	v_readlane_b32 s81, v166, 48
	v_mfma_f32_16x16x32_bf16 v[32:35], v[90:93], v[64:67], v[32:35]
	v_mov_b64_e32 v[90:91], 9
	v_bitop3_b32 v92, v83, s1, v80 bitop3:0xc8
	s_movk_i32 s1, 0x1fcc
	v_and_b32_e32 v91, 0xffffff00, v83
	v_bitop3_b32 v94, v83, s1, v80 bitop3:0xc8
	v_ashrrev_i32_e32 v80, 5, v83
	s_movk_i32 s1, 0xbb00
	v_add3_u32 v100, v87, v91, s1
	v_and_b32_e32 v80, 0xffffff00, v80
	s_movk_i32 s1, 0xfb00
	v_add3_u32 v101, v87, v80, s1
	s_waitcnt lgkmcnt(1)
	v_mfma_f32_16x16x32_bf16 v[24:27], v[104:107], v[72:75], v[24:27]
	v_mov_b32_e32 v93, s58
	v_mov_b32_e32 v83, v100
	v_readlane_b32 s82, v166, 49
	s_waitcnt lgkmcnt(0)
; DEV unsigned pack2(float a, float b) { return (unsigned)f2bf(a) | ((unsigned)f2bf(b) << 16); }
; DEV void phase_qkv(const Params& p, unsigned char* smem) {
;     ...
;           for (int m = 0; m < 4; ++m) {
;             const int rbase = mt * 128 + wr * 64 + m * 16 + fq * 4;
; #pragma unroll
;             for (int n = 0; n < 4; ++n) {
;               int d = n * 16 + fr;
;               bf16_t* dst;
;               if (rbase < NLAT) { int b = rbase >> 13, tt = rbase & 8191; dst = p.vtl + ((size_t)((b * 4 + kvh) * 64 + d)) * 8192 + tt; }
;               else { int rr = rbase - NLAT, b = rr >> 8, tt = rr & 255; dst = p.vtc + ((size_t)((b * 4 + kvh) * 64 + d)) * 256 + tt; }
;               *reinterpret_cast<uint2*>(dst) = make_uint2(pack2(acc[m][n][0] + bias[n], acc[m][n][1] + bias[n]),
;                                                           pack2(acc[m][n][2] + bias[n], acc[m][n][3] + bias[n]));
	v_mfma_f32_16x16x32_bf16 v[8:11], v[110:113], v[72:75], v[8:11]
	v_cndmask_b32_e32 v72, v100, v101, vcc
	v_or_b32_e32 v72, v72, v95
	v_ashrrev_i32_e32 v73, 31, v72
	v_mfma_f32_16x16x32_bf16 v[28:31], v[104:107], v[76:79], v[28:31]
	v_readlane_b32 s83, v166, 50
	v_readlane_b32 s84, v166, 51
	v_readlane_b32 s85, v166, 52
	v_mfma_f32_16x16x32_bf16 v[12:15], v[110:113], v[76:79], v[12:15]
	v_cndmask_b32_e64 v76, 9, 14, vcc
	v_cndmask_b32_e32 v77, v92, v94, vcc
	v_lshlrev_b32_e32 v80, 1, v77
	v_mfma_f32_16x16x32_bf16 v[20:23], v[104:107], v[68:71], v[20:23]
	v_readlane_b32 s86, v166, 53
	v_readlane_b32 s87, v166, 54
	v_mfma_f32_16x16x32_bf16 v[16:19], v[104:107], v[64:67], v[16:19]
	v_cndmask_b32_e32 v105, v85, v89, vcc
	v_cndmask_b32_e32 v104, v93, v103, vcc
	v_mfma_f32_16x16x32_bf16 v[4:7], v[110:113], v[68:71], v[4:7]
	v_lshlrev_b64 v[68:69], v76, v[72:73]
	v_lshl_add_u64 v[68:69], v[104:105], 0, v[68:69]
	v_mfma_f32_16x16x32_bf16 v[0:3], v[110:113], v[64:67], v[0:3]
	v_mov_b32_e32 v67, v62
	v_mov_b32_e32 v62, v61
	v_mov_b32_e32 v66, v60
	v_lshl_add_u64 v[64:65], v[68:69], 0, v[80:81]
	s_waitcnt vmcnt(3)
	v_pk_add_f32 v[62:63], v[62:63], v[88:89] op_sel_hi:[1,0]
	v_pk_add_f32 v[60:61], v[66:67], v[88:89] op_sel_hi:[1,0]
	v_and_b32_sdwa v68, v63, v108 dst_sel:DWORD dst_unused:UNUSED_PAD src0_sel:WORD_1 src1_sel:DWORD
	v_and_b32_sdwa v69, v62, v108 dst_sel:DWORD dst_unused:UNUSED_PAD src0_sel:WORD_1 src1_sel:DWORD
	v_and_b32_sdwa v66, v61, v108 dst_sel:DWORD dst_unused:UNUSED_PAD src0_sel:WORD_1 src1_sel:DWORD
	v_and_b32_sdwa v67, v60, v108 dst_sel:DWORD dst_unused:UNUSED_PAD src0_sel:WORD_1 src1_sel:DWORD
	v_add3_u32 v63, v63, v68, s3
	v_add3_u32 v62, v62, v69, s3
	v_add3_u32 v60, v60, v67, s3
	v_add3_u32 v61, v61, v66, s3
	v_and_b32_e32 v63, 0xffff0000, v63
	v_and_b32_e32 v62, 0xffff0000, v62
	v_or_b32_sdwa v61, v63, v61 dst_sel:DWORD dst_unused:UNUSED_PAD src0_sel:DWORD src1_sel:WORD_1
	v_or_b32_sdwa v60, v62, v60 dst_sel:DWORD dst_unused:UNUSED_PAD src0_sel:DWORD src1_sel:WORD_1
	global_store_dwordx2 v[64:65], v[60:61], off
	v_mov_b64_e32 v[60:61], v[92:93]
	s_and_saveexec_b64 s[38:39], vcc
	v_mov_b64_e32 v[98:99], 14
	v_mov_b64_e32 v[96:97], s[56:57]
	v_mov_b32_e32 v83, v101
	v_mov_b64_e32 v[60:61], v[94:95]
	s_or_b64 exec, exec, s[38:39]
	v_mov_b32_e32 v64, v56
	v_mov_b32_e32 v65, v58
	v_or_b32_e32 v61, 16, v95
	s_waitcnt vmcnt(3)
	v_pk_add_f32 v[64:65], v[64:65], v[86:87] op_sel_hi:[1,0]
	v_mov_b32_e32 v58, v57
	v_or_b32_e32 v62, v83, v61
	v_pk_add_f32 v[56:57], v[58:59], v[86:87] op_sel_hi:[1,0]
	v_and_b32_sdwa v59, v64, v108 dst_sel:DWORD dst_unused:UNUSED_PAD src0_sel:WORD_1 src1_sel:DWORD
	v_ashrrev_i32_e32 v63, 31, v62
	v_lshlrev_b32_e32 v80, 1, v60
	v_add3_u32 v59, v64, v59, s3
	v_and_b32_sdwa v60, v57, v108 dst_sel:DWORD dst_unused:UNUSED_PAD src0_sel:WORD_1 src1_sel:DWORD
	v_and_b32_sdwa v64, v56, v108 dst_sel:DWORD dst_unused:UNUSED_PAD src0_sel:WORD_1 src1_sel:DWORD
	v_lshlrev_b64 v[62:63], v98, v[62:63]
	v_and_b32_sdwa v58, v65, v108 dst_sel:DWORD dst_unused:UNUSED_PAD src0_sel:WORD_1 src1_sel:DWORD
	v_add3_u32 v57, v57, v60, s3
	v_add3_u32 v56, v56, v64, s3
	v_lshl_add_u64 v[62:63], v[96:97], 0, v[62:63]
	v_add3_u32 v58, v65, v58, s3
	v_and_b32_e32 v57, 0xffff0000, v57
	v_and_b32_e32 v56, 0xffff0000, v56
	v_lshl_add_u64 v[62:63], v[62:63], 0, v[80:81]
	v_or_b32_sdwa v57, v57, v58 dst_sel:DWORD dst_unused:UNUSED_PAD src0_sel:DWORD src1_sel:WORD_1
	v_or_b32_sdwa v56, v56, v59 dst_sel:DWORD dst_unused:UNUSED_PAD src0_sel:DWORD src1_sel:WORD_1
	global_store_dwordx2 v[62:63], v[56:57], off
	v_or_b32_e32 v56, 32, v95
	v_mov_b32_e32 v63, v54
	v_mov_b32_e32 v54, v53
	v_or_b32_e32 v58, v83, v56
	v_mov_b32_e32 v62, v52
	s_waitcnt vmcnt(3)
	v_pk_add_f32 v[52:53], v[54:55], v[84:85] op_sel_hi:[1,0]
	v_ashrrev_i32_e32 v59, 31, v58
	v_pk_add_f32 v[62:63], v[62:63], v[84:85] op_sel_hi:[1,0]
	v_and_b32_sdwa v57, v53, v108 dst_sel:DWORD dst_unused:UNUSED_PAD src0_sel:WORD_1 src1_sel:DWORD
	v_and_b32_sdwa v60, v52, v108 dst_sel:DWORD dst_unused:UNUSED_PAD src0_sel:WORD_1 src1_sel:DWORD
	v_lshlrev_b64 v[58:59], v98, v[58:59]
	v_and_b32_sdwa v54, v63, v108 dst_sel:DWORD dst_unused:UNUSED_PAD src0_sel:WORD_1 src1_sel:DWORD
	v_and_b32_sdwa v55, v62, v108 dst_sel:DWORD dst_unused:UNUSED_PAD src0_sel:WORD_1 src1_sel:DWORD
	v_add3_u32 v53, v53, v57, s3
	v_add3_u32 v52, v52, v60, s3
	v_lshl_add_u64 v[58:59], v[96:97], 0, v[58:59]
	v_add3_u32 v55, v62, v55, s3
	v_add3_u32 v54, v63, v54, s3
	v_and_b32_e32 v53, 0xffff0000, v53
	v_and_b32_e32 v52, 0xffff0000, v52
	v_lshl_add_u64 v[58:59], v[58:59], 0, v[80:81]
	v_or_b32_sdwa v53, v53, v54 dst_sel:DWORD dst_unused:UNUSED_PAD src0_sel:DWORD src1_sel:WORD_1
	v_or_b32_sdwa v52, v52, v55 dst_sel:DWORD dst_unused:UNUSED_PAD src0_sel:DWORD src1_sel:WORD_1
	global_store_dwordx2 v[58:59], v[52:53], off
	v_mov_b64_e32 v[52:53], s[58:59]
	v_mov_b32_e32 v54, v100
	s_and_saveexec_b64 s[38:39], vcc
	v_mov_b64_e32 v[90:91], 14
	v_mov_b64_e32 v[52:53], s[56:57]
	v_mov_b32_e32 v54, v101
	v_mov_b64_e32 v[92:93], v[94:95]
	s_or_b64 exec, exec, s[38:39]
	v_or_b32_e32 v57, 48, v95
	v_or_b32_e32 v54, v54, v57
	v_ashrrev_i32_e32 v55, 31, v54
	v_lshlrev_b64 v[54:55], v90, v[54:55]
	v_lshl_add_u64 v[52:53], v[52:53], 0, v[54:55]
	v_mov_b32_e32 v54, v48
	v_mov_b32_e32 v55, v50
	s_waitcnt vmcnt(3)
; DEV unsigned pack2(float a, float b) { return (unsigned)f2bf(a) | ((unsigned)f2bf(b) << 16); }
; DEV void phase_qkv(const Params& p, unsigned char* smem) {
;     ...
;           for (int m = 0; m < 4; ++m) {
;             const int rbase = mt * 128 + wr * 64 + m * 16 + fq * 4;
; #pragma unroll
;             for (int n = 0; n < 4; ++n) {
;               int d = n * 16 + fr;
;               bf16_t* dst;
;               if (rbase < NLAT) { int b = rbase >> 13, tt = rbase & 8191; dst = p.vtl + ((size_t)((b * 4 + kvh) * 64 + d)) * 8192 + tt; }
;               else { int rr = rbase - NLAT, b = rr >> 8, tt = rr & 255; dst = p.vtc + ((size_t)((b * 4 + kvh) * 64 + d)) * 256 + tt; }
;               *reinterpret_cast<uint2*>(dst) = make_uint2(pack2(acc[m][n][0] + bias[n], acc[m][n][1] + bias[n]),
;                                                           pack2(acc[m][n][2] + bias[n], acc[m][n][3] + bias[n]));
	v_pk_add_f32 v[54:55], v[54:55], v[82:83] op_sel_hi:[1,0]
	v_mov_b32_e32 v50, v49
	v_pk_add_f32 v[48:49], v[50:51], v[82:83] op_sel_hi:[1,0]
	v_and_b32_sdwa v50, v55, v108 dst_sel:DWORD dst_unused:UNUSED_PAD src0_sel:WORD_1 src1_sel:DWORD
	v_and_b32_sdwa v51, v54, v108 dst_sel:DWORD dst_unused:UNUSED_PAD src0_sel:WORD_1 src1_sel:DWORD
	v_add3_u32 v51, v54, v51, s3
	v_add3_u32 v50, v55, v50, s3
	v_and_b32_sdwa v54, v49, v108 dst_sel:DWORD dst_unused:UNUSED_PAD src0_sel:WORD_1 src1_sel:DWORD
	v_and_b32_sdwa v55, v48, v108 dst_sel:DWORD dst_unused:UNUSED_PAD src0_sel:WORD_1 src1_sel:DWORD
	v_add3_u32 v49, v49, v54, s3
	v_add3_u32 v48, v48, v55, s3
	v_lshlrev_b32_e32 v80, 1, v92
	v_and_b32_e32 v49, 0xffff0000, v49
	v_and_b32_e32 v48, 0xffff0000, v48
	v_lshl_add_u64 v[52:53], v[52:53], 0, v[80:81]
	v_or_b32_sdwa v49, v49, v50 dst_sel:DWORD dst_unused:UNUSED_PAD src0_sel:DWORD src1_sel:WORD_1
	v_or_b32_sdwa v48, v48, v51 dst_sel:DWORD dst_unused:UNUSED_PAD src0_sel:DWORD src1_sel:WORD_1
	global_store_dwordx2 v[52:53], v[48:49], off
	v_or_b32_e32 v49, 16, v102
	v_cmp_gt_i32_e32 vcc, s2, v49
	v_mov_b32_e32 v51, s57
	s_movk_i32 s1, 0xdc
	v_cndmask_b32_e32 v49, v100, v101, vcc
	v_or_b32_e32 v52, v49, v95
	v_mov_b32_e32 v49, s59
	v_cndmask_b32_e32 v55, v49, v51, vcc
	v_mov_b32_e32 v49, s58
	v_mov_b32_e32 v51, s56
	v_cndmask_b32_e32 v54, v49, v51, vcc
	v_ashrrev_i32_e32 v53, 31, v52
	v_cndmask_b32_e64 v49, 9, 14, vcc
	v_bitop3_b32 v48, v102, s1, 16 bitop3:0xc8
	s_movk_i32 s1, 0x1fdc
	v_lshlrev_b64 v[52:53], v49, v[52:53]
	v_mov_b32_e32 v89, v88
	v_bitop3_b32 v50, v102, s1, 16 bitop3:0xc8
	v_lshl_add_u64 v[52:53], v[54:55], 0, v[52:53]
	v_mov_b32_e32 v55, v46
	v_mov_b32_e32 v46, v45
	v_cndmask_b32_e32 v49, v48, v50, vcc
	v_mov_b32_e32 v54, v44
	v_pk_add_f32 v[44:45], v[46:47], v[88:89]
	v_lshlrev_b32_e32 v80, 1, v49
	v_pk_add_f32 v[54:55], v[54:55], v[88:89]
	v_and_b32_sdwa v49, v45, v108 dst_sel:DWORD dst_unused:UNUSED_PAD src0_sel:WORD_1 src1_sel:DWORD
	v_and_b32_sdwa v51, v44, v108 dst_sel:DWORD dst_unused:UNUSED_PAD src0_sel:WORD_1 src1_sel:DWORD
	v_and_b32_sdwa v46, v55, v108 dst_sel:DWORD dst_unused:UNUSED_PAD src0_sel:WORD_1 src1_sel:DWORD
	v_and_b32_sdwa v47, v54, v108 dst_sel:DWORD dst_unused:UNUSED_PAD src0_sel:WORD_1 src1_sel:DWORD
	v_add3_u32 v45, v45, v49, s3
	v_add3_u32 v44, v44, v51, s3
	v_add3_u32 v47, v54, v47, s3
	v_add3_u32 v46, v55, v46, s3
	v_and_b32_e32 v45, 0xffff0000, v45
	v_and_b32_e32 v44, 0xffff0000, v44
	v_lshl_add_u64 v[52:53], v[52:53], 0, v[80:81]
	v_or_b32_sdwa v45, v45, v46 dst_sel:DWORD dst_unused:UNUSED_PAD src0_sel:DWORD src1_sel:WORD_1
	v_or_b32_sdwa v44, v44, v47 dst_sel:DWORD dst_unused:UNUSED_PAD src0_sel:DWORD src1_sel:WORD_1
	global_store_dwordx2 v[52:53], v[44:45], off
	v_mov_b64_e32 v[44:45], 9
	v_mov_b64_e32 v[46:47], s[58:59]
	v_mov_b32_e32 v45, v100
	v_mov_b64_e32 v[52:53], 9
	v_mov_b64_e32 v[54:55], v[48:49]
	s_and_saveexec_b64 s[38:39], vcc
	v_mov_b64_e32 v[52:53], 14
	v_mov_b64_e32 v[46:47], s[56:57]
	v_mov_b32_e32 v45, v101
	v_mov_b64_e32 v[54:55], v[50:51]
	s_or_b64 exec, exec, s[38:39]
	v_or_b32_e32 v58, v45, v61
	v_ashrrev_i32_e32 v59, 31, v58
	v_lshlrev_b64 v[58:59], v52, v[58:59]
	v_lshl_add_u64 v[58:59], v[46:47], 0, v[58:59]
	v_lshlrev_b32_e32 v80, 1, v54
	v_mov_b32_e32 v87, v86
	v_lshl_add_u64 v[54:55], v[58:59], 0, v[80:81]
	v_mov_b32_e32 v59, v42
	v_mov_b32_e32 v42, v41
	v_mov_b32_e32 v58, v40
	v_pk_add_f32 v[40:41], v[42:43], v[86:87]
	v_pk_add_f32 v[58:59], v[58:59], v[86:87]
	v_and_b32_sdwa v49, v41, v108 dst_sel:DWORD dst_unused:UNUSED_PAD src0_sel:WORD_1 src1_sel:DWORD
	v_and_b32_sdwa v51, v40, v108 dst_sel:DWORD dst_unused:UNUSED_PAD src0_sel:WORD_1 src1_sel:DWORD
	v_and_b32_sdwa v42, v59, v108 dst_sel:DWORD dst_unused:UNUSED_PAD src0_sel:WORD_1 src1_sel:DWORD
	v_and_b32_sdwa v43, v58, v108 dst_sel:DWORD dst_unused:UNUSED_PAD src0_sel:WORD_1 src1_sel:DWORD
	v_add3_u32 v41, v41, v49, s3
	v_add3_u32 v40, v40, v51, s3
	v_add3_u32 v43, v58, v43, s3
	v_add3_u32 v42, v59, v42, s3
	v_and_b32_e32 v41, 0xffff0000, v41
	v_and_b32_e32 v40, 0xffff0000, v40
	v_mov_b32_e32 v85, v84
	v_or_b32_sdwa v41, v41, v42 dst_sel:DWORD dst_unused:UNUSED_PAD src0_sel:DWORD src1_sel:WORD_1
	v_or_b32_sdwa v40, v40, v43 dst_sel:DWORD dst_unused:UNUSED_PAD src0_sel:DWORD src1_sel:WORD_1
	v_mov_b32_e32 v42, v36
	v_mov_b32_e32 v43, v38
	v_pk_add_f32 v[42:43], v[42:43], v[84:85]
	v_mov_b32_e32 v38, v37
	global_store_dwordx2 v[54:55], v[40:41], off
	v_or_b32_e32 v40, v45, v56
	v_pk_add_f32 v[36:37], v[38:39], v[84:85]
	v_and_b32_sdwa v38, v43, v108 dst_sel:DWORD dst_unused:UNUSED_PAD src0_sel:WORD_1 src1_sel:DWORD
	v_and_b32_sdwa v39, v42, v108 dst_sel:DWORD dst_unused:UNUSED_PAD src0_sel:WORD_1 src1_sel:DWORD
	v_ashrrev_i32_e32 v41, 31, v40
	v_add3_u32 v39, v42, v39, s3
	v_add3_u32 v38, v43, v38, s3
	v_and_b32_sdwa v42, v37, v108 dst_sel:DWORD dst_unused:UNUSED_PAD src0_sel:WORD_1 src1_sel:DWORD
	v_and_b32_sdwa v43, v36, v108 dst_sel:DWORD dst_unused:UNUSED_PAD src0_sel:WORD_1 src1_sel:DWORD
	v_lshlrev_b64 v[40:41], v52, v[40:41]
	v_add3_u32 v37, v37, v42, s3
	v_add3_u32 v36, v36, v43, s3
	v_lshl_add_u64 v[40:41], v[46:47], 0, v[40:41]
	v_and_b32_e32 v37, 0xffff0000, v37
	v_and_b32_e32 v36, 0xffff0000, v36
	v_lshl_add_u64 v[40:41], v[40:41], 0, v[80:81]
	v_or_b32_sdwa v37, v37, v38 dst_sel:DWORD dst_unused:UNUSED_PAD src0_sel:DWORD src1_sel:WORD_1
	v_or_b32_sdwa v36, v36, v39 dst_sel:DWORD dst_unused:UNUSED_PAD src0_sel:DWORD src1_sel:WORD_1
	global_store_dwordx2 v[40:41], v[36:37], off
	v_mov_b64_e32 v[36:37], s[58:59]
	v_mov_b32_e32 v38, v100
	s_and_saveexec_b64 s[38:39], vcc
	v_mov_b64_e32 v[44:45], 14
; DEV unsigned pack2(float a, float b) { return (unsigned)f2bf(a) | ((unsigned)f2bf(b) << 16); }
; DEV void phase_qkv(const Params& p, unsigned char* smem) {
;     ...
;           for (int m = 0; m < 4; ++m) {
;             const int rbase = mt * 128 + wr * 64 + m * 16 + fq * 4;
; #pragma unroll
;             for (int n = 0; n < 4; ++n) {
;               int d = n * 16 + fr;
;               bf16_t* dst;
;               if (rbase < NLAT) { int b = rbase >> 13, tt = rbase & 8191; dst = p.vtl + ((size_t)((b * 4 + kvh) * 64 + d)) * 8192 + tt; }
;               else { int rr = rbase - NLAT, b = rr >> 8, tt = rr & 255; dst = p.vtc + ((size_t)((b * 4 + kvh) * 64 + d)) * 256 + tt; }
;               *reinterpret_cast<uint2*>(dst) = make_uint2(pack2(acc[m][n][0] + bias[n], acc[m][n][1] + bias[n]),
;                                                           pack2(acc[m][n][2] + bias[n], acc[m][n][3] + bias[n]));
	v_mov_b64_e32 v[36:37], s[56:57]
	v_mov_b32_e32 v38, v101
	v_mov_b64_e32 v[48:49], v[50:51]
	s_or_b64 exec, exec, s[38:39]
	v_or_b32_e32 v38, v38, v57
	v_ashrrev_i32_e32 v39, 31, v38
	v_lshlrev_b64 v[38:39], v44, v[38:39]
	v_mov_b32_e32 v83, v82
	v_lshl_add_u64 v[36:37], v[36:37], 0, v[38:39]
	v_mov_b32_e32 v38, v32
	v_mov_b32_e32 v39, v34
	v_pk_add_f32 v[38:39], v[38:39], v[82:83]
	v_mov_b32_e32 v34, v33
	v_pk_add_f32 v[32:33], v[34:35], v[82:83]
	v_and_b32_sdwa v34, v39, v108 dst_sel:DWORD dst_unused:UNUSED_PAD src0_sel:WORD_1 src1_sel:DWORD
	v_and_b32_sdwa v35, v38, v108 dst_sel:DWORD dst_unused:UNUSED_PAD src0_sel:WORD_1 src1_sel:DWORD
	v_add3_u32 v35, v38, v35, s3
	v_add3_u32 v34, v39, v34, s3
	v_and_b32_sdwa v38, v33, v108 dst_sel:DWORD dst_unused:UNUSED_PAD src0_sel:WORD_1 src1_sel:DWORD
	v_and_b32_sdwa v39, v32, v108 dst_sel:DWORD dst_unused:UNUSED_PAD src0_sel:WORD_1 src1_sel:DWORD
	v_add3_u32 v33, v33, v38, s3
	v_add3_u32 v32, v32, v39, s3
	v_lshlrev_b32_e32 v80, 1, v48
	v_and_b32_e32 v33, 0xffff0000, v33
	v_and_b32_e32 v32, 0xffff0000, v32
	v_lshl_add_u64 v[36:37], v[36:37], 0, v[80:81]
	v_or_b32_sdwa v33, v33, v34 dst_sel:DWORD dst_unused:UNUSED_PAD src0_sel:DWORD src1_sel:WORD_1
	v_or_b32_sdwa v32, v32, v35 dst_sel:DWORD dst_unused:UNUSED_PAD src0_sel:DWORD src1_sel:WORD_1
	global_store_dwordx2 v[36:37], v[32:33], off
	v_or_b32_e32 v33, 32, v102
	v_cmp_gt_i32_e32 vcc, s2, v33
	v_mov_b32_e32 v35, s57
	s_movk_i32 s1, 0xec
	v_cndmask_b32_e32 v33, v100, v101, vcc
	v_or_b32_e32 v36, v33, v95
	v_mov_b32_e32 v33, s59
	v_cndmask_b32_e32 v39, v33, v35, vcc
	v_mov_b32_e32 v33, s58
	v_mov_b32_e32 v35, s56
	v_cndmask_b32_e32 v38, v33, v35, vcc
	v_ashrrev_i32_e32 v37, 31, v36
	v_cndmask_b32_e64 v33, 9, 14, vcc
	v_bitop3_b32 v32, v102, s1, 32 bitop3:0xc8
	s_movk_i32 s1, 0x1fec
	v_lshlrev_b64 v[36:37], v33, v[36:37]
	v_bitop3_b32 v34, v102, s1, 32 bitop3:0xc8
	v_lshl_add_u64 v[36:37], v[38:39], 0, v[36:37]
	v_mov_b32_e32 v39, v30
	v_mov_b32_e32 v30, v29
	v_cndmask_b32_e32 v33, v32, v34, vcc
	v_mov_b32_e32 v38, v28
	v_pk_add_f32 v[28:29], v[30:31], v[88:89]
	v_lshlrev_b32_e32 v80, 1, v33
	v_pk_add_f32 v[38:39], v[38:39], v[88:89]
	v_and_b32_sdwa v33, v29, v108 dst_sel:DWORD dst_unused:UNUSED_PAD src0_sel:WORD_1 src1_sel:DWORD
	v_and_b32_sdwa v35, v28, v108 dst_sel:DWORD dst_unused:UNUSED_PAD src0_sel:WORD_1 src1_sel:DWORD
	v_and_b32_sdwa v30, v39, v108 dst_sel:DWORD dst_unused:UNUSED_PAD src0_sel:WORD_1 src1_sel:DWORD
	v_and_b32_sdwa v31, v38, v108 dst_sel:DWORD dst_unused:UNUSED_PAD src0_sel:WORD_1 src1_sel:DWORD
	v_add3_u32 v29, v29, v33, s3
	v_add3_u32 v28, v28, v35, s3
	v_add3_u32 v31, v38, v31, s3
	v_add3_u32 v30, v39, v30, s3
	v_and_b32_e32 v29, 0xffff0000, v29
	v_and_b32_e32 v28, 0xffff0000, v28
	v_lshl_add_u64 v[36:37], v[36:37], 0, v[80:81]
	v_or_b32_sdwa v29, v29, v30 dst_sel:DWORD dst_unused:UNUSED_PAD src0_sel:DWORD src1_sel:WORD_1
	v_or_b32_sdwa v28, v28, v31 dst_sel:DWORD dst_unused:UNUSED_PAD src0_sel:DWORD src1_sel:WORD_1
	global_store_dwordx2 v[36:37], v[28:29], off
	v_mov_b64_e32 v[28:29], 9
	v_mov_b64_e32 v[30:31], s[58:59]
	v_mov_b32_e32 v29, v100
	v_mov_b64_e32 v[36:37], 9
	v_mov_b64_e32 v[38:39], v[32:33]
	s_and_saveexec_b64 s[38:39], vcc
	v_mov_b64_e32 v[36:37], 14
	v_mov_b64_e32 v[30:31], s[56:57]
	v_mov_b32_e32 v29, v101
	v_mov_b64_e32 v[38:39], v[34:35]
	s_or_b64 exec, exec, s[38:39]
	v_or_b32_e32 v40, v29, v61
	v_ashrrev_i32_e32 v41, 31, v40
	v_lshlrev_b64 v[40:41], v36, v[40:41]
	v_lshl_add_u64 v[40:41], v[30:31], 0, v[40:41]
	v_lshlrev_b32_e32 v80, 1, v38
	v_lshl_add_u64 v[38:39], v[40:41], 0, v[80:81]
	v_mov_b32_e32 v41, v26
	v_mov_b32_e32 v26, v25
	v_mov_b32_e32 v40, v24
	v_pk_add_f32 v[24:25], v[26:27], v[86:87]
	v_pk_add_f32 v[40:41], v[40:41], v[86:87]
	v_and_b32_sdwa v33, v25, v108 dst_sel:DWORD dst_unused:UNUSED_PAD src0_sel:WORD_1 src1_sel:DWORD
	v_and_b32_sdwa v35, v24, v108 dst_sel:DWORD dst_unused:UNUSED_PAD src0_sel:WORD_1 src1_sel:DWORD
	v_and_b32_sdwa v26, v41, v108 dst_sel:DWORD dst_unused:UNUSED_PAD src0_sel:WORD_1 src1_sel:DWORD
	v_and_b32_sdwa v27, v40, v108 dst_sel:DWORD dst_unused:UNUSED_PAD src0_sel:WORD_1 src1_sel:DWORD
	v_add3_u32 v25, v25, v33, s3
	v_add3_u32 v24, v24, v35, s3
	v_add3_u32 v27, v40, v27, s3
	v_add3_u32 v26, v41, v26, s3
	v_and_b32_e32 v25, 0xffff0000, v25
	v_and_b32_e32 v24, 0xffff0000, v24
	v_or_b32_sdwa v25, v25, v26 dst_sel:DWORD dst_unused:UNUSED_PAD src0_sel:DWORD src1_sel:WORD_1
	v_or_b32_sdwa v24, v24, v27 dst_sel:DWORD dst_unused:UNUSED_PAD src0_sel:DWORD src1_sel:WORD_1
	v_mov_b32_e32 v26, v20
	v_mov_b32_e32 v27, v22
	v_pk_add_f32 v[26:27], v[26:27], v[84:85]
	v_mov_b32_e32 v22, v21
	global_store_dwordx2 v[38:39], v[24:25], off
	v_or_b32_e32 v24, v29, v56
	v_pk_add_f32 v[20:21], v[22:23], v[84:85]
	v_and_b32_sdwa v22, v27, v108 dst_sel:DWORD dst_unused:UNUSED_PAD src0_sel:WORD_1 src1_sel:DWORD
	v_and_b32_sdwa v23, v26, v108 dst_sel:DWORD dst_unused:UNUSED_PAD src0_sel:WORD_1 src1_sel:DWORD
	v_ashrrev_i32_e32 v25, 31, v24
	v_add3_u32 v23, v26, v23, s3
	v_add3_u32 v22, v27, v22, s3
	v_and_b32_sdwa v26, v21, v108 dst_sel:DWORD dst_unused:UNUSED_PAD src0_sel:WORD_1 src1_sel:DWORD
	v_and_b32_sdwa v27, v20, v108 dst_sel:DWORD dst_unused:UNUSED_PAD src0_sel:WORD_1 src1_sel:DWORD
	v_lshlrev_b64 v[24:25], v36, v[24:25]
	v_add3_u32 v21, v21, v26, s3
	v_add3_u32 v20, v20, v27, s3
	v_lshl_add_u64 v[24:25], v[30:31], 0, v[24:25]
	v_and_b32_e32 v21, 0xffff0000, v21
	v_and_b32_e32 v20, 0xffff0000, v20
	v_lshl_add_u64 v[24:25], v[24:25], 0, v[80:81]
	v_or_b32_sdwa v21, v21, v22 dst_sel:DWORD dst_unused:UNUSED_PAD src0_sel:DWORD src1_sel:WORD_1
; DEV unsigned pack2(float a, float b) { return (unsigned)f2bf(a) | ((unsigned)f2bf(b) << 16); }
; DEV void phase_qkv(const Params& p, unsigned char* smem) {
;     ...
;           for (int m = 0; m < 4; ++m) {
;             const int rbase = mt * 128 + wr * 64 + m * 16 + fq * 4;
; #pragma unroll
;             for (int n = 0; n < 4; ++n) {
;               int d = n * 16 + fr;
;               bf16_t* dst;
;               if (rbase < NLAT) { int b = rbase >> 13, tt = rbase & 8191; dst = p.vtl + ((size_t)((b * 4 + kvh) * 64 + d)) * 8192 + tt; }
;               else { int rr = rbase - NLAT, b = rr >> 8, tt = rr & 255; dst = p.vtc + ((size_t)((b * 4 + kvh) * 64 + d)) * 256 + tt; }
;               *reinterpret_cast<uint2*>(dst) = make_uint2(pack2(acc[m][n][0] + bias[n], acc[m][n][1] + bias[n]),
;                                                           pack2(acc[m][n][2] + bias[n], acc[m][n][3] + bias[n]));
	v_or_b32_sdwa v20, v20, v23 dst_sel:DWORD dst_unused:UNUSED_PAD src0_sel:DWORD src1_sel:WORD_1
	global_store_dwordx2 v[24:25], v[20:21], off
	v_mov_b64_e32 v[20:21], s[58:59]
	v_mov_b32_e32 v22, v100
	s_and_saveexec_b64 s[38:39], vcc
	v_mov_b64_e32 v[28:29], 14
	v_mov_b64_e32 v[20:21], s[56:57]
	v_mov_b32_e32 v22, v101
	v_mov_b64_e32 v[32:33], v[34:35]
	s_or_b64 exec, exec, s[38:39]
	v_or_b32_e32 v22, v22, v57
	v_ashrrev_i32_e32 v23, 31, v22
	v_lshlrev_b64 v[22:23], v28, v[22:23]
	v_lshl_add_u64 v[20:21], v[20:21], 0, v[22:23]
	v_mov_b32_e32 v22, v16
	v_mov_b32_e32 v23, v18
	v_pk_add_f32 v[22:23], v[22:23], v[82:83]
	v_mov_b32_e32 v18, v17
	v_pk_add_f32 v[16:17], v[18:19], v[82:83]
	v_and_b32_sdwa v18, v23, v108 dst_sel:DWORD dst_unused:UNUSED_PAD src0_sel:WORD_1 src1_sel:DWORD
	v_and_b32_sdwa v19, v22, v108 dst_sel:DWORD dst_unused:UNUSED_PAD src0_sel:WORD_1 src1_sel:DWORD
	v_add3_u32 v19, v22, v19, s3
	v_add3_u32 v18, v23, v18, s3
	v_and_b32_sdwa v22, v17, v108 dst_sel:DWORD dst_unused:UNUSED_PAD src0_sel:WORD_1 src1_sel:DWORD
	v_and_b32_sdwa v23, v16, v108 dst_sel:DWORD dst_unused:UNUSED_PAD src0_sel:WORD_1 src1_sel:DWORD
	v_add3_u32 v17, v17, v22, s3
	v_add3_u32 v16, v16, v23, s3
	v_lshlrev_b32_e32 v80, 1, v32
	v_and_b32_e32 v17, 0xffff0000, v17
	v_and_b32_e32 v16, 0xffff0000, v16
	v_lshl_add_u64 v[20:21], v[20:21], 0, v[80:81]
	v_or_b32_sdwa v17, v17, v18 dst_sel:DWORD dst_unused:UNUSED_PAD src0_sel:DWORD src1_sel:WORD_1
	v_or_b32_sdwa v16, v16, v19 dst_sel:DWORD dst_unused:UNUSED_PAD src0_sel:DWORD src1_sel:WORD_1
	global_store_dwordx2 v[20:21], v[16:17], off
	v_or_b32_e32 v17, 48, v102
	v_cmp_gt_i32_e32 vcc, s2, v17
	v_mov_b32_e32 v19, s57
	s_movk_i32 s1, 0xfc
	v_cndmask_b32_e32 v17, v100, v101, vcc
	v_or_b32_e32 v20, v17, v95
	v_mov_b32_e32 v17, s59
	v_cndmask_b32_e32 v23, v17, v19, vcc
	v_mov_b32_e32 v17, s58
	v_mov_b32_e32 v19, s56
	v_cndmask_b32_e32 v22, v17, v19, vcc
	v_ashrrev_i32_e32 v21, 31, v20
	v_cndmask_b32_e64 v17, 9, 14, vcc
	v_bitop3_b32 v16, v102, s1, 48 bitop3:0xc8
	s_movk_i32 s1, 0x1ffc
	v_lshlrev_b64 v[20:21], v17, v[20:21]
	v_bitop3_b32 v18, v102, s1, 48 bitop3:0xc8
	v_lshl_add_u64 v[20:21], v[22:23], 0, v[20:21]
	v_mov_b32_e32 v23, v14
	v_mov_b32_e32 v14, v13
	v_cndmask_b32_e32 v17, v16, v18, vcc
	v_mov_b32_e32 v22, v12
	v_pk_add_f32 v[12:13], v[14:15], v[88:89]
	v_lshlrev_b32_e32 v80, 1, v17
	v_pk_add_f32 v[22:23], v[22:23], v[88:89]
	v_and_b32_sdwa v17, v13, v108 dst_sel:DWORD dst_unused:UNUSED_PAD src0_sel:WORD_1 src1_sel:DWORD
	v_and_b32_sdwa v19, v12, v108 dst_sel:DWORD dst_unused:UNUSED_PAD src0_sel:WORD_1 src1_sel:DWORD
	v_and_b32_sdwa v14, v23, v108 dst_sel:DWORD dst_unused:UNUSED_PAD src0_sel:WORD_1 src1_sel:DWORD
	v_and_b32_sdwa v15, v22, v108 dst_sel:DWORD dst_unused:UNUSED_PAD src0_sel:WORD_1 src1_sel:DWORD
	v_add3_u32 v13, v13, v17, s3
	v_add3_u32 v12, v12, v19, s3
	v_add3_u32 v15, v22, v15, s3
	v_add3_u32 v14, v23, v14, s3
	v_and_b32_e32 v13, 0xffff0000, v13
	v_and_b32_e32 v12, 0xffff0000, v12
	v_lshl_add_u64 v[20:21], v[20:21], 0, v[80:81]
	v_or_b32_sdwa v13, v13, v14 dst_sel:DWORD dst_unused:UNUSED_PAD src0_sel:DWORD src1_sel:WORD_1
	v_or_b32_sdwa v12, v12, v15 dst_sel:DWORD dst_unused:UNUSED_PAD src0_sel:DWORD src1_sel:WORD_1
	global_store_dwordx2 v[20:21], v[12:13], off
	v_mov_b64_e32 v[12:13], 9
	v_mov_b64_e32 v[14:15], s[58:59]
	v_mov_b32_e32 v13, v100
	v_mov_b64_e32 v[20:21], 9
	v_mov_b64_e32 v[22:23], v[16:17]
	s_and_saveexec_b64 s[38:39], vcc
	v_mov_b64_e32 v[20:21], 14
	v_mov_b64_e32 v[14:15], s[56:57]
	v_mov_b32_e32 v13, v101
	v_mov_b64_e32 v[22:23], v[18:19]
	s_or_b64 exec, exec, s[38:39]
	v_or_b32_e32 v24, v13, v61
	v_ashrrev_i32_e32 v25, 31, v24
	v_lshlrev_b64 v[24:25], v20, v[24:25]
	v_lshl_add_u64 v[24:25], v[14:15], 0, v[24:25]
	v_lshlrev_b32_e32 v80, 1, v22
	v_lshl_add_u64 v[22:23], v[24:25], 0, v[80:81]
	v_mov_b32_e32 v25, v10
	v_mov_b32_e32 v10, v9
	v_mov_b32_e32 v24, v8
	v_pk_add_f32 v[8:9], v[10:11], v[86:87]
	v_pk_add_f32 v[24:25], v[24:25], v[86:87]
	v_and_b32_sdwa v17, v9, v108 dst_sel:DWORD dst_unused:UNUSED_PAD src0_sel:WORD_1 src1_sel:DWORD
	v_and_b32_sdwa v19, v8, v108 dst_sel:DWORD dst_unused:UNUSED_PAD src0_sel:WORD_1 src1_sel:DWORD
	v_and_b32_sdwa v10, v25, v108 dst_sel:DWORD dst_unused:UNUSED_PAD src0_sel:WORD_1 src1_sel:DWORD
	v_and_b32_sdwa v11, v24, v108 dst_sel:DWORD dst_unused:UNUSED_PAD src0_sel:WORD_1 src1_sel:DWORD
	v_add3_u32 v9, v9, v17, s3
	v_add3_u32 v8, v8, v19, s3
	v_add3_u32 v11, v24, v11, s3
	v_add3_u32 v10, v25, v10, s3
	v_and_b32_e32 v9, 0xffff0000, v9
	v_and_b32_e32 v8, 0xffff0000, v8
	v_or_b32_sdwa v9, v9, v10 dst_sel:DWORD dst_unused:UNUSED_PAD src0_sel:DWORD src1_sel:WORD_1
	v_or_b32_sdwa v8, v8, v11 dst_sel:DWORD dst_unused:UNUSED_PAD src0_sel:DWORD src1_sel:WORD_1
	v_mov_b32_e32 v10, v4
	v_mov_b32_e32 v11, v6
	v_pk_add_f32 v[10:11], v[10:11], v[84:85]
	v_mov_b32_e32 v6, v5
	global_store_dwordx2 v[22:23], v[8:9], off
	v_or_b32_e32 v8, v13, v56
	v_pk_add_f32 v[4:5], v[6:7], v[84:85]
	v_and_b32_sdwa v6, v11, v108 dst_sel:DWORD dst_unused:UNUSED_PAD src0_sel:WORD_1 src1_sel:DWORD
	v_and_b32_sdwa v7, v10, v108 dst_sel:DWORD dst_unused:UNUSED_PAD src0_sel:WORD_1 src1_sel:DWORD
	v_ashrrev_i32_e32 v9, 31, v8
	v_add3_u32 v7, v10, v7, s3
	v_add3_u32 v6, v11, v6, s3
	v_and_b32_sdwa v10, v5, v108 dst_sel:DWORD dst_unused:UNUSED_PAD src0_sel:WORD_1 src1_sel:DWORD
	v_and_b32_sdwa v11, v4, v108 dst_sel:DWORD dst_unused:UNUSED_PAD src0_sel:WORD_1 src1_sel:DWORD
	v_lshlrev_b64 v[8:9], v20, v[8:9]
	v_add3_u32 v5, v5, v10, s3
	v_add3_u32 v4, v4, v11, s3
	v_lshl_add_u64 v[8:9], v[14:15], 0, v[8:9]
	v_and_b32_e32 v5, 0xffff0000, v5
	v_and_b32_e32 v4, 0xffff0000, v4
; DEV unsigned pack2(float a, float b) { return (unsigned)f2bf(a) | ((unsigned)f2bf(b) << 16); }
; DEV int otid() { int t = threadIdx.x; asm volatile("" : "+v"(t)); return t; }
; template <bool SWAP, class RowA, class Epi>
; DEV void gemm_tile(unsigned char* smem, RowA rowA, const bf16_t* Bt, int K, Epi epi) {
;   const int tid = otid(), lane = tid & 63, wid = tid >> 6, wr = wid >> 1, wc = wid & 1, fr = lane & 15, fq = lane >> 4;
;   const int r0 = tid >> 2;
;   const int a_w = (r0 >> 2) & 3, g_w = (((a_w ^ (a_w >> 1)) & 1) << 1) | (a_w >> 1);
;   const int cc = ((tid & 3) ^ g_w) * 8;
;   const int a_r = (fr >> 2) & 3, g_r = (((a_r ^ (a_r >> 1)) & 1) << 1) | (a_r >> 1);
;   const int rdoff = fr * 64 + ((fq ^ g_r) * 16);
;   const bf16_t* a0 = rowA(r0) + cc;
;   const bf16_t* a1 = rowA(r0 + 64) + cc;
;   const bf16_t* b0 = Bt + (size_t)r0 * K + cc;
;   const bf16_t* b1 = Bt + (size_t)(r0 + 64) * K + cc;
;   f32x4 acc[4][4];
; #pragma unroll
;   for (int m = 0; m < 4; ++m)
; #pragma unroll
;     for (int n = 0; n < 4; ++n) acc[m][n] = f32x4{0.f, 0.f, 0.f, 0.f};
;   const int nk = K / 32;
;   auto stage = [&](int kt, int buf) {
;     unsigned char* SA = smem + buf * 16384 + tid * 16;
;     unsigned char* SB = SA + 8192;
;     const int ko = kt * 32;
;     glds16(a0 + ko, SA); glds16(a1 + ko, SA + 4096);
;     glds16(b0 + ko, SB); glds16(b1 + ko, SB + 4096);
;   };
;   stage(0, 0);
; DEV void phase_qkv(const Params& p, unsigned char* smem) {
;     ...
;           for (int m = 0; m < 4; ++m) {
;             const int rbase = mt * 128 + wr * 64 + m * 16 + fq * 4;
; #pragma unroll
;             for (int n = 0; n < 4; ++n) {
;               int d = n * 16 + fr;
;               bf16_t* dst;
;               if (rbase < NLAT) { int b = rbase >> 13, tt = rbase & 8191; dst = p.vtl + ((size_t)((b * 4 + kvh) * 64 + d)) * 8192 + tt; }
;               else { int rr = rbase - NLAT, b = rr >> 8, tt = rr & 255; dst = p.vtc + ((size_t)((b * 4 + kvh) * 64 + d)) * 256 + tt; }
;               *reinterpret_cast<uint2*>(dst) = make_uint2(pack2(acc[m][n][0] + bias[n], acc[m][n][1] + bias[n]),
;                                                           pack2(acc[m][n][2] + bias[n], acc[m][n][3] + bias[n]));
	v_lshl_add_u64 v[8:9], v[8:9], 0, v[80:81]
	v_or_b32_sdwa v5, v5, v6 dst_sel:DWORD dst_unused:UNUSED_PAD src0_sel:DWORD src1_sel:WORD_1
	v_or_b32_sdwa v4, v4, v7 dst_sel:DWORD dst_unused:UNUSED_PAD src0_sel:DWORD src1_sel:WORD_1
	global_store_dwordx2 v[8:9], v[4:5], off
	v_mov_b64_e32 v[4:5], s[58:59]
	s_and_saveexec_b64 s[38:39], vcc
	v_mov_b64_e32 v[12:13], 14
	v_mov_b64_e32 v[4:5], s[56:57]
	v_mov_b32_e32 v100, v101
	v_mov_b64_e32 v[16:17], v[18:19]
	s_or_b64 exec, exec, s[38:39]
	v_or_b32_e32 v6, v100, v57
	v_ashrrev_i32_e32 v7, 31, v6
	v_lshlrev_b64 v[6:7], v12, v[6:7]
	v_lshl_add_u64 v[4:5], v[4:5], 0, v[6:7]
	v_mov_b32_e32 v6, v0
	v_mov_b32_e32 v7, v2
	v_pk_add_f32 v[6:7], v[6:7], v[82:83]
	v_mov_b32_e32 v2, v1
	v_pk_add_f32 v[0:1], v[2:3], v[82:83]
	v_and_b32_sdwa v2, v7, v108 dst_sel:DWORD dst_unused:UNUSED_PAD src0_sel:WORD_1 src1_sel:DWORD
	v_and_b32_sdwa v3, v6, v108 dst_sel:DWORD dst_unused:UNUSED_PAD src0_sel:WORD_1 src1_sel:DWORD
	v_add3_u32 v3, v6, v3, s3
	v_add3_u32 v2, v7, v2, s3
	v_and_b32_sdwa v6, v1, v108 dst_sel:DWORD dst_unused:UNUSED_PAD src0_sel:WORD_1 src1_sel:DWORD
	v_and_b32_sdwa v7, v0, v108 dst_sel:DWORD dst_unused:UNUSED_PAD src0_sel:WORD_1 src1_sel:DWORD
	v_add3_u32 v1, v1, v6, s3
	v_add3_u32 v0, v0, v7, s3
	v_lshlrev_b32_e32 v80, 1, v16
	v_and_b32_e32 v1, 0xffff0000, v1
	v_and_b32_e32 v0, 0xffff0000, v0
	v_lshl_add_u64 v[4:5], v[4:5], 0, v[80:81]
	v_or_b32_sdwa v1, v1, v2 dst_sel:DWORD dst_unused:UNUSED_PAD src0_sel:DWORD src1_sel:WORD_1
	v_or_b32_sdwa v0, v0, v3 dst_sel:DWORD dst_unused:UNUSED_PAD src0_sel:DWORD src1_sel:WORD_1
	s_mov_b64 s[38:39], 0
	global_store_dwordx2 v[4:5], v[0:1], off
	s_barrier
.LBB0_194:
	s_and_b64 vcc, exec, s[38:39]
	s_cbranch_vccz .LBB0_173
	v_mov_b32_e32 v8, v122
	s_ashr_i32 s35, s34, 31
	v_lshrrev_b32_e32 v1, 4, v8
	v_lshrrev_b32_e32 v2, 5, v8
	v_xor_b32_e32 v1, v1, v2
	v_lshlrev_b32_e32 v1, 1, v1
	v_readlane_b32 s72, v165, 7
	v_ashrrev_i32_e32 v0, 2, v8
	v_bfe_u32 v3, v8, 5, 1
	v_and_b32_e32 v1, 2, v1
	v_and_b32_e32 v2, 3, v8
	s_lshl_b64 s[38:39], s[34:35], 18
	v_readlane_b32 s80, v165, 15
	v_bitop3_b32 v9, v1, v2, v3 bitop3:0x36
	v_ashrrev_i32_e32 v1, 31, v0
	v_readlane_b32 s81, v165, 16
	s_add_u32 s38, s80, s38
	v_lshlrev_b64 v[0:1], 11, v[0:1]
	s_addc_u32 s39, s81, s39
	v_lshl_add_u64 v[2:3], v[0:1], 0, s[22:23]
	v_lshl_add_u64 v[4:5], s[36:37], 0, v[2:3]
	v_lshl_add_u64 v[6:7], s[38:39], 0, v[0:1]
	v_lshl_add_u64 v[0:1], s[36:37], 0, v[0:1]
	v_lshlrev_b32_e32 v80, 4, v9
	v_lshlrev_b32_e32 v72, 4, v8
	v_lshl_add_u64 v[64:65], v[0:1], 0, v[80:81]
	v_lshl_add_u64 v[0:1], v[4:5], 0, v[80:81]
	v_readfirstlane_b32 s1, v72
	v_add_u32_e32 v5, 0x1000, v72
	s_mov_b32 m0, s1
	v_readfirstlane_b32 s1, v5
	v_add_u32_e32 v4, 0x2000, v72
	s_mov_b32 m0, s1
	v_readfirstlane_b32 s1, v4
	v_add_u32_e32 v0, 0x3000, v72
	v_lshl_add_u64 v[2:3], s[38:39], 0, v[2:3]
	v_lshl_add_u64 v[66:67], v[6:7], 0, v[80:81]
	s_mov_b32 m0, s1
	v_readfirstlane_b32 s1, v0
	v_lshl_add_u64 v[2:3], v[2:3], 0, v[80:81]
	s_mov_b32 m0, s1
	v_lshrrev_b32_e32 v0, 2, v8
	v_lshrrev_b32_e32 v1, 3, v8
	v_xor_b32_e32 v0, v0, v1
	v_lshlrev_b32_e32 v0, 1, v0
	v_bfe_u32 v68, v8, 4, 2
	v_bfe_u32 v2, v8, 3, 1
	v_and_b32_e32 v0, 2, v0
	v_and_b32_e32 v110, 15, v8
	v_bfe_u32 v69, v8, 6, 1
	v_bitop3_b32 v0, v0, v68, v2 bitop3:0x36
	v_ashrrev_i32_e32 v71, 7, v8
	v_lshlrev_b32_e32 v70, 6, v110
	v_mov_b32_e32 v28, 0
	v_lshl_or_b32 v73, v0, 4, v70
	v_lshlrev_b32_e32 v74, 12, v71
	v_lshlrev_b32_e32 v75, 12, v69
	s_mov_b32 s1, 0
	s_mov_b64 s[36:37], 0
	v_mov_b32_e32 v29, v28
	v_mov_b32_e32 v30, v28
	v_mov_b32_e32 v31, v28
	v_mov_b32_e32 v24, v28
	v_mov_b32_e32 v25, v28
	v_mov_b32_e32 v26, v28
	v_mov_b32_e32 v27, v28
	v_mov_b32_e32 v20, v28
	v_mov_b32_e32 v21, v28
	v_mov_b32_e32 v22, v28
	v_mov_b32_e32 v23, v28
	v_mov_b32_e32 v4, v28
	v_mov_b32_e32 v5, v28
	v_mov_b32_e32 v6, v28
	v_mov_b32_e32 v7, v28
	v_mov_b32_e32 v0, v28
	v_mov_b32_e32 v1, v28
	v_mov_b32_e32 v2, v28
	v_mov_b32_e32 v3, v28
	v_mov_b32_e32 v8, v28
	v_mov_b32_e32 v9, v28
	v_mov_b32_e32 v10, v28
	v_mov_b32_e32 v11, v28
	v_mov_b32_e32 v12, v28
	v_mov_b32_e32 v13, v28
	v_mov_b32_e32 v14, v28
	v_mov_b32_e32 v15, v28
	v_mov_b32_e32 v16, v28
	v_mov_b32_e32 v17, v28
	v_mov_b32_e32 v18, v28
	v_mov_b32_e32 v19, v28
	v_mov_b32_e32 v32, v28
	v_mov_b32_e32 v33, v28
	v_mov_b32_e32 v34, v28
	v_mov_b32_e32 v35, v28
	v_mov_b32_e32 v36, v28
	v_mov_b32_e32 v37, v28
	v_mov_b32_e32 v38, v28
	v_mov_b32_e32 v39, v28
	v_mov_b32_e32 v40, v28
	v_mov_b32_e32 v41, v28
	v_mov_b32_e32 v42, v28
	v_mov_b32_e32 v43, v28
	v_mov_b32_e32 v44, v28
	v_mov_b32_e32 v45, v28
	v_mov_b32_e32 v46, v28
	v_mov_b32_e32 v47, v28
	v_mov_b32_e32 v48, v28
	v_mov_b32_e32 v49, v28
	v_mov_b32_e32 v50, v28
	v_mov_b32_e32 v51, v28
	v_mov_b32_e32 v52, v28
	v_mov_b32_e32 v53, v28
	v_mov_b32_e32 v54, v28
	v_mov_b32_e32 v55, v28
	v_mov_b32_e32 v56, v28
	v_mov_b32_e32 v57, v28
	v_mov_b32_e32 v58, v28
	v_mov_b32_e32 v59, v28
	v_mov_b32_e32 v60, v28
	v_mov_b32_e32 v61, v28
	v_mov_b32_e32 v62, v28
	v_mov_b32_e32 v63, v28
	v_readlane_b32 s73, v165, 8
	v_readlane_b32 s74, v165, 9
	v_readlane_b32 s75, v165, 10
	v_readlane_b32 s76, v165, 11
	v_readlane_b32 s77, v165, 12
	v_readlane_b32 s78, v165, 13
	v_readlane_b32 s79, v165, 14
	v_readlane_b32 s82, v165, 17
	v_readlane_b32 s83, v165, 18
	v_readlane_b32 s84, v165, 19
	v_readlane_b32 s85, v165, 20
	v_readlane_b32 s86, v165, 21
	v_readlane_b32 s87, v165, 22
	v_and_b32_e32 v76, 15, v122
	v_bfe_u32 v77, v122, 4, 2
	v_bfe_u32 v78, v122, 1, 3
	v_xor_b32_e32 v77, v77, v78
	v_lshlrev_b32_e32 v77, 4, v77
	v_lshl_or_b32 v73, v76, 7, v77
	v_lshlrev_b32_e32 v74, 1, v74
	v_lshlrev_b32_e32 v75, 1, v75
	v_and_b32_e32 v76, 7, v122
	v_bfe_u32 v77, v122, 4, 3
	v_xor_b32_e32 v76, v76, v77
	v_lshlrev_b32_e32 v76, 4, v76
	v_lshrrev_b32_e32 v77, 3, v122
	v_lshl_or_b32 v76, v77, 11, v76
	v_bfe_u32 v77, v122, 4, 2
	v_lshrrev_b32_e32 v78, 1, v77
	v_xor_b32_e32 v79, v77, v78
	v_and_b32_e32 v79, 1, v79
	v_lshl_or_b32 v78, v79, 1, v78
	v_and_b32_e32 v77, 3, v122
	v_xor_b32_e32 v77, v77, v78
	v_lshlrev_b32_e32 v77, 4, v77
	v_lshrrev_b32_e32 v78, 2, v122
	v_lshl_or_b32 v77, v78, 11, v77
	v_sub_u32_e32 v76, v76, v77
	v_ashrrev_i32_e32 v77, 31, v76
	v_lshl_add_u64 v[64:65], v[64:65], 0, v[76:77]
	v_lshl_add_u64 v[66:67], v[66:67], 0, v[76:77]
	v_mov_b32_e32 v144, 0x10000
	v_mov_b32_e32 v145, 0
; template <bool SWAP, class RowA, class Epi>
; DEV void gemm_tile(unsigned char* smem, RowA rowA, const bf16_t* Bt, int K, Epi epi) {
;     ...
;   for (int t = 0; t < nk; ++t) {
;     asm volatile("s_waitcnt vmcnt(0)" ::: "memory");
;     __syncthreads();
;     if (t + 1 < nk) stage(t + 1, (t + 1) & 1);
;     const unsigned char* SA = smem + (t & 1) * 16384;
;     const unsigned char* SB = SA + 8192;
;     bf16x8 At[4], Bl[4];
; #pragma unroll
;     for (int m = 0; m < 4; ++m) At[m] = *reinterpret_cast<const bf16x8*>(SA + (wr * 64 + m * 16) * 64 + rdoff);
; #pragma unroll
;     for (int n = 0; n < 4; ++n) Bl[n] = *reinterpret_cast<const bf16x8*>(SB + (wc * 64 + n * 16) * 64 + rdoff);
; #pragma unroll
;     for (int m = 0; m < 4; ++m)
; #pragma unroll
;       for (int n = 0; n < 4; ++n)
;         acc[m][n] = SWAP ? __builtin_amdgcn_mfma_f32_16x16x32_bf16(Bl[n], At[m], acc[m][n], 0, 0, 0)
;                          : __builtin_amdgcn_mfma_f32_16x16x32_bf16(At[m], Bl[n], acc[m][n], 0, 0, 0);
;   }
; DEV void phase_qkv(const Params& p, unsigned char* smem) {
;     ...
;         [&](f32x4 (&acc)[4][4], int wr, int wc, int fr, int fq) {
;           const int c0 = nt * 128 + wc * 64;
;           const bool isq = c0 < 1024;
;           const float sc = isq ? 0.125f : 1.f;
;           float4 bias[4];
; #pragma unroll
;           for (int n = 0; n < 4; ++n) bias[n] = *reinterpret_cast<const float4*>(p.b_qkv + c0 + n * 16 + fq * 4);
; #pragma unroll
;           for (int m = 0; m < 4; ++m) {
;             const int row = mt * 128 + wr * 64 + m * 16 + fr;
;             f32x4 x0 = acc[m][0], x1 = acc[m][1], x2 = acc[m][2], x3 = acc[m][3];
;             x0[0] += bias[0].x; x0[1] += bias[0].y; x0[2] += bias[0].z; x0[3] += bias[0].w;
;             x1[0] += bias[1].x; x1[1] += bias[1].y; x1[2] += bias[1].z; x1[3] += bias[1].w;
;             x2[0] += bias[2].x; x2[1] += bias[2].y; x2[2] += bias[2].z; x2[3] += bias[2].w;
;             x3[0] += bias[3].x; x3[1] += bias[3].y; x3[2] += bias[3].z; x3[3] += bias[3].w;
;             if (row < NLAT) {
.LBB0_196:
	s_bitcmp1_b32 s36, 6
	s_cbranch_scc1 .Lpair_odd_196
	s_waitcnt lgkmcnt(0)
	s_barrier
	v_readfirstlane_b32 s38, v72
	s_mov_b32 m0, s38
	v_lshl_add_u64 v[76:77], v[64:65], 0, s[36:37]
	global_load_lds_dwordx4 v[76:77], off
	s_add_i32 m0, m0, 0x1000
	v_lshl_add_u64 v[78:79], v[76:77], 0, v[144:145]
	global_load_lds_dwordx4 v[78:79], off
	s_add_i32 m0, m0, 0x1000
	v_lshl_add_u64 v[76:77], v[78:79], 0, v[144:145]
	global_load_lds_dwordx4 v[76:77], off
	s_add_i32 m0, m0, 0x1000
	v_lshl_add_u64 v[78:79], v[76:77], 0, v[144:145]
	global_load_lds_dwordx4 v[78:79], off
	s_add_i32 m0, m0, 0x1000
	v_lshl_add_u64 v[76:77], v[66:67], 0, s[36:37]
	global_load_lds_dwordx4 v[76:77], off
	s_add_i32 m0, m0, 0x1000
	v_lshl_add_u64 v[78:79], v[76:77], 0, v[144:145]
	global_load_lds_dwordx4 v[78:79], off
	s_add_i32 m0, m0, 0x1000
	v_lshl_add_u64 v[76:77], v[78:79], 0, v[144:145]
	global_load_lds_dwordx4 v[76:77], off
	s_add_i32 m0, m0, 0x1000
	v_lshl_add_u64 v[78:79], v[76:77], 0, v[144:145]
	global_load_lds_dwordx4 v[78:79], off
	s_waitcnt vmcnt(0)
	s_barrier
.Lpair_odd_196:
	s_and_b32 s1, s36, 64
	v_xor_b32_e32 v80, s1, v73
	v_add_u32_e32 v98, v80, v74
	v_add_u32_e32 v80, v80, v75
	ds_read_b128 v[76:79], v80 offset:16384
	ds_read_b128 v[82:85], v98
	ds_read_b128 v[86:89], v80 offset:18432
	ds_read_b128 v[90:93], v80 offset:20480
	ds_read_b128 v[94:97], v80 offset:22528
	s_waitcnt lgkmcnt(0)
	v_mfma_f32_16x16x32_bf16 v[60:63], v[76:79], v[82:85], v[60:63]
	s_add_u32 s36, s36, 64
	s_addc_u32 s37, s37, 0
	s_cmpk_eq_i32 s36, 0x7c0
	v_mfma_f32_16x16x32_bf16 v[56:59], v[86:89], v[82:85], v[56:59]
	v_mfma_f32_16x16x32_bf16 v[52:55], v[90:93], v[82:85], v[52:55]
	v_mfma_f32_16x16x32_bf16 v[48:51], v[94:97], v[82:85], v[48:51]
	ds_read_b128 v[82:85], v98 offset:2048
	s_waitcnt lgkmcnt(0)
	v_mfma_f32_16x16x32_bf16 v[44:47], v[76:79], v[82:85], v[44:47]
	v_mfma_f32_16x16x32_bf16 v[40:43], v[86:89], v[82:85], v[40:43]
	v_mfma_f32_16x16x32_bf16 v[36:39], v[90:93], v[82:85], v[36:39]
	v_mfma_f32_16x16x32_bf16 v[32:35], v[94:97], v[82:85], v[32:35]
	ds_read_b128 v[82:85], v98 offset:4096
	s_waitcnt lgkmcnt(0)
	v_mfma_f32_16x16x32_bf16 v[16:19], v[76:79], v[82:85], v[16:19]
	v_mfma_f32_16x16x32_bf16 v[12:15], v[86:89], v[82:85], v[12:15]
	v_mfma_f32_16x16x32_bf16 v[8:11], v[90:93], v[82:85], v[8:11]
	v_mfma_f32_16x16x32_bf16 v[0:3], v[94:97], v[82:85], v[0:3]
	ds_read_b128 v[82:85], v98 offset:6144
	s_waitcnt lgkmcnt(0)
	v_mfma_f32_16x16x32_bf16 v[4:7], v[76:79], v[82:85], v[4:7]
	v_mfma_f32_16x16x32_bf16 v[20:23], v[86:89], v[82:85], v[20:23]
	v_mfma_f32_16x16x32_bf16 v[24:27], v[90:93], v[82:85], v[24:27]
	v_mfma_f32_16x16x32_bf16 v[28:31], v[94:97], v[82:85], v[28:31]
	s_cbranch_scc0 .LBB0_196
	v_xor_b32_e32 v146, 64, v73
	v_add_u32_e32 v80, v146, v75
	s_waitcnt vmcnt(0)
	s_waitcnt vmcnt(0)
	s_barrier
	ds_read_b128 v[76:79], v80 offset:16384
	v_add_u32_e32 v86, v146, v74
	ds_read_b128 v[72:75], v80 offset:18432
	ds_read_b128 v[64:67], v86
	ds_read_b128 v[82:85], v86 offset:2048
	ds_read_b128 v[92:95], v80 offset:20480
	ds_read_b128 v[96:99], v80 offset:22528
	s_waitcnt lgkmcnt(3)
	v_mfma_f32_16x16x32_bf16 v[88:91], v[76:79], v[64:67], v[60:63]
	s_lshl_b32 s1, s34, 7
	v_lshl_or_b32 v80, v69, 6, s1
	v_readlane_b32 s72, v166, 39
	v_mfma_f32_16x16x32_bf16 v[100:103], v[72:75], v[64:67], v[56:59]
	v_readlane_b32 s74, v166, 41
	v_readlane_b32 s75, v166, 42
	s_lshl_b32 s0, s0, 7
	s_waitcnt lgkmcnt(1)
	v_mfma_f32_16x16x32_bf16 v[114:117], v[92:95], v[64:67], v[52:55]
	v_lshl_add_u32 v111, v71, 6, s0
	v_lshlrev_b32_e32 v112, 2, v68
	v_readlane_b32 s73, v166, 40
	s_waitcnt lgkmcnt(0)
	v_mfma_f32_16x16x32_bf16 v[104:107], v[96:99], v[64:67], v[48:51]
	v_ashrrev_i32_e32 v65, 31, v80
	v_mov_b32_e32 v64, v80
	v_readlane_b32 s76, v166, 43
	v_mfma_f32_16x16x32_bf16 v[56:59], v[76:79], v[82:85], v[44:47]
	v_readlane_b32 s77, v166, 44
	v_readlane_b32 s78, v166, 45
	v_readlane_b32 s79, v166, 46
	v_mfma_f32_16x16x32_bf16 v[60:63], v[72:75], v[82:85], v[40:43]
	v_readlane_b32 s80, v166, 47
	v_readlane_b32 s81, v166, 48
	v_readlane_b32 s82, v166, 49
	v_mfma_f32_16x16x32_bf16 v[48:51], v[92:95], v[82:85], v[36:39]
	v_readlane_b32 s83, v166, 50
	v_readlane_b32 s84, v166, 51
	v_readlane_b32 s85, v166, 52
	v_mfma_f32_16x16x32_bf16 v[52:55], v[96:99], v[82:85], v[32:35]
	ds_read_b128 v[44:47], v86 offset:4096
	ds_read_b128 v[82:85], v86 offset:6144
	v_readlane_b32 s86, v166, 53
	v_readlane_b32 s87, v166, 54
	s_waitcnt lgkmcnt(1)
	v_mfma_f32_16x16x32_bf16 v[36:39], v[72:75], v[44:47], v[12:15]
	s_nop 2
	v_lshl_add_u64 v[12:13], v[64:65], 2, s[74:75]
	v_lshlrev_b32_e32 v14, 4, v68
	v_mov_b32_e32 v15, v81
	v_lshl_add_u64 v[66:67], v[12:13], 0, v[14:15]
	v_mfma_f32_16x16x32_bf16 v[32:35], v[76:79], v[44:47], v[16:19]
	global_load_dwordx4 v[12:15], v[66:67], off
	v_and_b32_e32 v68, 0x1fc0, v111
	s_waitcnt vmcnt(0)
	v_add_f32_e32 v87, v90, v14
	v_mfma_f32_16x16x32_bf16 v[40:43], v[92:95], v[44:47], v[8:11]
	v_mov_b32_e32 v90, v103
	v_mfma_f32_16x16x32_bf16 v[44:47], v[96:99], v[44:47], v[0:3]
	global_load_dwordx4 v[16:19], v[66:67], off offset:64
	s_nop 1
	global_load_dwordx4 v[0:3], v[66:67], off offset:128
	s_waitcnt lgkmcnt(0)
	v_mfma_f32_16x16x32_bf16 v[8:11], v[76:79], v[82:85], v[4:7]
	v_or_b32_e32 v76, v111, v110
	v_cmp_gt_i32_e32 vcc, s2, v76
	s_nop 0
	global_load_dwordx4 v[4:7], v[66:67], off offset:192
	v_mfma_f32_16x16x32_bf16 v[20:23], v[72:75], v[82:85], v[20:23]
	v_mov_b32_e32 v75, v15
	v_lshlrev_b32_e32 v66, 2, v112
	s_waitcnt vmcnt(2)
	v_mov_b32_e32 v74, v19
	v_mfma_f32_16x16x32_bf16 v[24:27], v[92:95], v[82:85], v[24:27]
	s_waitcnt vmcnt(1)
	v_mov_b32_e32 v73, v3
	s_waitcnt vmcnt(0)
	v_mov_b32_e32 v72, v7
	v_mfma_f32_16x16x32_bf16 v[28:31], v[96:99], v[82:85], v[28:31]
	v_add_f32_e32 v83, v116, v2
	v_mov_b32_e32 v116, v107
	v_pk_add_f32 v[98:99], v[88:89], v[12:13]
	v_pk_add_f32 v[96:97], v[100:101], v[16:17]
	v_add_f32_e32 v85, v102, v18
	v_pk_add_f32 v[102:103], v[114:115], v[0:1]
	v_pk_add_f32 v[100:101], v[104:105], v[4:5]
	v_add_f32_e32 v79, v106, v6
	v_pk_add_f32 v[106:107], v[90:91], v[74:75]
	v_pk_add_f32 v[104:105], v[116:117], v[72:73]
	v_mov_b32_e32 v78, v100
	v_mov_b32_e32 v88, v101
	v_mov_b32_e32 v82, v102
	v_mov_b32_e32 v90, v103
	v_mov_b32_e32 v84, v96
	v_mov_b32_e32 v92, v97
	v_mov_b32_e32 v86, v98
	v_mov_b32_e32 v94, v99
	v_mov_b32_e32 v89, v104
	v_mov_b32_e32 v91, v105
	v_mov_b32_e32 v93, v106
	v_mov_b32_e32 v95, v107
	s_and_saveexec_b64 s[0:1], vcc
	s_cbranch_execz .LBB0_199
; DEV void phase_qkv(const Params& p, unsigned char* smem) {
;     ...
;             if (row < NLAT) {
;               const int tt = row & 8191, rp = tt >> 6, cp = tt & 63;
;               const float4 cr = *reinterpret_cast<const float4*>(p.rope + rp * 16 + fq * 4);
;               const float4 sr = *reinterpret_cast<const float4*>(p.rope + 2048 + rp * 16 + fq * 4);
;               const float4 cc4 = *reinterpret_cast<const float4*>(p.rope + cp * 16 + fq * 4);
;               const float4 sc4 = *reinterpret_cast<const float4*>(p.rope + 2048 + cp * 16 + fq * 4);
;               const float crv[4] = {cr.x, cr.y, cr.z, cr.w}, srv[4] = {sr.x, sr.y, sr.z, sr.w};
;               const float ccv[4] = {cc4.x, cc4.y, cc4.z, cc4.w}, scv[4] = {sc4.x, sc4.y, sc4.z, sc4.w};
; #pragma unroll
;               for (int j = 0; j < 4; ++j) {
;                 float y0 = x0[j] * crv[j] - x1[j] * srv[j], y1 = x1[j] * crv[j] + x0[j] * srv[j];
;                 float y2 = x2[j] * ccv[j] - x3[j] * scv[j], y3 = x3[j] * ccv[j] + x2[j] * scv[j];
;                 x0[j] = y0; x1[j] = y1; x2[j] = y2; x3[j] = y3;
;               }
;             }
	v_readlane_b32 s72, v165, 7
	v_mov_b32_e32 v69, v81
	v_readlane_b32 s78, v165, 13
	v_readlane_b32 s79, v165, 14
	v_mov_b32_e32 v71, v81
	v_mov_b32_e32 v67, v81
	v_lshl_add_u64 v[114:115], s[78:79], 0, v[68:69]
	v_lshl_add_u64 v[88:89], s[18:19], 0, v[68:69]
	v_lshl_add_u64 v[92:93], s[18:19], 0, v[70:71]
	v_lshl_add_u64 v[70:71], s[78:79], 0, v[70:71]
	v_lshl_add_u64 v[88:89], v[88:89], 0, v[66:67]
	v_lshl_add_u64 v[92:93], v[92:93], 0, v[66:67]
	v_lshl_add_u64 v[114:115], v[114:115], 0, v[66:67]
	v_lshl_add_u64 v[70:71], v[70:71], 0, v[66:67]
	global_load_dwordx4 v[88:91], v[88:89], off
	v_readlane_b32 s73, v165, 8
	global_load_dwordx4 v[92:95], v[92:93], off
	v_readlane_b32 s74, v165, 9
	global_load_dwordx4 v[114:117], v[114:115], off
	v_readlane_b32 s75, v165, 10
	global_load_dwordx4 v[118:121], v[70:71], off
	v_readlane_b32 s76, v165, 11
	v_readlane_b32 s77, v165, 12
	v_readlane_b32 s80, v165, 15
	v_readlane_b32 s81, v165, 16
	v_readlane_b32 s82, v165, 17
	v_readlane_b32 s83, v165, 18
	v_readlane_b32 s84, v165, 19
	v_readlane_b32 s85, v165, 20
	v_readlane_b32 s86, v165, 21
	v_readlane_b32 s87, v165, 22
	s_waitcnt vmcnt(3)
	v_mul_f32_e32 v128, v85, v90
	v_mul_f32_e32 v132, v87, v90
	s_waitcnt vmcnt(2)
	v_mul_f32_e32 v136, v79, v94
	v_mul_f32_e32 v140, v83, v94
	s_waitcnt vmcnt(1)
	v_mul_f32_e32 v126, v87, v116
	v_mul_f32_e32 v130, v85, v116
	s_waitcnt vmcnt(0)
	v_mul_f32_e32 v134, v83, v120
	v_mul_f32_e32 v138, v79, v120
	v_mov_b32_e32 v116, v91
	v_mov_b32_e32 v90, v117
	v_mov_b32_e32 v120, v95
	v_mov_b32_e32 v94, v121
	v_pk_mul_f32 v[116:117], v[106:107], v[116:117]
	v_pk_mul_f32 v[90:91], v[106:107], v[90:91]
	v_pk_mul_f32 v[106:107], v[104:105], v[120:121]
	v_pk_mul_f32 v[94:95], v[104:105], v[94:95]
	v_pk_mul_f32 v[70:71], v[98:99], v[88:89]
	v_pk_mul_f32 v[88:89], v[96:97], v[88:89]
	v_pk_mul_f32 v[124:125], v[102:103], v[92:93]
	v_pk_mul_f32 v[92:93], v[100:101], v[92:93]
	v_mov_b32_e32 v127, v117
	v_mov_b32_e32 v129, v116
	v_mov_b32_e32 v131, v90
	v_mov_b32_e32 v133, v91
	v_mov_b32_e32 v135, v107
	v_mov_b32_e32 v137, v106
	v_mov_b32_e32 v139, v94
	v_mov_b32_e32 v141, v95
	v_pk_fma_f32 v[86:87], v[98:99], v[114:115], v[88:89] neg_lo:[0,0,1] neg_hi:[0,0,1]
	v_pk_fma_f32 v[84:85], v[96:97], v[114:115], v[70:71]
	v_pk_fma_f32 v[82:83], v[102:103], v[118:119], v[92:93] neg_lo:[0,0,1] neg_hi:[0,0,1]
	v_pk_fma_f32 v[78:79], v[100:101], v[118:119], v[124:125]
	v_pk_add_f32 v[70:71], v[126:127], v[128:129] neg_lo:[0,1] neg_hi:[0,1]
	v_pk_add_f32 v[96:97], v[130:131], v[132:133]
	v_pk_add_f32 v[98:99], v[134:135], v[136:137] neg_lo:[0,1] neg_hi:[0,1]
	v_pk_add_f32 v[100:101], v[138:139], v[140:141]
	v_mov_b32_e32 v88, v79
	v_mov_b32_e32 v90, v83
	v_mov_b32_e32 v92, v85
	v_mov_b32_e32 v94, v87
	v_mov_b32_e32 v79, v100
	v_mov_b32_e32 v89, v101
	v_mov_b32_e32 v83, v98
	v_mov_b32_e32 v91, v99
	v_mov_b32_e32 v85, v96
	v_mov_b32_e32 v93, v97
	v_mov_b32_e32 v87, v70
	v_mov_b32_e32 v95, v71

; DEV int otid() { int t = threadIdx.x; asm volatile("" : "+v"(t)); return t; }
; template <bool SWAP, class RowA, class Epi>
; DEV void gemm_tile(unsigned char* smem, RowA rowA, const bf16_t* Bt, int K, Epi epi) {
;   const int tid = otid(), lane = tid & 63, wid = tid >> 6, wr = wid >> 1, wc = wid & 1, fr = lane & 15, fq = lane >> 4;
;   const int r0 = tid >> 2;
;   const int a_w = (r0 >> 2) & 3, g_w = (((a_w ^ (a_w >> 1)) & 1) << 1) | (a_w >> 1);
;   const int cc = ((tid & 3) ^ g_w) * 8;
;   const int a_r = (fr >> 2) & 3, g_r = (((a_r ^ (a_r >> 1)) & 1) << 1) | (a_r >> 1);
;   const int rdoff = fr * 64 + ((fq ^ g_r) * 16);
;   const bf16_t* a0 = rowA(r0) + cc;
;   const bf16_t* a1 = rowA(r0 + 64) + cc;
;   const bf16_t* b0 = Bt + (size_t)r0 * K + cc;
;   const bf16_t* b1 = Bt + (size_t)(r0 + 64) * K + cc;
;   f32x4 acc[4][4];
; #pragma unroll
;   for (int m = 0; m < 4; ++m)
; #pragma unroll
;     for (int n = 0; n < 4; ++n) acc[m][n] = f32x4{0.f, 0.f, 0.f, 0.f};
;   const int nk = K / 32;
;   auto stage = [&](int kt, int buf) {
;     unsigned char* SA = smem + buf * 16384 + tid * 16;
;     unsigned char* SB = SA + 8192;
;     const int ko = kt * 32;
;     glds16(a0 + ko, SA); glds16(a1 + ko, SA + 4096);
;     glds16(b0 + ko, SB); glds16(b1 + ko, SB + 4096);
;   };
;   stage(0, 0);
; DEV void phase_proj_out(const Params& p, const bf16_t* Abuf, const bf16_t* Wt, const float* bias, int nrows, unsigned char* smem, bool drain) {
;     ...
;   for (int t = blockIdx.x; t < ntile; t += gridDim.x) {
;     int nt = t & 7, mt = t >> 3;
;     const bf16_t* A = Abuf + (size_t)mt * 128 * 1024;
;     gemm_tile<true>(smem, [&](int r) { return A + (size_t)r * 1024; }, Wt + (size_t)nt * 128 * 1024, 1024,
.LBB0_342:
	v_mov_b32_e32 v10, v122
	s_ashr_i32 s16, s19, 3
	v_lshrrev_b32_e32 v1, 4, v10
	v_lshrrev_b32_e32 v2, 5, v10
	v_xor_b32_e32 v1, v1, v2
	s_and_b32 s0, s18, 7
	s_ashr_i32 s17, s16, 31
	v_lshlrev_b32_e32 v1, 1, v1
	s_lshl_b32 s8, s0, 18
	s_and_b32 s23, s19, 7
	s_lshl_b64 s[0:1], s[16:17], 18
	v_ashrrev_i32_e32 v0, 2, v10
	v_bfe_u32 v3, v10, 5, 1
	v_and_b32_e32 v1, 2, v1
	v_and_b32_e32 v2, 3, v10
	s_add_u32 s0, s60, s0
	v_bitop3_b32 v11, v1, v2, v3 bitop3:0x36
	v_ashrrev_i32_e32 v1, 31, v0
	s_addc_u32 s1, s61, s1
	v_lshlrev_b64 v[0:1], 11, v[0:1]
	v_readlane_b32 s72, v165, 7
	v_lshl_add_u64 v[2:3], v[0:1], 0, s[30:31]
	v_lshl_add_u64 v[8:9], s[0:1], 0, v[0:1]
	v_lshlrev_b32_e32 v72, 4, v11
	v_lshlrev_b32_e32 v70, 4, v10
	s_lshl_b32 s17, s23, 18
	v_readlane_b32 s82, v165, 17
	v_lshl_add_u64 v[4:5], s[0:1], 0, v[2:3]
	v_lshl_add_u64 v[64:65], v[8:9], 0, v[72:73]
	v_readfirstlane_b32 s0, v70
	v_add_u32_e32 v9, 0x1000, v70
	v_readlane_b32 s83, v165, 18
	s_add_u32 s28, s82, s17
	s_mov_b32 m0, s0
	v_readfirstlane_b32 s0, v9
	s_addc_u32 s29, s83, 0
	v_lshl_add_u64 v[4:5], v[4:5], 0, v[72:73]
	v_add_u32_e32 v8, 0x2000, v70
	s_mov_b32 m0, s0
	v_lshl_add_u64 v[6:7], s[28:29], 0, v[0:1]
	v_readfirstlane_b32 s0, v8
	v_add_u32_e32 v4, 0x3000, v70
	v_lshl_add_u64 v[2:3], s[28:29], 0, v[2:3]
	v_lshl_add_u64 v[6:7], v[6:7], 0, v[72:73]
	s_mov_b32 m0, s0
	v_readfirstlane_b32 s0, v4
	v_lshl_add_u64 v[2:3], v[2:3], 0, v[72:73]
	s_mov_b32 m0, s0
	v_lshrrev_b32_e32 v12, 2, v10
	v_lshrrev_b32_e32 v13, 3, v10
	v_xor_b32_e32 v2, v12, v13
	v_lshlrev_b32_e32 v2, 1, v2
	v_lshl_add_u64 v[0:1], s[8:9], 0, v[0:1]
	v_bfe_u32 v69, v10, 4, 2
	v_bfe_u32 v14, v10, 3, 1
	v_and_b32_e32 v2, 2, v2
	v_and_b32_e32 v75, 15, v10
	v_or_b32_e32 v0, v0, v72
	v_bfe_u32 v68, v10, 6, 1
	v_bitop3_b32 v2, v2, v69, v14 bitop3:0x36
	v_ashrrev_i32_e32 v74, 7, v10
	v_lshlrev_b32_e32 v3, 6, v75
	v_lshl_add_u64 v[66:67], s[82:83], 0, v[0:1]
	v_mov_b32_e32 v0, 0
	v_lshl_or_b32 v71, v2, 4, v3
	v_lshlrev_b32_e32 v77, 12, v74
	v_lshlrev_b32_e32 v78, 12, v68
	s_mov_b32 s8, 0
	s_mov_b64 s[0:1], 0
	v_mov_b32_e32 v1, v0
	v_mov_b32_e32 v2, v0
	v_mov_b32_e32 v3, v0
	v_mov_b32_e32 v4, v0
	v_mov_b32_e32 v5, v0
	v_mov_b32_e32 v6, v0
	v_mov_b32_e32 v7, v0
	v_mov_b32_e32 v8, v0
	v_mov_b32_e32 v9, v0
	v_mov_b32_e32 v10, v0
	v_mov_b32_e32 v11, v0
	v_mov_b32_e32 v12, v0
	v_mov_b32_e32 v13, v0
	v_mov_b32_e32 v14, v0
	v_mov_b32_e32 v15, v0
	v_mov_b32_e32 v16, v0
	v_mov_b32_e32 v17, v0
	v_mov_b32_e32 v18, v0
	v_mov_b32_e32 v19, v0
	s_waitcnt vmcnt(0)
	v_mov_b32_e32 v20, v0
	v_mov_b32_e32 v21, v0
	v_mov_b32_e32 v22, v0
	v_mov_b32_e32 v23, v0
	v_mov_b32_e32 v24, v0
	v_mov_b32_e32 v25, v0
	v_mov_b32_e32 v26, v0
	v_mov_b32_e32 v27, v0
	v_mov_b32_e32 v28, v0
	v_mov_b32_e32 v29, v0
	v_mov_b32_e32 v30, v0
	v_mov_b32_e32 v31, v0
	v_mov_b32_e32 v32, v0
	v_mov_b32_e32 v33, v0
	v_mov_b32_e32 v34, v0
	v_mov_b32_e32 v35, v0
	v_mov_b32_e32 v36, v0
	v_mov_b32_e32 v37, v0
	v_mov_b32_e32 v38, v0
	v_mov_b32_e32 v39, v0
	v_mov_b32_e32 v40, v0
	v_mov_b32_e32 v41, v0
	v_mov_b32_e32 v42, v0
	v_mov_b32_e32 v43, v0
	v_mov_b32_e32 v44, v0
	v_mov_b32_e32 v45, v0
	v_mov_b32_e32 v46, v0
	v_mov_b32_e32 v47, v0
	v_mov_b32_e32 v48, v0
	v_mov_b32_e32 v49, v0
	v_mov_b32_e32 v50, v0
	v_mov_b32_e32 v51, v0
	v_mov_b32_e32 v52, v0
	v_mov_b32_e32 v53, v0
	v_mov_b32_e32 v54, v0
	v_mov_b32_e32 v55, v0
	v_mov_b32_e32 v56, v0
	v_mov_b32_e32 v57, v0
	v_mov_b32_e32 v58, v0
	v_mov_b32_e32 v59, v0
	v_mov_b32_e32 v60, v0
	v_mov_b32_e32 v61, v0
	v_mov_b32_e32 v62, v0
	v_mov_b32_e32 v63, v0
	v_readlane_b32 s73, v165, 8
	v_readlane_b32 s74, v165, 9
	v_readlane_b32 s75, v165, 10
	v_readlane_b32 s76, v165, 11
	v_readlane_b32 s77, v165, 12
	v_readlane_b32 s78, v165, 13
	v_readlane_b32 s79, v165, 14
	v_readlane_b32 s80, v165, 15
	v_readlane_b32 s81, v165, 16
	v_readlane_b32 s84, v165, 19
	v_readlane_b32 s85, v165, 20
	v_readlane_b32 s86, v165, 21
	v_readlane_b32 s87, v165, 22
	v_and_b32_e32 v80, 15, v122
	v_bfe_u32 v81, v122, 4, 2
	v_bfe_u32 v82, v122, 1, 3
	v_xor_b32_e32 v81, v81, v82
	v_lshlrev_b32_e32 v81, 4, v81
	v_lshl_or_b32 v71, v80, 7, v81
	v_lshlrev_b32_e32 v77, 1, v77
	v_lshlrev_b32_e32 v78, 1, v78
	v_and_b32_e32 v80, 7, v122
	v_bfe_u32 v81, v122, 4, 3
	v_xor_b32_e32 v80, v80, v81
	v_lshlrev_b32_e32 v80, 4, v80
	v_lshrrev_b32_e32 v81, 3, v122
	v_lshl_or_b32 v80, v81, 11, v80
	v_bfe_u32 v81, v122, 4, 2
	v_lshrrev_b32_e32 v82, 1, v81
	v_xor_b32_e32 v83, v81, v82
	v_and_b32_e32 v83, 1, v83
	v_lshl_or_b32 v82, v83, 1, v82
	v_and_b32_e32 v81, 3, v122
	v_xor_b32_e32 v81, v81, v82
	v_lshlrev_b32_e32 v81, 4, v81
	v_lshrrev_b32_e32 v82, 2, v122
	v_lshl_or_b32 v81, v82, 11, v81
	v_sub_u32_e32 v80, v80, v81
	v_ashrrev_i32_e32 v81, 31, v80
	v_lshl_add_u64 v[64:65], v[64:65], 0, v[80:81]
	v_lshl_add_u64 v[66:67], v[66:67], 0, v[80:81]
	v_mov_b32_e32 v140, 0x10000
	v_mov_b32_e32 v141, 0
; template <bool SWAP, class RowA, class Epi>
; DEV void gemm_tile(unsigned char* smem, RowA rowA, const bf16_t* Bt, int K, Epi epi) {
;     ...
;   for (int t = 0; t < nk; ++t) {
;     asm volatile("s_waitcnt vmcnt(0)" ::: "memory");
;     __syncthreads();
;     if (t + 1 < nk) stage(t + 1, (t + 1) & 1);
;     const unsigned char* SA = smem + (t & 1) * 16384;
;     const unsigned char* SB = SA + 8192;
;     bf16x8 At[4], Bl[4];
; #pragma unroll
;     for (int m = 0; m < 4; ++m) At[m] = *reinterpret_cast<const bf16x8*>(SA + (wr * 64 + m * 16) * 64 + rdoff);
; #pragma unroll
;     for (int n = 0; n < 4; ++n) Bl[n] = *reinterpret_cast<const bf16x8*>(SB + (wc * 64 + n * 16) * 64 + rdoff);
; #pragma unroll
;     for (int m = 0; m < 4; ++m)
; #pragma unroll
;       for (int n = 0; n < 4; ++n)
;         acc[m][n] = SWAP ? __builtin_amdgcn_mfma_f32_16x16x32_bf16(Bl[n], At[m], acc[m][n], 0, 0, 0)
;                          : __builtin_amdgcn_mfma_f32_16x16x32_bf16(At[m], Bl[n], acc[m][n], 0, 0, 0);
; DEV void phase_proj_out(const Params& p, const bf16_t* Abuf, const bf16_t* Wt, const float* bias, int nrows, unsigned char* smem, bool drain) {
;     ...
;       [&](f32x4 (&acc)[4][4], int wr, int wc, int fr, int fq) {
; #pragma unroll
;         for (int n = 0; n < 4; ++n) {
;           const int col = nt * 128 + wc * 64 + n * 16 + fq * 4;
;           float4 bv = make_float4(0.f, 0.f, 0.f, 0.f);
;           if (bias) bv = *reinterpret_cast<const float4*>(bias + col);
.LBB0_343:
	s_bitcmp1_b32 s0, 6
	s_cbranch_scc1 .Lpair_odd_343
	s_waitcnt lgkmcnt(0)
	s_barrier
	v_readfirstlane_b32 s28, v70
	s_mov_b32 m0, s28
	v_lshl_add_u64 v[80:81], v[64:65], 0, s[0:1]
	global_load_lds_dwordx4 v[80:81], off
	s_add_i32 m0, m0, 0x1000
	v_lshl_add_u64 v[82:83], v[80:81], 0, v[140:141]
	global_load_lds_dwordx4 v[82:83], off
	s_add_i32 m0, m0, 0x1000
	v_lshl_add_u64 v[80:81], v[82:83], 0, v[140:141]
	global_load_lds_dwordx4 v[80:81], off
	s_add_i32 m0, m0, 0x1000
	v_lshl_add_u64 v[82:83], v[80:81], 0, v[140:141]
	global_load_lds_dwordx4 v[82:83], off
	s_add_i32 m0, m0, 0x1000
	v_lshl_add_u64 v[80:81], v[66:67], 0, s[0:1]
	global_load_lds_dwordx4 v[80:81], off
	s_add_i32 m0, m0, 0x1000
	v_lshl_add_u64 v[82:83], v[80:81], 0, v[140:141]
	global_load_lds_dwordx4 v[82:83], off
	s_add_i32 m0, m0, 0x1000
	v_lshl_add_u64 v[80:81], v[82:83], 0, v[140:141]
	global_load_lds_dwordx4 v[80:81], off
	s_add_i32 m0, m0, 0x1000
	v_lshl_add_u64 v[82:83], v[80:81], 0, v[140:141]
	global_load_lds_dwordx4 v[82:83], off
	s_waitcnt vmcnt(0)
	s_barrier
.Lpair_odd_343:
	s_and_b32 s8, s0, 64
	v_xor_b32_e32 v72, s8, v71
	v_add_u32_e32 v79, v72, v77
	v_add_u32_e32 v72, v72, v78
	ds_read_b128 v[80:83], v79
	ds_read_b128 v[84:87], v79 offset:2048
	ds_read_b128 v[88:91], v79 offset:4096
	ds_read_b128 v[92:95], v79 offset:6144
	ds_read_b128 v[96:99], v72 offset:16384
	ds_read_b128 v[100:103], v72 offset:18432
	ds_read_b128 v[104:107], v72 offset:20480
	ds_read_b128 v[108:111], v72 offset:22528
	s_waitcnt lgkmcnt(0)
	v_mfma_f32_16x16x32_bf16 v[60:63], v[96:99], v[80:83], v[60:63]
	s_add_u32 s0, s0, 64
	s_addc_u32 s1, s1, 0
	s_cmpk_eq_i32 s0, 0x7c0
	v_mfma_f32_16x16x32_bf16 v[56:59], v[100:103], v[80:83], v[56:59]
	v_mfma_f32_16x16x32_bf16 v[52:55], v[104:107], v[80:83], v[52:55]
	v_mfma_f32_16x16x32_bf16 v[48:51], v[108:111], v[80:83], v[48:51]
	v_mfma_f32_16x16x32_bf16 v[44:47], v[96:99], v[84:87], v[44:47]
	v_mfma_f32_16x16x32_bf16 v[40:43], v[100:103], v[84:87], v[40:43]
	v_mfma_f32_16x16x32_bf16 v[36:39], v[104:107], v[84:87], v[36:39]
	v_mfma_f32_16x16x32_bf16 v[32:35], v[108:111], v[84:87], v[32:35]
	v_mfma_f32_16x16x32_bf16 v[28:31], v[96:99], v[88:91], v[28:31]
	v_mfma_f32_16x16x32_bf16 v[24:27], v[100:103], v[88:91], v[24:27]
	v_mfma_f32_16x16x32_bf16 v[20:23], v[104:107], v[88:91], v[20:23]
	v_mfma_f32_16x16x32_bf16 v[16:19], v[108:111], v[88:91], v[16:19]
	v_mfma_f32_16x16x32_bf16 v[12:15], v[96:99], v[92:95], v[12:15]
	v_mfma_f32_16x16x32_bf16 v[8:11], v[100:103], v[92:95], v[8:11]
	v_mfma_f32_16x16x32_bf16 v[4:7], v[104:107], v[92:95], v[4:7]
	v_mfma_f32_16x16x32_bf16 v[0:3], v[108:111], v[92:95], v[0:3]
	s_cbranch_scc0 .LBB0_343
	v_xor_b32_e32 v142, 64, v71
	v_add_u32_e32 v70, v142, v78
	s_waitcnt vmcnt(0)
	s_waitcnt vmcnt(0)
	s_barrier
	ds_read_b128 v[78:81], v70 offset:16384
	ds_read_b128 v[82:85], v70 offset:18432
	ds_read_b128 v[86:89], v70 offset:20480
	ds_read_b128 v[90:93], v70 offset:22528
	v_add_u32_e32 v71, v142, v77
	ds_read_b128 v[64:67], v71
	ds_read_b128 v[94:97], v71 offset:2048
	s_waitcnt lgkmcnt(1)
	v_mfma_f32_16x16x32_bf16 v[60:63], v[78:81], v[64:67], v[60:63]
	v_lshlrev_b32_e32 v68, 6, v68
	v_lshlrev_b32_e32 v69, 2, v69
	s_lshl_b32 s0, s23, 7
	v_mfma_f32_16x16x32_bf16 v[56:59], v[82:85], v[64:67], v[56:59]
	s_andn2_b64 vcc, exec, s[6:7]
	v_mov_b32_e32 v70, 0
	v_mfma_f32_16x16x32_bf16 v[52:55], v[86:89], v[64:67], v[52:55]
	v_mfma_f32_16x16x32_bf16 v[48:51], v[90:93], v[64:67], v[48:51]
	s_waitcnt lgkmcnt(0)
	v_mfma_f32_16x16x32_bf16 v[64:67], v[78:81], v[94:97], v[44:47]
	v_mfma_f32_16x16x32_bf16 v[40:43], v[82:85], v[94:97], v[40:43]
	s_nop 1
	ds_read_b128 v[44:47], v71 offset:4096
	v_mfma_f32_16x16x32_bf16 v[36:39], v[86:89], v[94:97], v[36:39]
	v_mfma_f32_16x16x32_bf16 v[32:35], v[90:93], v[94:97], v[32:35]
	ds_read_b128 v[94:97], v71 offset:6144
	v_mov_b32_e32 v71, 0
	s_waitcnt lgkmcnt(1)
	v_mfma_f32_16x16x32_bf16 v[28:31], v[78:81], v[44:47], v[28:31]
	v_mfma_f32_16x16x32_bf16 v[24:27], v[82:85], v[44:47], v[24:27]
	v_mfma_f32_16x16x32_bf16 v[20:23], v[86:89], v[44:47], v[20:23]
	v_mfma_f32_16x16x32_bf16 v[16:19], v[90:93], v[44:47], v[16:19]
	s_waitcnt lgkmcnt(0)
	v_mfma_f32_16x16x32_bf16 v[44:47], v[78:81], v[94:97], v[12:15]
	v_mfma_f32_16x16x32_bf16 v[8:11], v[82:85], v[94:97], v[8:11]
	s_nop 1
	v_or3_b32 v13, v68, s0, v69
	v_cndmask_b32_e64 v14, 0, 1, s[6:7]
	v_mov_b32_e32 v12, 0
	v_mfma_f32_16x16x32_bf16 v[4:7], v[86:89], v[94:97], v[4:7]
	v_cmp_ne_u32_e64 s[0:1], 1, v14
	v_lshlrev_b32_e32 v72, 2, v13
	v_mov_b32_e32 v68, 0
	v_mfma_f32_16x16x32_bf16 v[0:3], v[90:93], v[94:97], v[0:3]
	v_mov_b32_e32 v69, 0
	s_cbranch_vccnz .LBB0_346
	v_readlane_b32 s72, v166, 39
	v_readlane_b32 s80, v166, 47
	v_readlane_b32 s81, v166, 48
	v_readlane_b32 s73, v166, 40
	v_readlane_b32 s74, v166, 41
	v_readlane_b32 s75, v166, 42
	v_readlane_b32 s76, v166, 43
	v_readlane_b32 s77, v166, 44
	global_load_dwordx4 v[68:71], v72, s[80:81]
	v_readlane_b32 s78, v166, 45
	v_readlane_b32 s79, v166, 46
	v_readlane_b32 s82, v166, 49
	v_readlane_b32 s83, v166, 50
	v_readlane_b32 s84, v166, 51
	v_readlane_b32 s85, v166, 52
	v_readlane_b32 s86, v166, 53
	v_readlane_b32 s87, v166, 54

; DEV int otid() { int t = threadIdx.x; asm volatile("" : "+v"(t)); return t; }
; template <bool SWAP, class RowA, class Epi>
; DEV void gemm_tile(unsigned char* smem, RowA rowA, const bf16_t* Bt, int K, Epi epi) {
;   const int tid = otid(), lane = tid & 63, wid = tid >> 6, wr = wid >> 1, wc = wid & 1, fr = lane & 15, fq = lane >> 4;
;   const int r0 = tid >> 2;
;   const int a_w = (r0 >> 2) & 3, g_w = (((a_w ^ (a_w >> 1)) & 1) << 1) | (a_w >> 1);
;   const int cc = ((tid & 3) ^ g_w) * 8;
;   const int a_r = (fr >> 2) & 3, g_r = (((a_r ^ (a_r >> 1)) & 1) << 1) | (a_r >> 1);
;   const int rdoff = fr * 64 + ((fq ^ g_r) * 16);
;   const bf16_t* a0 = rowA(r0) + cc;
;   const bf16_t* a1 = rowA(r0 + 64) + cc;
;   const bf16_t* b0 = Bt + (size_t)r0 * K + cc;
;   const bf16_t* b1 = Bt + (size_t)(r0 + 64) * K + cc;
;   f32x4 acc[4][4];
; #pragma unroll
;   for (int m = 0; m < 4; ++m)
; #pragma unroll
;     for (int n = 0; n < 4; ++n) acc[m][n] = f32x4{0.f, 0.f, 0.f, 0.f};
;   const int nk = K / 32;
;   auto stage = [&](int kt, int buf) {
;     unsigned char* SA = smem + buf * 16384 + tid * 16;
;     unsigned char* SB = SA + 8192;
;     const int ko = kt * 32;
;     glds16(a0 + ko, SA); glds16(a1 + ko, SA + 4096);
;     glds16(b0 + ko, SB); glds16(b1 + ko, SB + 4096);
;   };
;   stage(0, 0);
;   for (int t = 0; t < nk; ++t) {
;     asm volatile("s_waitcnt vmcnt(0)" ::: "memory");
;     __syncthreads();
;     if (t + 1 < nk) stage(t + 1, (t + 1) & 1);
; DEV void phase_ml_in(const Params& p, unsigned char* smem) {
;     ...
;   for (int t = blockIdx.x; t < ntile; t += gridDim.x) {
;     int nt = t % 25, mt = t / 25;
;     const bf16_t* A = p.hbuf + (size_t)mt * 128 * 1024;
.LBB0_847:
	v_mov_b32_e32 v8, v122
	s_mov_b32 s23, 0
	v_lshrrev_b32_e32 v1, 4, v8
	v_lshrrev_b32_e32 v2, 5, v8
	v_xor_b32_e32 v1, v1, v2
	v_lshlrev_b32_e32 v1, 1, v1
	v_readlane_b32 s36, v165, 7
	v_ashrrev_i32_e32 v0, 2, v8
	v_bfe_u32 v3, v8, 5, 1
	v_and_b32_e32 v1, 2, v1
	v_and_b32_e32 v2, 3, v8
	s_lshl_b64 s[0:1], s[22:23], 18
	v_readlane_b32 s48, v165, 19
	v_bitop3_b32 v9, v1, v2, v3 bitop3:0x36
	v_ashrrev_i32_e32 v1, 31, v0
	v_readlane_b32 s49, v165, 20
	s_add_u32 s0, s48, s0
	v_lshlrev_b64 v[0:1], 11, v[0:1]
	s_addc_u32 s1, s49, s1
	v_lshl_add_u64 v[2:3], v[0:1], 0, s[16:17]
	v_lshl_add_u64 v[4:5], s[30:31], 0, v[2:3]
	v_lshl_add_u64 v[6:7], s[0:1], 0, v[0:1]
	v_lshl_add_u64 v[2:3], s[0:1], 0, v[2:3]
	v_lshl_add_u64 v[0:1], s[30:31], 0, v[0:1]
	v_lshlrev_b32_e32 v68, 4, v9
	v_lshl_add_u64 v[64:65], v[0:1], 0, v[68:69]
	v_lshl_add_u64 v[0:1], v[4:5], 0, v[68:69]
	v_lshl_add_u64 v[66:67], v[6:7], 0, v[68:69]
	v_lshl_add_u64 v[2:3], v[2:3], 0, v[68:69]
	v_lshlrev_b32_e32 v68, 4, v8
	v_add_u32_e32 v5, 0x1000, v68
	v_readfirstlane_b32 s0, v68
	s_mov_b32 m0, s0
	v_readfirstlane_b32 s0, v5
	v_add_u32_e32 v4, 0x2000, v68
	s_mov_b32 m0, s0
	v_readfirstlane_b32 s0, v4
	v_add_u32_e32 v0, 0x3000, v68
	s_mov_b32 m0, s0
	v_readfirstlane_b32 s0, v0
	s_mov_b32 m0, s0
	v_lshrrev_b32_e32 v0, 2, v8
	v_lshrrev_b32_e32 v1, 3, v8
	v_xor_b32_e32 v0, v0, v1
	v_lshlrev_b32_e32 v0, 1, v0
	v_bfe_u32 v71, v8, 4, 2
	v_bfe_u32 v2, v8, 3, 1
	v_and_b32_e32 v0, 2, v0
	v_and_b32_e32 v76, 15, v8
	v_bitop3_b32 v0, v0, v71, v2 bitop3:0x36
	v_lshlrev_b32_e32 v1, 6, v76
	s_waitcnt vmcnt(0)
	v_bfe_u32 v72, v8, 6, 1
	v_ashrrev_i32_e32 v73, 7, v8
	v_lshl_or_b32 v74, v0, 4, v1
	v_mov_b32_e32 v0, 0
	v_lshlrev_b32_e32 v77, 12, v73
	v_lshlrev_b32_e32 v75, 12, v72
	s_mov_b32 s2, 0
	s_mov_b64 s[0:1], 0
	v_mov_b32_e32 v1, v0
	v_mov_b32_e32 v2, v0
	v_mov_b32_e32 v3, v0
	s_waitcnt vmcnt(0)
	v_mov_b32_e32 v16, v0
	v_mov_b32_e32 v17, v0
	v_mov_b32_e32 v18, v0
	v_mov_b32_e32 v19, v0
	v_mov_b32_e32 v32, v0
	v_mov_b32_e32 v33, v0
	v_mov_b32_e32 v34, v0
	v_mov_b32_e32 v35, v0
	v_mov_b32_e32 v48, v0
	v_mov_b32_e32 v49, v0
	v_mov_b32_e32 v50, v0
	v_mov_b32_e32 v51, v0
	v_mov_b32_e32 v4, v0
	v_mov_b32_e32 v5, v0
	v_mov_b32_e32 v6, v0
	v_mov_b32_e32 v7, v0
	v_mov_b32_e32 v20, v0
	v_mov_b32_e32 v21, v0
	v_mov_b32_e32 v22, v0
	v_mov_b32_e32 v23, v0
	v_mov_b32_e32 v36, v0
	v_mov_b32_e32 v37, v0
	v_mov_b32_e32 v38, v0
	v_mov_b32_e32 v39, v0
	v_mov_b32_e32 v52, v0
	v_mov_b32_e32 v53, v0
	v_mov_b32_e32 v54, v0
	v_mov_b32_e32 v55, v0
	v_mov_b32_e32 v8, v0
	v_mov_b32_e32 v9, v0
	v_mov_b32_e32 v10, v0
	v_mov_b32_e32 v11, v0
	v_mov_b32_e32 v24, v0
	v_mov_b32_e32 v25, v0
	v_mov_b32_e32 v26, v0
	v_mov_b32_e32 v27, v0
	v_mov_b32_e32 v40, v0
	v_mov_b32_e32 v41, v0
	v_mov_b32_e32 v42, v0
	v_mov_b32_e32 v43, v0
	v_mov_b32_e32 v56, v0
	v_mov_b32_e32 v57, v0
	v_mov_b32_e32 v58, v0
	v_mov_b32_e32 v59, v0
	v_mov_b32_e32 v12, v0
	v_mov_b32_e32 v13, v0
	v_mov_b32_e32 v14, v0
	v_mov_b32_e32 v15, v0
	v_mov_b32_e32 v28, v0
	v_mov_b32_e32 v29, v0
	v_mov_b32_e32 v30, v0
	v_mov_b32_e32 v31, v0
	v_mov_b32_e32 v44, v0
	v_mov_b32_e32 v45, v0
	v_mov_b32_e32 v46, v0
	v_mov_b32_e32 v47, v0
	v_mov_b32_e32 v60, v0
	v_mov_b32_e32 v61, v0
	v_mov_b32_e32 v62, v0
	v_mov_b32_e32 v63, v0
	v_readlane_b32 s37, v165, 8
	v_readlane_b32 s38, v165, 9
	v_readlane_b32 s39, v165, 10
	v_readlane_b32 s40, v165, 11
	v_readlane_b32 s41, v165, 12
	v_readlane_b32 s42, v165, 13
	v_readlane_b32 s43, v165, 14
	v_readlane_b32 s44, v165, 15
	v_readlane_b32 s45, v165, 16
	v_readlane_b32 s46, v165, 17
	v_readlane_b32 s47, v165, 18
	v_readlane_b32 s50, v165, 21
	v_readlane_b32 s51, v165, 22
	v_and_b32_e32 v78, 15, v122
	v_bfe_u32 v79, v122, 4, 2
	v_bfe_u32 v80, v122, 1, 3
	v_xor_b32_e32 v79, v79, v80
	v_lshlrev_b32_e32 v79, 4, v79
	v_lshl_or_b32 v74, v78, 7, v79
	v_lshlrev_b32_e32 v77, 1, v77
	v_lshlrev_b32_e32 v75, 1, v75
	v_and_b32_e32 v78, 7, v122
	v_bfe_u32 v79, v122, 4, 3
	v_xor_b32_e32 v78, v78, v79
	v_lshlrev_b32_e32 v78, 4, v78
	v_lshrrev_b32_e32 v79, 3, v122
	v_lshl_or_b32 v78, v79, 11, v78
	v_bfe_u32 v79, v122, 4, 2
	v_lshrrev_b32_e32 v80, 1, v79
	v_xor_b32_e32 v81, v79, v80
	v_and_b32_e32 v81, 1, v81
	v_lshl_or_b32 v80, v81, 1, v80
	v_and_b32_e32 v79, 3, v122
	v_xor_b32_e32 v79, v79, v80
	v_lshlrev_b32_e32 v79, 4, v79
	v_lshrrev_b32_e32 v80, 2, v122
	v_lshl_or_b32 v79, v80, 11, v79
	v_sub_u32_e32 v78, v78, v79
	v_ashrrev_i32_e32 v79, 31, v78
	v_lshl_add_u64 v[64:65], v[64:65], 0, v[78:79]
	v_lshl_add_u64 v[66:67], v[66:67], 0, v[78:79]
	v_mov_b32_e32 v140, 0x10000
	v_mov_b32_e32 v141, 0
.LBB0_848:
	s_bitcmp1_b32 s0, 6
	s_cbranch_scc1 .Lpair_odd_848
	s_waitcnt lgkmcnt(0)
	s_barrier
	v_readfirstlane_b32 s4, v68
	s_mov_b32 m0, s4
	v_lshl_add_u64 v[78:79], v[64:65], 0, s[0:1]
	global_load_lds_dwordx4 v[78:79], off
	s_add_i32 m0, m0, 0x1000
	v_lshl_add_u64 v[80:81], v[78:79], 0, v[140:141]
	global_load_lds_dwordx4 v[80:81], off
	s_add_i32 m0, m0, 0x1000
	v_lshl_add_u64 v[78:79], v[80:81], 0, v[140:141]
	global_load_lds_dwordx4 v[78:79], off
	s_add_i32 m0, m0, 0x1000
	v_lshl_add_u64 v[80:81], v[78:79], 0, v[140:141]
	global_load_lds_dwordx4 v[80:81], off
	s_add_i32 m0, m0, 0x1000
	v_lshl_add_u64 v[78:79], v[66:67], 0, s[0:1]
	global_load_lds_dwordx4 v[78:79], off
	s_add_i32 m0, m0, 0x1000
	v_lshl_add_u64 v[80:81], v[78:79], 0, v[140:141]
	global_load_lds_dwordx4 v[80:81], off
	s_add_i32 m0, m0, 0x1000
	v_lshl_add_u64 v[78:79], v[80:81], 0, v[140:141]
	global_load_lds_dwordx4 v[78:79], off
	s_add_i32 m0, m0, 0x1000
	v_lshl_add_u64 v[80:81], v[78:79], 0, v[140:141]
	global_load_lds_dwordx4 v[80:81], off
	s_waitcnt vmcnt(0)
	s_barrier
; template <bool SWAP, class RowA, class Epi>
; DEV void gemm_tile(unsigned char* smem, RowA rowA, const bf16_t* Bt, int K, Epi epi) {
;     ...
;   for (int t = 0; t < nk; ++t) {
;     asm volatile("s_waitcnt vmcnt(0)" ::: "memory");
;     __syncthreads();
;     if (t + 1 < nk) stage(t + 1, (t + 1) & 1);
;     const unsigned char* SA = smem + (t & 1) * 16384;
;     const unsigned char* SB = SA + 8192;
;     bf16x8 At[4], Bl[4];
; #pragma unroll
;     for (int m = 0; m < 4; ++m) At[m] = *reinterpret_cast<const bf16x8*>(SA + (wr * 64 + m * 16) * 64 + rdoff);
; #pragma unroll
;     for (int n = 0; n < 4; ++n) Bl[n] = *reinterpret_cast<const bf16x8*>(SB + (wc * 64 + n * 16) * 64 + rdoff);
; #pragma unroll
;     for (int m = 0; m < 4; ++m)
; #pragma unroll
;       for (int n = 0; n < 4; ++n)
;         acc[m][n] = SWAP ? __builtin_amdgcn_mfma_f32_16x16x32_bf16(Bl[n], At[m], acc[m][n], 0, 0, 0)
;                          : __builtin_amdgcn_mfma_f32_16x16x32_bf16(At[m], Bl[n], acc[m][n], 0, 0, 0);
; DEV void phase_ml_in(const Params& p, unsigned char* smem) {
;     ...
;         [&](f32x4 (&acc)[4][4], int wr, int wc, int fr, int fq) {
;           const int c0 = nt * 128 + wc * 64;
;           if (c0 >= 3104) return;
; #pragma unroll
;           for (int n = 0; n < 4; ++n) {
;             const int col = c0 + n * 16 + fr;
;             const float bv = col < 3104 ? p.b_in[col] : 0.f;
; #pragma unroll
;             for (int m = 0; m < 4; ++m) {
;               const int rbase = mt * 128 + wr * 64 + m * 16 + fq * 4;
;               if (c0 < 2048) {
;                 int ea = col - 1024, h = ea >> 7, e = ea & 127;
;                 int b, tau;
;                 if (rbase < NLAT) { b = rbase >> 13; tau = CTX + (rbase & 8191); } else { int rr = rbase - NLAT; b = rr >> 8; tau = rr & 255; }
;                 bf16_t* dst = p.vtm + ((size_t)((b * 8 + h) * 128 + e)) * TAU + tau;
;                 *reinterpret_cast<uint2*>(dst) = make_uint2(pack2(acc[m][n][0] + bv, acc[m][n][1] + bv), pack2(acc[m][n][2] + bv, acc[m][n][3] + bv));
;               } else if (col < 3104) {
;                 const int gc = col - 3072;
;                 const bool isf = (gc >> 3) & 1;
; #pragma unroll
;                 for (int j = 0; j < 4; ++j) {
;                   float g = softcap(acc[m][n][j] + bv);
;                   p.ga[(size_t)(rbase + j) * 32 + gc] = isf ? logsig(g) : g;
.Lpair_odd_848:
	s_and_b32 s2, s0, 64
	v_xor_b32_e32 v98, s2, v74
	v_add_u32_e32 v94, v98, v77
	v_add_u32_e32 v110, v98, v75
	ds_read_b128 v[78:81], v94
	ds_read_b128 v[86:89], v94 offset:2048
	ds_read_b128 v[90:93], v94 offset:4096
	ds_read_b128 v[94:97], v94 offset:6144
	ds_read_b128 v[98:101], v110 offset:16384
	ds_read_b128 v[102:105], v110 offset:18432
	ds_read_b128 v[106:109], v110 offset:20480
	ds_read_b128 v[110:113], v110 offset:22528
	s_waitcnt lgkmcnt(0)
	v_mfma_f32_16x16x32_bf16 v[60:63], v[78:81], v[98:101], v[60:63]
	s_add_u32 s0, s0, 64
	s_addc_u32 s1, s1, 0
	s_cmpk_eq_i32 s0, 0x7c0
	v_mfma_f32_16x16x32_bf16 v[44:47], v[78:81], v[102:105], v[44:47]
	v_mfma_f32_16x16x32_bf16 v[28:31], v[78:81], v[106:109], v[28:31]
	v_mfma_f32_16x16x32_bf16 v[12:15], v[78:81], v[110:113], v[12:15]
	v_mfma_f32_16x16x32_bf16 v[56:59], v[86:89], v[98:101], v[56:59]
	v_mfma_f32_16x16x32_bf16 v[40:43], v[86:89], v[102:105], v[40:43]
	v_mfma_f32_16x16x32_bf16 v[24:27], v[86:89], v[106:109], v[24:27]
	v_mfma_f32_16x16x32_bf16 v[8:11], v[86:89], v[110:113], v[8:11]
	v_mfma_f32_16x16x32_bf16 v[52:55], v[90:93], v[98:101], v[52:55]
	v_mfma_f32_16x16x32_bf16 v[36:39], v[90:93], v[102:105], v[36:39]
	v_mfma_f32_16x16x32_bf16 v[20:23], v[90:93], v[106:109], v[20:23]
	v_mfma_f32_16x16x32_bf16 v[4:7], v[90:93], v[110:113], v[4:7]
	v_mfma_f32_16x16x32_bf16 v[48:51], v[94:97], v[98:101], v[48:51]
	v_mfma_f32_16x16x32_bf16 v[32:35], v[94:97], v[102:105], v[32:35]
	v_mfma_f32_16x16x32_bf16 v[16:19], v[94:97], v[106:109], v[16:19]
	v_mfma_f32_16x16x32_bf16 v[0:3], v[94:97], v[110:113], v[0:3]
	s_cbranch_scc0 .LBB0_848
	v_xor_b32_e32 v142, 64, v74
	v_add_u32_e32 v68, v142, v77
	s_waitcnt vmcnt(0)
	s_waitcnt vmcnt(0)
	s_barrier
	ds_read_b128 v[64:67], v68
	v_add_u32_e32 v74, v142, v75
	ds_read_b128 v[78:81], v74 offset:16384
	ds_read_b128 v[86:89], v74 offset:18432
	ds_read_b128 v[90:93], v74 offset:20480
	ds_read_b128 v[94:97], v74 offset:22528
	s_waitcnt lgkmcnt(3)
	v_mfma_f32_16x16x32_bf16 v[60:63], v[64:67], v[78:81], v[60:63]
	s_lshl_b32 s21, s22, 7
	v_lshl_or_b32 v77, v72, 6, s21
	v_cmp_gt_u32_e32 vcc, s26, v77
	s_waitcnt lgkmcnt(2)
	v_mfma_f32_16x16x32_bf16 v[44:47], v[64:67], v[86:89], v[44:47]
	s_waitcnt lgkmcnt(1)
	v_mfma_f32_16x16x32_bf16 v[28:31], v[64:67], v[90:93], v[28:31]
	s_waitcnt lgkmcnt(0)
	v_mfma_f32_16x16x32_bf16 v[12:15], v[64:67], v[94:97], v[12:15]
	ds_read_b128 v[64:67], v68 offset:2048
	s_waitcnt lgkmcnt(0)
	v_mfma_f32_16x16x32_bf16 v[56:59], v[64:67], v[78:81], v[56:59]
	v_mfma_f32_16x16x32_bf16 v[40:43], v[64:67], v[86:89], v[40:43]
	v_mfma_f32_16x16x32_bf16 v[24:27], v[64:67], v[90:93], v[24:27]
	v_mfma_f32_16x16x32_bf16 v[8:11], v[64:67], v[94:97], v[8:11]
	ds_read_b128 v[64:67], v68 offset:4096
	s_waitcnt lgkmcnt(0)
	v_mfma_f32_16x16x32_bf16 v[52:55], v[64:67], v[78:81], v[52:55]
	v_mfma_f32_16x16x32_bf16 v[36:39], v[64:67], v[86:89], v[36:39]
	v_mfma_f32_16x16x32_bf16 v[20:23], v[64:67], v[90:93], v[20:23]
	v_mfma_f32_16x16x32_bf16 v[4:7], v[64:67], v[94:97], v[4:7]
	ds_read_b128 v[64:67], v68 offset:6144
	s_waitcnt lgkmcnt(0)
	v_mfma_f32_16x16x32_bf16 v[48:51], v[64:67], v[78:81], v[48:51]
	v_mfma_f32_16x16x32_bf16 v[32:35], v[64:67], v[86:89], v[32:35]
	v_mfma_f32_16x16x32_bf16 v[16:19], v[64:67], v[90:93], v[16:19]
	v_mfma_f32_16x16x32_bf16 v[0:3], v[64:67], v[94:97], v[0:3]
	s_and_saveexec_b64 s[34:35], vcc
	v_readlane_b32 s36, v165, 23
	v_readlane_b32 s46, v165, 33
	v_readlane_b32 s47, v165, 34
	v_readlane_b32 s48, v165, 35
	v_readlane_b32 s49, v165, 36
	v_readlane_b32 s37, v165, 24
	v_readlane_b32 s38, v165, 25
	v_readlane_b32 s39, v165, 26
	v_readlane_b32 s40, v165, 27
	v_readlane_b32 s41, v165, 28
	v_readlane_b32 s42, v165, 29
	v_readlane_b32 s43, v165, 30
	v_readlane_b32 s44, v165, 31
	v_readlane_b32 s45, v165, 32
	v_readlane_b32 s50, v165, 37
	v_readlane_b32 s51, v165, 38
	s_cbranch_execz .LBB0_1638
	v_readlane_b32 s72, v166, 39
	v_or_b32_e32 v68, v77, v76
	v_readlane_b32 s84, v166, 51
	v_readlane_b32 s85, v166, 52
	s_cmp_gt_u32 s22, 15
	s_cselect_b64 s[12:13], -1, 0
	v_lshl_add_u64 v[66:67], v[68:69], 2, s[84:85]
	global_load_dword v72, v[66:67], off
	s_lshl_b32 s0, s20, 7
	v_lshl_add_u32 v73, v73, 6, s0
	v_cmp_lt_u32_e64 s[8:9], 7, v76
	v_lshl_or_b32 v64, v71, 2, v73
	s_mov_b64 s[0:1], -1
	s_and_b64 vcc, exec, s[12:13]
	v_readlane_b32 s73, v166, 40
	v_readlane_b32 s74, v166, 41
	v_readlane_b32 s75, v166, 42
	v_readlane_b32 s76, v166, 43
	v_readlane_b32 s77, v166, 44
	v_readlane_b32 s78, v166, 45
	v_readlane_b32 s79, v166, 46
	v_readlane_b32 s80, v166, 47
	v_readlane_b32 s81, v166, 48
	v_readlane_b32 s82, v166, 49
	v_readlane_b32 s83, v166, 50
	v_readlane_b32 s86, v166, 53
	v_readlane_b32 s87, v166, 54
	s_cbranch_vccz .LBB0_892
	s_waitcnt vmcnt(0)
	v_add_f32_e32 v65, v60, v72
	v_mul_f32_e32 v65, 0x3d888889, v65
	v_cmp_nlt_f32_e64 s[0:1], |v65|, s27
	s_and_saveexec_b64 s[2:3], s[0:1]
	s_xor_b64 s[0:1], exec, s[2:3]
	s_cbranch_execz .LBB0_853
	v_add_f32_e64 v71, |v65|, |v65|
	v_mul_f32_e32 v74, 0x3fb8aa3b, v71
	v_rndne_f32_e32 v75, v74
	v_sub_f32_e32 v78, v74, v75
	v_fma_f32 v74, v71, s60, -v74
	v_fmac_f32_e32 v74, 0x32a5705f, v71
	v_add_f32_e32 v74, v78, v74
	v_cvt_i32_f32_e32 v75, v75
	v_exp_f32_e32 v74, v74
	v_cmp_ngt_f32_e32 vcc, s61, v71
	v_ldexp_f32 v74, v74, v75
	s_nop 0
	v_cndmask_b32_e32 v74, 0, v74, vcc
	v_cmp_nlt_f32_e32 vcc, s62, v71
	s_nop 1
	v_cndmask_b32_e32 v71, v84, v74, vcc
	v_add_f32_e32 v71, 1.0, v71
	v_rcp_f32_e32 v71, v71
	s_nop 0
	v_fma_f32 v71, v71, -2.0, 1.0

; DEV int otid() { int t = threadIdx.x; asm volatile("" : "+v"(t)); return t; }
; template <bool SWAP, class RowA, class Epi>
; DEV void gemm_tile(unsigned char* smem, RowA rowA, const bf16_t* Bt, int K, Epi epi) {
;   const int tid = otid(), lane = tid & 63, wid = tid >> 6, wr = wid >> 1, wc = wid & 1, fr = lane & 15, fq = lane >> 4;
;   const int r0 = tid >> 2;
;   const int a_w = (r0 >> 2) & 3, g_w = (((a_w ^ (a_w >> 1)) & 1) << 1) | (a_w >> 1);
;   const int cc = ((tid & 3) ^ g_w) * 8;
;   const int a_r = (fr >> 2) & 3, g_r = (((a_r ^ (a_r >> 1)) & 1) << 1) | (a_r >> 1);
;   const int rdoff = fr * 64 + ((fq ^ g_r) * 16);
;   const bf16_t* a0 = rowA(r0) + cc;
;   const bf16_t* a1 = rowA(r0 + 64) + cc;
;   const bf16_t* b0 = Bt + (size_t)r0 * K + cc;
;   const bf16_t* b1 = Bt + (size_t)(r0 + 64) * K + cc;
;   f32x4 acc[4][4];
; #pragma unroll
;   for (int m = 0; m < 4; ++m)
; #pragma unroll
;     for (int n = 0; n < 4; ++n) acc[m][n] = f32x4{0.f, 0.f, 0.f, 0.f};
;   const int nk = K / 32;
;   auto stage = [&](int kt, int buf) {
;     unsigned char* SA = smem + buf * 16384 + tid * 16;
;     unsigned char* SB = SA + 8192;
;     const int ko = kt * 32;
;     glds16(a0 + ko, SA); glds16(a1 + ko, SA + 4096);
;     glds16(b0 + ko, SB); glds16(b1 + ko, SB + 4096);
;   };
;   stage(0, 0);
;   for (int t = 0; t < nk; ++t) {
;     asm volatile("s_waitcnt vmcnt(0)" ::: "memory");
;     __syncthreads();
;     if (t + 1 < nk) stage(t + 1, (t + 1) & 1);
; DEV void phase_ml_in(const Params& p, unsigned char* smem) {
;     ...
;     if (nt < 8 || (nt >= 16 && nt < 24)) {
;       bf16_t* obase = nt < 8 ? p.qb : p.ob - 2048;
;       gemm_tile<true>(smem, [&](int r) { return A + (size_t)r * 1024; }, p.win_t + (size_t)nt * 128 * 1024, 1024,
.LBB0_1639:
	v_mov_b32_e32 v8, v122
	s_ashr_i32 s23, s22, 31
	v_lshrrev_b32_e32 v1, 4, v8
	v_lshrrev_b32_e32 v2, 5, v8
	v_xor_b32_e32 v1, v1, v2
	v_lshlrev_b32_e32 v1, 1, v1
	v_readlane_b32 s36, v165, 7
	v_ashrrev_i32_e32 v0, 2, v8
	v_bfe_u32 v3, v8, 5, 1
	v_and_b32_e32 v1, 2, v1
	v_and_b32_e32 v2, 3, v8
	s_lshl_b64 s[0:1], s[22:23], 18
	v_readlane_b32 s48, v165, 19
	v_bitop3_b32 v9, v1, v2, v3 bitop3:0x36
	v_ashrrev_i32_e32 v1, 31, v0
	v_readlane_b32 s49, v165, 20
	s_add_u32 s0, s48, s0
	v_lshlrev_b64 v[0:1], 11, v[0:1]
	s_addc_u32 s1, s49, s1
	v_lshl_add_u64 v[2:3], v[0:1], 0, s[16:17]
	v_lshl_add_u64 v[4:5], s[30:31], 0, v[2:3]
	v_lshl_add_u64 v[6:7], s[0:1], 0, v[0:1]
	v_lshl_add_u64 v[0:1], s[30:31], 0, v[0:1]
	v_lshlrev_b32_e32 v68, 4, v9
	v_lshlrev_b32_e32 v76, 4, v8
	v_lshl_add_u64 v[2:3], s[0:1], 0, v[2:3]
	v_lshl_add_u64 v[64:65], v[0:1], 0, v[68:69]
	v_lshl_add_u64 v[0:1], v[4:5], 0, v[68:69]
	v_readfirstlane_b32 s0, v76
	v_add_u32_e32 v5, 0x1000, v76
	s_mov_b32 m0, s0
	v_readfirstlane_b32 s0, v5
	v_add_u32_e32 v4, 0x2000, v76
	s_mov_b32 m0, s0
	v_readfirstlane_b32 s0, v4
	v_add_u32_e32 v0, 0x3000, v76
	v_lshl_add_u64 v[66:67], v[6:7], 0, v[68:69]
	s_mov_b32 m0, s0
	v_readfirstlane_b32 s0, v0
	v_lshl_add_u64 v[2:3], v[2:3], 0, v[68:69]
	s_mov_b32 m0, s0
	v_lshrrev_b32_e32 v0, 2, v8
	v_lshrrev_b32_e32 v1, 3, v8
	v_xor_b32_e32 v0, v0, v1
	v_lshlrev_b32_e32 v0, 1, v0
	s_waitcnt vmcnt(0)
	v_bfe_u32 v72, v8, 4, 2
	v_bfe_u32 v2, v8, 3, 1
	v_and_b32_e32 v0, 2, v0
	v_and_b32_e32 v73, 15, v8
	v_bitop3_b32 v0, v0, v72, v2 bitop3:0x36
	v_lshlrev_b32_e32 v1, 6, v73
	v_bfe_u32 v71, v8, 6, 1
	v_ashrrev_i32_e32 v68, 7, v8
	v_lshl_or_b32 v74, v0, 4, v1
	v_mov_b32_e32 v0, 0
	v_lshlrev_b32_e32 v75, 12, v68
	v_lshlrev_b32_e32 v77, 12, v71
	s_mov_b32 s2, 0
	s_mov_b64 s[0:1], 0
	v_mov_b32_e32 v1, v0
	v_mov_b32_e32 v2, v0
	v_mov_b32_e32 v3, v0
	v_mov_b32_e32 v16, v0
	v_mov_b32_e32 v17, v0
	v_mov_b32_e32 v18, v0
	v_mov_b32_e32 v19, v0
	v_mov_b32_e32 v32, v0
	v_mov_b32_e32 v33, v0
	v_mov_b32_e32 v34, v0
	v_mov_b32_e32 v35, v0
	v_mov_b32_e32 v48, v0
	v_mov_b32_e32 v49, v0
	v_mov_b32_e32 v50, v0
	v_mov_b32_e32 v51, v0
	v_mov_b32_e32 v4, v0
	v_mov_b32_e32 v5, v0
	v_mov_b32_e32 v6, v0
	v_mov_b32_e32 v7, v0
	v_mov_b32_e32 v20, v0
	v_mov_b32_e32 v21, v0
	v_mov_b32_e32 v22, v0
	v_mov_b32_e32 v23, v0
	v_mov_b32_e32 v36, v0
	v_mov_b32_e32 v37, v0
	v_mov_b32_e32 v38, v0
	v_mov_b32_e32 v39, v0
	v_mov_b32_e32 v52, v0
	v_mov_b32_e32 v53, v0
	v_mov_b32_e32 v54, v0
	v_mov_b32_e32 v55, v0
	v_mov_b32_e32 v8, v0
	v_mov_b32_e32 v9, v0
	v_mov_b32_e32 v10, v0
	v_mov_b32_e32 v11, v0
	v_mov_b32_e32 v24, v0
	v_mov_b32_e32 v25, v0
	v_mov_b32_e32 v26, v0
	v_mov_b32_e32 v27, v0
	v_mov_b32_e32 v40, v0
	v_mov_b32_e32 v41, v0
	v_mov_b32_e32 v42, v0
	v_mov_b32_e32 v43, v0
	v_mov_b32_e32 v56, v0
	v_mov_b32_e32 v57, v0
	v_mov_b32_e32 v58, v0
	v_mov_b32_e32 v59, v0
	v_mov_b32_e32 v12, v0
	v_mov_b32_e32 v13, v0
	v_mov_b32_e32 v14, v0
	v_mov_b32_e32 v15, v0
	v_mov_b32_e32 v28, v0
	v_mov_b32_e32 v29, v0
	v_mov_b32_e32 v30, v0
	v_mov_b32_e32 v31, v0
	v_mov_b32_e32 v44, v0
	v_mov_b32_e32 v45, v0
	v_mov_b32_e32 v46, v0
	v_mov_b32_e32 v47, v0
	v_mov_b32_e32 v60, v0
	v_mov_b32_e32 v61, v0
	v_mov_b32_e32 v62, v0
	v_mov_b32_e32 v63, v0
	v_readlane_b32 s37, v165, 8
	v_readlane_b32 s38, v165, 9
	v_readlane_b32 s39, v165, 10
	v_readlane_b32 s40, v165, 11
	v_readlane_b32 s41, v165, 12
	v_readlane_b32 s42, v165, 13
	v_readlane_b32 s43, v165, 14
	v_readlane_b32 s44, v165, 15
	v_readlane_b32 s45, v165, 16
	v_readlane_b32 s46, v165, 17
	v_readlane_b32 s47, v165, 18
	v_readlane_b32 s50, v165, 21
	v_readlane_b32 s51, v165, 22
	v_and_b32_e32 v78, 15, v122
	v_bfe_u32 v79, v122, 4, 2
	v_bfe_u32 v80, v122, 1, 3
	v_xor_b32_e32 v79, v79, v80
	v_lshlrev_b32_e32 v79, 4, v79
	v_lshl_or_b32 v74, v78, 7, v79
	v_lshlrev_b32_e32 v75, 1, v75
	v_lshlrev_b32_e32 v77, 1, v77
	v_and_b32_e32 v78, 7, v122
	v_bfe_u32 v79, v122, 4, 3
	v_xor_b32_e32 v78, v78, v79
	v_lshlrev_b32_e32 v78, 4, v78
	v_lshrrev_b32_e32 v79, 3, v122
	v_lshl_or_b32 v78, v79, 11, v78
	v_bfe_u32 v79, v122, 4, 2
	v_lshrrev_b32_e32 v80, 1, v79
	v_xor_b32_e32 v81, v79, v80
	v_and_b32_e32 v81, 1, v81
	v_lshl_or_b32 v80, v81, 1, v80
	v_and_b32_e32 v79, 3, v122
	v_xor_b32_e32 v79, v79, v80
	v_lshlrev_b32_e32 v79, 4, v79
	v_lshrrev_b32_e32 v80, 2, v122
	v_lshl_or_b32 v79, v80, 11, v79
	v_sub_u32_e32 v78, v78, v79
	v_ashrrev_i32_e32 v79, 31, v78
	v_lshl_add_u64 v[64:65], v[64:65], 0, v[78:79]
	v_lshl_add_u64 v[66:67], v[66:67], 0, v[78:79]
	v_mov_b32_e32 v140, 0x10000
	v_mov_b32_e32 v141, 0
.LBB0_1640:
	s_bitcmp1_b32 s0, 6
	s_cbranch_scc1 .Lpair_odd_1640
	s_waitcnt lgkmcnt(0)
	s_barrier
	v_readfirstlane_b32 s4, v76
	s_mov_b32 m0, s4
	v_lshl_add_u64 v[78:79], v[64:65], 0, s[0:1]
	global_load_lds_dwordx4 v[78:79], off
	s_add_i32 m0, m0, 0x1000
	v_lshl_add_u64 v[80:81], v[78:79], 0, v[140:141]
	global_load_lds_dwordx4 v[80:81], off
	s_add_i32 m0, m0, 0x1000
	v_lshl_add_u64 v[78:79], v[80:81], 0, v[140:141]
	global_load_lds_dwordx4 v[78:79], off
	s_add_i32 m0, m0, 0x1000
	v_lshl_add_u64 v[80:81], v[78:79], 0, v[140:141]
	global_load_lds_dwordx4 v[80:81], off
	s_add_i32 m0, m0, 0x1000
	v_lshl_add_u64 v[78:79], v[66:67], 0, s[0:1]
	global_load_lds_dwordx4 v[78:79], off
	s_add_i32 m0, m0, 0x1000
	v_lshl_add_u64 v[80:81], v[78:79], 0, v[140:141]
	global_load_lds_dwordx4 v[80:81], off
	s_add_i32 m0, m0, 0x1000
	v_lshl_add_u64 v[78:79], v[80:81], 0, v[140:141]
	global_load_lds_dwordx4 v[78:79], off
	s_add_i32 m0, m0, 0x1000
	v_lshl_add_u64 v[80:81], v[78:79], 0, v[140:141]
	global_load_lds_dwordx4 v[80:81], off
	s_waitcnt vmcnt(0)
	s_barrier
; template <bool SWAP, class RowA, class Epi>
; DEV void gemm_tile(unsigned char* smem, RowA rowA, const bf16_t* Bt, int K, Epi epi) {
;     ...
;   for (int t = 0; t < nk; ++t) {
;     asm volatile("s_waitcnt vmcnt(0)" ::: "memory");
;     __syncthreads();
;     if (t + 1 < nk) stage(t + 1, (t + 1) & 1);
;     const unsigned char* SA = smem + (t & 1) * 16384;
;     const unsigned char* SB = SA + 8192;
;     bf16x8 At[4], Bl[4];
; #pragma unroll
;     for (int m = 0; m < 4; ++m) At[m] = *reinterpret_cast<const bf16x8*>(SA + (wr * 64 + m * 16) * 64 + rdoff);
; #pragma unroll
;     for (int n = 0; n < 4; ++n) Bl[n] = *reinterpret_cast<const bf16x8*>(SB + (wc * 64 + n * 16) * 64 + rdoff);
; #pragma unroll
;     for (int m = 0; m < 4; ++m)
; #pragma unroll
;       for (int n = 0; n < 4; ++n)
;         acc[m][n] = SWAP ? __builtin_amdgcn_mfma_f32_16x16x32_bf16(Bl[n], At[m], acc[m][n], 0, 0, 0)
;                          : __builtin_amdgcn_mfma_f32_16x16x32_bf16(At[m], Bl[n], acc[m][n], 0, 0, 0);
; DEV void phase_ml_in(const Params& p, unsigned char* smem) {
;     ...
;       bf16_t* obase = nt < 8 ? p.qb : p.ob - 2048;
;       gemm_tile<true>(smem, [&](int r) { return A + (size_t)r * 1024; }, p.win_t + (size_t)nt * 128 * 1024, 1024,
;         [&](f32x4 (&acc)[4][4], int wr, int wc, int fr, int fq) {
; #pragma unroll
;           for (int n = 0; n < 4; ++n) {
;             const int col = nt * 128 + wc * 64 + n * 16 + fq * 4;
;             const float4 b4 = *reinterpret_cast<const float4*>(p.b_in + col);
; #pragma unroll
;             for (int m = 0; m < 4; ++m) {
;               const int row = mt * 128 + wr * 64 + m * 16 + fr;
;               *reinterpret_cast<uint2*>(obase + (size_t)row * 1024 + col) =
.Lpair_odd_1640:
	s_and_b32 s2, s0, 64
	v_xor_b32_e32 v98, s2, v74
	v_add_u32_e32 v94, v98, v75
	v_add_u32_e32 v110, v98, v77
	ds_read_b128 v[78:81], v94
	ds_read_b128 v[86:89], v94 offset:2048
	ds_read_b128 v[90:93], v94 offset:4096
	ds_read_b128 v[94:97], v94 offset:6144
	ds_read_b128 v[98:101], v110 offset:16384
	ds_read_b128 v[102:105], v110 offset:18432
	ds_read_b128 v[106:109], v110 offset:20480
	ds_read_b128 v[110:113], v110 offset:22528
	s_waitcnt lgkmcnt(0)
	v_mfma_f32_16x16x32_bf16 v[60:63], v[98:101], v[78:81], v[60:63]
	s_add_u32 s0, s0, 64
	s_addc_u32 s1, s1, 0
	s_cmpk_lg_i32 s0, 0x7c0
	v_mfma_f32_16x16x32_bf16 v[44:47], v[102:105], v[78:81], v[44:47]
	v_mfma_f32_16x16x32_bf16 v[28:31], v[106:109], v[78:81], v[28:31]
	v_mfma_f32_16x16x32_bf16 v[12:15], v[110:113], v[78:81], v[12:15]
	v_mfma_f32_16x16x32_bf16 v[56:59], v[98:101], v[86:89], v[56:59]
	v_mfma_f32_16x16x32_bf16 v[40:43], v[102:105], v[86:89], v[40:43]
	v_mfma_f32_16x16x32_bf16 v[24:27], v[106:109], v[86:89], v[24:27]
	v_mfma_f32_16x16x32_bf16 v[8:11], v[110:113], v[86:89], v[8:11]
	v_mfma_f32_16x16x32_bf16 v[52:55], v[98:101], v[90:93], v[52:55]
	v_mfma_f32_16x16x32_bf16 v[36:39], v[102:105], v[90:93], v[36:39]
	v_mfma_f32_16x16x32_bf16 v[20:23], v[106:109], v[90:93], v[20:23]
	v_mfma_f32_16x16x32_bf16 v[4:7], v[110:113], v[90:93], v[4:7]
	v_mfma_f32_16x16x32_bf16 v[48:51], v[98:101], v[94:97], v[48:51]
	v_mfma_f32_16x16x32_bf16 v[32:35], v[102:105], v[94:97], v[32:35]
	v_mfma_f32_16x16x32_bf16 v[16:19], v[106:109], v[94:97], v[16:19]
	v_mfma_f32_16x16x32_bf16 v[0:3], v[110:113], v[94:97], v[0:3]
	s_cbranch_scc1 .LBB0_1640
	v_xor_b32_e32 v142, 64, v74
	v_add_u32_e32 v64, v142, v77
	s_waitcnt vmcnt(0)
	s_waitcnt vmcnt(0)
	s_barrier
	ds_read_b128 v[76:79], v64 offset:22528
	ds_read_b128 v[86:89], v64 offset:20480
	ds_read_b128 v[90:93], v64 offset:18432
	ds_read_b128 v[94:97], v64 offset:16384
	v_add_u32_e32 v64, v142, v75
	ds_read_b128 v[98:101], v64 offset:6144
	ds_read_b128 v[102:105], v64 offset:4096
	ds_read_b128 v[106:109], v64 offset:2048
	ds_read_b128 v[110:113], v64
	v_readlane_b32 s36, v165, 23
	s_and_b64 s[0:1], s[28:29], exec
	v_readlane_b32 s48, v165, 35
	v_readlane_b32 s49, v165, 36
	s_cselect_b32 s1, s49, s25
	s_cselect_b32 s0, s48, s24
	s_waitcnt lgkmcnt(0)
	v_mfma_f32_16x16x32_bf16 v[64:67], v[94:97], v[110:113], v[60:63]
	s_lshl_b32 s2, s22, 7
	v_readlane_b32 s72, v166, 39
	v_readlane_b32 s84, v166, 51
	v_lshlrev_b32_e32 v60, 6, v71
	v_lshlrev_b32_e32 v61, 2, v72
	v_or3_b32 v60, v60, s2, v61
	s_lshl_b32 s2, s20, 7
	v_lshl_add_u32 v62, v68, 6, s2
	v_or_b32_e32 v62, v62, v73
	v_ashrrev_i32_e32 v63, 31, v62
	v_ashrrev_i32_e32 v61, 31, v60
	v_readlane_b32 s85, v166, 52
	v_lshlrev_b64 v[72:73], 11, v[62:63]
	v_lshl_add_u64 v[72:73], s[0:1], 0, v[72:73]
	v_lshl_add_u64 v[80:81], v[60:61], 2, s[84:85]
	v_lshlrev_b64 v[60:61], 1, v[60:61]
	v_mfma_f32_16x16x32_bf16 v[12:15], v[76:79], v[110:113], v[12:15]
	v_readlane_b32 s46, v165, 33
	v_readlane_b32 s47, v165, 34
	v_readlane_b32 s37, v165, 24
	v_mfma_f32_16x16x32_bf16 v[8:11], v[76:79], v[106:109], v[8:11]
	v_readlane_b32 s38, v165, 25
	v_readlane_b32 s39, v165, 26
	v_readlane_b32 s40, v165, 27
	v_mfma_f32_16x16x32_bf16 v[4:7], v[76:79], v[102:105], v[4:7]
	v_readlane_b32 s41, v165, 28
	v_readlane_b32 s42, v165, 29
	v_readlane_b32 s43, v165, 30
	v_mfma_f32_16x16x32_bf16 v[0:3], v[76:79], v[98:101], v[0:3]
	v_lshl_add_u64 v[78:79], v[72:73], 0, v[60:61]
	v_or_b32_e32 v72, 16, v62
	v_ashrrev_i32_e32 v73, 31, v72
	v_lshlrev_b64 v[72:73], 11, v[72:73]
	v_lshl_add_u64 v[72:73], s[0:1], 0, v[72:73]
	v_lshl_add_u64 v[76:77], v[72:73], 0, v[60:61]
	v_or_b32_e32 v72, 32, v62
	v_or_b32_e32 v62, 48, v62
	v_ashrrev_i32_e32 v73, 31, v72
	v_ashrrev_i32_e32 v63, 31, v62
	v_lshlrev_b64 v[72:73], 11, v[72:73]
	v_lshlrev_b64 v[62:63], 11, v[62:63]
	v_lshl_add_u64 v[72:73], s[0:1], 0, v[72:73]
	v_lshl_add_u64 v[62:63], s[0:1], 0, v[62:63]
	v_lshl_add_u64 v[74:75], v[72:73], 0, v[60:61]
	v_lshl_add_u64 v[72:73], v[62:63], 0, v[60:61]
	global_load_dwordx4 v[60:63], v[80:81], off
	v_mfma_f32_16x16x32_bf16 v[56:59], v[94:97], v[106:109], v[56:59]
	v_readlane_b32 s44, v165, 31
	v_readlane_b32 s45, v165, 32
	v_readlane_b32 s50, v165, 37
	v_mfma_f32_16x16x32_bf16 v[52:55], v[94:97], v[102:105], v[52:55]
	v_readlane_b32 s51, v165, 38
	v_readlane_b32 s73, v166, 40
	v_readlane_b32 s74, v166, 41
	v_mfma_f32_16x16x32_bf16 v[48:51], v[94:97], v[98:101], v[48:51]
	v_readlane_b32 s75, v166, 42
	v_readlane_b32 s76, v166, 43
	v_readlane_b32 s77, v166, 44
	v_mfma_f32_16x16x32_bf16 v[44:47], v[90:93], v[110:113], v[44:47]
	v_readlane_b32 s78, v166, 45
	v_readlane_b32 s79, v166, 46
	v_readlane_b32 s80, v166, 47
	v_mfma_f32_16x16x32_bf16 v[40:43], v[90:93], v[106:109], v[40:43]
	v_readlane_b32 s81, v166, 48
	v_readlane_b32 s82, v166, 49
	v_readlane_b32 s83, v166, 50
	v_mfma_f32_16x16x32_bf16 v[36:39], v[90:93], v[102:105], v[36:39]
	v_readlane_b32 s86, v166, 53
	v_readlane_b32 s87, v166, 54
	s_waitcnt vmcnt(0)
; DEV unsigned pack2(float a, float b) { return (unsigned)f2bf(a) | ((unsigned)f2bf(b) << 16); }
; DEV void phase_ml_in(const Params& p, unsigned char* smem) {
;     ...
;           for (int n = 0; n < 4; ++n) {
;             const int col = nt * 128 + wc * 64 + n * 16 + fq * 4;
;             const float4 b4 = *reinterpret_cast<const float4*>(p.b_in + col);
; #pragma unroll
;             for (int m = 0; m < 4; ++m) {
;               const int row = mt * 128 + wr * 64 + m * 16 + fr;
;               *reinterpret_cast<uint2*>(obase + (size_t)row * 1024 + col) =
;                   make_uint2(pack2(acc[m][n][0] + b4.x, acc[m][n][1] + b4.y), pack2(acc[m][n][2] + b4.z, acc[m][n][3] + b4.w));
;             }
	v_pk_add_f32 v[66:67], v[66:67], v[62:63]
	v_pk_add_f32 v[64:65], v[64:65], v[60:61]
	v_and_b32_sdwa v68, v66, v85 dst_sel:DWORD dst_unused:UNUSED_PAD src0_sel:WORD_1 src1_sel:DWORD
	v_and_b32_sdwa v71, v64, v85 dst_sel:DWORD dst_unused:UNUSED_PAD src0_sel:WORD_1 src1_sel:DWORD
	v_add3_u32 v64, v64, v71, s55
	v_add3_u32 v66, v66, v68, s55
	v_and_b32_sdwa v68, v67, v85 dst_sel:DWORD dst_unused:UNUSED_PAD src0_sel:WORD_1 src1_sel:DWORD
	v_and_b32_sdwa v71, v65, v85 dst_sel:DWORD dst_unused:UNUSED_PAD src0_sel:WORD_1 src1_sel:DWORD
	v_add3_u32 v67, v67, v68, s55
	v_add3_u32 v65, v65, v71, s55
	v_and_b32_e32 v67, 0xffff0000, v67
	v_and_b32_e32 v68, 0xffff0000, v65
	v_or_b32_sdwa v65, v67, v66 dst_sel:DWORD dst_unused:UNUSED_PAD src0_sel:DWORD src1_sel:WORD_1
	v_or_b32_sdwa v64, v68, v64 dst_sel:DWORD dst_unused:UNUSED_PAD src0_sel:DWORD src1_sel:WORD_1
	v_pk_add_f32 v[58:59], v[58:59], v[62:63]
	v_pk_add_f32 v[56:57], v[56:57], v[60:61]
	global_store_dwordx2 v[78:79], v[64:65], off
	v_and_b32_sdwa v64, v58, v85 dst_sel:DWORD dst_unused:UNUSED_PAD src0_sel:WORD_1 src1_sel:DWORD
	v_and_b32_sdwa v65, v56, v85 dst_sel:DWORD dst_unused:UNUSED_PAD src0_sel:WORD_1 src1_sel:DWORD
	v_add3_u32 v56, v56, v65, s55
	v_add3_u32 v58, v58, v64, s55
	v_and_b32_sdwa v64, v59, v85 dst_sel:DWORD dst_unused:UNUSED_PAD src0_sel:WORD_1 src1_sel:DWORD
	v_and_b32_sdwa v65, v57, v85 dst_sel:DWORD dst_unused:UNUSED_PAD src0_sel:WORD_1 src1_sel:DWORD
	v_add3_u32 v59, v59, v64, s55
	v_add3_u32 v57, v57, v65, s55
	v_and_b32_e32 v59, 0xffff0000, v59
	v_and_b32_e32 v64, 0xffff0000, v57
	v_or_b32_sdwa v57, v59, v58 dst_sel:DWORD dst_unused:UNUSED_PAD src0_sel:DWORD src1_sel:WORD_1
	v_or_b32_sdwa v56, v64, v56 dst_sel:DWORD dst_unused:UNUSED_PAD src0_sel:DWORD src1_sel:WORD_1
	v_pk_add_f32 v[54:55], v[54:55], v[62:63]
	v_pk_add_f32 v[52:53], v[52:53], v[60:61]
	global_store_dwordx2 v[76:77], v[56:57], off
	v_and_b32_sdwa v56, v54, v85 dst_sel:DWORD dst_unused:UNUSED_PAD src0_sel:WORD_1 src1_sel:DWORD
	v_and_b32_sdwa v57, v52, v85 dst_sel:DWORD dst_unused:UNUSED_PAD src0_sel:WORD_1 src1_sel:DWORD
	v_add3_u32 v52, v52, v57, s55
	v_add3_u32 v54, v54, v56, s55
	v_and_b32_sdwa v56, v55, v85 dst_sel:DWORD dst_unused:UNUSED_PAD src0_sel:WORD_1 src1_sel:DWORD
	v_and_b32_sdwa v57, v53, v85 dst_sel:DWORD dst_unused:UNUSED_PAD src0_sel:WORD_1 src1_sel:DWORD
	v_add3_u32 v55, v55, v56, s55
	v_add3_u32 v53, v53, v57, s55
	v_and_b32_e32 v55, 0xffff0000, v55
	v_and_b32_e32 v56, 0xffff0000, v53
	v_or_b32_sdwa v53, v55, v54 dst_sel:DWORD dst_unused:UNUSED_PAD src0_sel:DWORD src1_sel:WORD_1
	v_or_b32_sdwa v52, v56, v52 dst_sel:DWORD dst_unused:UNUSED_PAD src0_sel:DWORD src1_sel:WORD_1
	v_pk_add_f32 v[50:51], v[50:51], v[62:63]
	v_pk_add_f32 v[48:49], v[48:49], v[60:61]
	global_store_dwordx2 v[74:75], v[52:53], off
	v_and_b32_sdwa v52, v50, v85 dst_sel:DWORD dst_unused:UNUSED_PAD src0_sel:WORD_1 src1_sel:DWORD
	v_and_b32_sdwa v53, v48, v85 dst_sel:DWORD dst_unused:UNUSED_PAD src0_sel:WORD_1 src1_sel:DWORD
	v_add3_u32 v48, v48, v53, s55
	v_add3_u32 v50, v50, v52, s55
	v_and_b32_sdwa v52, v51, v85 dst_sel:DWORD dst_unused:UNUSED_PAD src0_sel:WORD_1 src1_sel:DWORD
	v_and_b32_sdwa v53, v49, v85 dst_sel:DWORD dst_unused:UNUSED_PAD src0_sel:WORD_1 src1_sel:DWORD
	v_add3_u32 v51, v51, v52, s55
	v_add3_u32 v49, v49, v53, s55
	v_and_b32_e32 v51, 0xffff0000, v51
	v_and_b32_e32 v52, 0xffff0000, v49
	v_or_b32_sdwa v49, v51, v50 dst_sel:DWORD dst_unused:UNUSED_PAD src0_sel:DWORD src1_sel:WORD_1
	v_or_b32_sdwa v48, v52, v48 dst_sel:DWORD dst_unused:UNUSED_PAD src0_sel:DWORD src1_sel:WORD_1
	global_store_dwordx2 v[72:73], v[48:49], off
	global_load_dwordx4 v[48:51], v[80:81], off offset:64
	v_mfma_f32_16x16x32_bf16 v[32:35], v[90:93], v[98:101], v[32:35]
	s_waitcnt vmcnt(0)
	v_pk_add_f32 v[46:47], v[46:47], v[50:51]
	v_pk_add_f32 v[44:45], v[44:45], v[48:49]
	v_and_b32_sdwa v52, v46, v85 dst_sel:DWORD dst_unused:UNUSED_PAD src0_sel:WORD_1 src1_sel:DWORD
	v_and_b32_sdwa v53, v44, v85 dst_sel:DWORD dst_unused:UNUSED_PAD src0_sel:WORD_1 src1_sel:DWORD
	v_add3_u32 v44, v44, v53, s55
	v_add3_u32 v46, v46, v52, s55
	v_and_b32_sdwa v52, v47, v85 dst_sel:DWORD dst_unused:UNUSED_PAD src0_sel:WORD_1 src1_sel:DWORD
	v_and_b32_sdwa v53, v45, v85 dst_sel:DWORD dst_unused:UNUSED_PAD src0_sel:WORD_1 src1_sel:DWORD
	v_add3_u32 v47, v47, v52, s55
	v_add3_u32 v45, v45, v53, s55
	v_and_b32_e32 v47, 0xffff0000, v47
	v_and_b32_e32 v52, 0xffff0000, v45
	v_or_b32_sdwa v45, v47, v46 dst_sel:DWORD dst_unused:UNUSED_PAD src0_sel:DWORD src1_sel:WORD_1
	v_or_b32_sdwa v44, v52, v44 dst_sel:DWORD dst_unused:UNUSED_PAD src0_sel:DWORD src1_sel:WORD_1
	v_pk_add_f32 v[42:43], v[42:43], v[50:51]
	v_pk_add_f32 v[40:41], v[40:41], v[48:49]
	global_store_dwordx2 v[78:79], v[44:45], off offset:32
	v_and_b32_sdwa v44, v42, v85 dst_sel:DWORD dst_unused:UNUSED_PAD src0_sel:WORD_1 src1_sel:DWORD
	v_and_b32_sdwa v45, v40, v85 dst_sel:DWORD dst_unused:UNUSED_PAD src0_sel:WORD_1 src1_sel:DWORD
	v_add3_u32 v40, v40, v45, s55
	v_add3_u32 v42, v42, v44, s55
	v_and_b32_sdwa v44, v43, v85 dst_sel:DWORD dst_unused:UNUSED_PAD src0_sel:WORD_1 src1_sel:DWORD
	v_and_b32_sdwa v45, v41, v85 dst_sel:DWORD dst_unused:UNUSED_PAD src0_sel:WORD_1 src1_sel:DWORD
	v_add3_u32 v43, v43, v44, s55
	v_add3_u32 v41, v41, v45, s55
	v_and_b32_e32 v43, 0xffff0000, v43
	v_and_b32_e32 v44, 0xffff0000, v41
	v_or_b32_sdwa v41, v43, v42 dst_sel:DWORD dst_unused:UNUSED_PAD src0_sel:DWORD src1_sel:WORD_1
	v_or_b32_sdwa v40, v44, v40 dst_sel:DWORD dst_unused:UNUSED_PAD src0_sel:DWORD src1_sel:WORD_1
	v_pk_add_f32 v[38:39], v[38:39], v[50:51]
	v_pk_add_f32 v[36:37], v[36:37], v[48:49]
; DEV unsigned pack2(float a, float b) { return (unsigned)f2bf(a) | ((unsigned)f2bf(b) << 16); }
; DEV void phase_ml_in(const Params& p, unsigned char* smem) {
;     ...
;           for (int n = 0; n < 4; ++n) {
;             const int col = nt * 128 + wc * 64 + n * 16 + fq * 4;
;             const float4 b4 = *reinterpret_cast<const float4*>(p.b_in + col);
; #pragma unroll
;             for (int m = 0; m < 4; ++m) {
;               const int row = mt * 128 + wr * 64 + m * 16 + fr;
;               *reinterpret_cast<uint2*>(obase + (size_t)row * 1024 + col) =
;                   make_uint2(pack2(acc[m][n][0] + b4.x, acc[m][n][1] + b4.y), pack2(acc[m][n][2] + b4.z, acc[m][n][3] + b4.w));
;             }
;           }
	global_store_dwordx2 v[76:77], v[40:41], off offset:32
	v_and_b32_sdwa v40, v38, v85 dst_sel:DWORD dst_unused:UNUSED_PAD src0_sel:WORD_1 src1_sel:DWORD
	v_and_b32_sdwa v41, v36, v85 dst_sel:DWORD dst_unused:UNUSED_PAD src0_sel:WORD_1 src1_sel:DWORD
	v_add3_u32 v36, v36, v41, s55
	v_add3_u32 v38, v38, v40, s55
	v_and_b32_sdwa v40, v39, v85 dst_sel:DWORD dst_unused:UNUSED_PAD src0_sel:WORD_1 src1_sel:DWORD
	v_and_b32_sdwa v41, v37, v85 dst_sel:DWORD dst_unused:UNUSED_PAD src0_sel:WORD_1 src1_sel:DWORD
	v_add3_u32 v39, v39, v40, s55
	v_add3_u32 v37, v37, v41, s55
	v_and_b32_e32 v39, 0xffff0000, v39
	v_and_b32_e32 v40, 0xffff0000, v37
	v_or_b32_sdwa v37, v39, v38 dst_sel:DWORD dst_unused:UNUSED_PAD src0_sel:DWORD src1_sel:WORD_1
	v_or_b32_sdwa v36, v40, v36 dst_sel:DWORD dst_unused:UNUSED_PAD src0_sel:DWORD src1_sel:WORD_1
	v_pk_add_f32 v[34:35], v[34:35], v[50:51]
	v_pk_add_f32 v[32:33], v[32:33], v[48:49]
	global_store_dwordx2 v[74:75], v[36:37], off offset:32
	v_and_b32_sdwa v36, v34, v85 dst_sel:DWORD dst_unused:UNUSED_PAD src0_sel:WORD_1 src1_sel:DWORD
	v_and_b32_sdwa v37, v32, v85 dst_sel:DWORD dst_unused:UNUSED_PAD src0_sel:WORD_1 src1_sel:DWORD
	v_add3_u32 v32, v32, v37, s55
	v_add3_u32 v34, v34, v36, s55
	v_and_b32_sdwa v36, v35, v85 dst_sel:DWORD dst_unused:UNUSED_PAD src0_sel:WORD_1 src1_sel:DWORD
	v_and_b32_sdwa v37, v33, v85 dst_sel:DWORD dst_unused:UNUSED_PAD src0_sel:WORD_1 src1_sel:DWORD
	v_add3_u32 v35, v35, v36, s55
	v_add3_u32 v33, v33, v37, s55
	v_and_b32_e32 v35, 0xffff0000, v35
	v_and_b32_e32 v36, 0xffff0000, v33
	v_or_b32_sdwa v33, v35, v34 dst_sel:DWORD dst_unused:UNUSED_PAD src0_sel:DWORD src1_sel:WORD_1
	v_or_b32_sdwa v32, v36, v32 dst_sel:DWORD dst_unused:UNUSED_PAD src0_sel:DWORD src1_sel:WORD_1
	global_store_dwordx2 v[72:73], v[32:33], off offset:32
	global_load_dwordx4 v[32:35], v[80:81], off offset:128
	v_mfma_f32_16x16x32_bf16 v[28:31], v[86:89], v[110:113], v[28:31]
	v_mfma_f32_16x16x32_bf16 v[24:27], v[86:89], v[106:109], v[24:27]
	v_mfma_f32_16x16x32_bf16 v[20:23], v[86:89], v[102:105], v[20:23]
	s_waitcnt vmcnt(0)
	s_nop 4
	v_pk_add_f32 v[30:31], v[30:31], v[34:35]
	v_pk_add_f32 v[28:29], v[28:29], v[32:33]
	v_and_b32_sdwa v36, v30, v85 dst_sel:DWORD dst_unused:UNUSED_PAD src0_sel:WORD_1 src1_sel:DWORD
	v_and_b32_sdwa v37, v28, v85 dst_sel:DWORD dst_unused:UNUSED_PAD src0_sel:WORD_1 src1_sel:DWORD
	v_add3_u32 v28, v28, v37, s55
	v_add3_u32 v30, v30, v36, s55
	v_and_b32_sdwa v36, v31, v85 dst_sel:DWORD dst_unused:UNUSED_PAD src0_sel:WORD_1 src1_sel:DWORD
	v_and_b32_sdwa v37, v29, v85 dst_sel:DWORD dst_unused:UNUSED_PAD src0_sel:WORD_1 src1_sel:DWORD
	v_add3_u32 v31, v31, v36, s55
	v_add3_u32 v29, v29, v37, s55
	v_and_b32_e32 v31, 0xffff0000, v31
	v_and_b32_e32 v36, 0xffff0000, v29
	v_or_b32_sdwa v29, v31, v30 dst_sel:DWORD dst_unused:UNUSED_PAD src0_sel:DWORD src1_sel:WORD_1
	v_or_b32_sdwa v28, v36, v28 dst_sel:DWORD dst_unused:UNUSED_PAD src0_sel:DWORD src1_sel:WORD_1
	v_pk_add_f32 v[26:27], v[26:27], v[34:35]
	v_pk_add_f32 v[24:25], v[24:25], v[32:33]
	global_store_dwordx2 v[78:79], v[28:29], off offset:64
	v_and_b32_sdwa v28, v26, v85 dst_sel:DWORD dst_unused:UNUSED_PAD src0_sel:WORD_1 src1_sel:DWORD
	v_and_b32_sdwa v29, v24, v85 dst_sel:DWORD dst_unused:UNUSED_PAD src0_sel:WORD_1 src1_sel:DWORD
	v_add3_u32 v24, v24, v29, s55
	v_add3_u32 v26, v26, v28, s55
	v_and_b32_sdwa v28, v27, v85 dst_sel:DWORD dst_unused:UNUSED_PAD src0_sel:WORD_1 src1_sel:DWORD
	v_and_b32_sdwa v29, v25, v85 dst_sel:DWORD dst_unused:UNUSED_PAD src0_sel:WORD_1 src1_sel:DWORD
	v_add3_u32 v27, v27, v28, s55
	v_add3_u32 v25, v25, v29, s55
	v_and_b32_e32 v27, 0xffff0000, v27
	v_and_b32_e32 v28, 0xffff0000, v25
	v_or_b32_sdwa v25, v27, v26 dst_sel:DWORD dst_unused:UNUSED_PAD src0_sel:DWORD src1_sel:WORD_1
	v_or_b32_sdwa v24, v28, v24 dst_sel:DWORD dst_unused:UNUSED_PAD src0_sel:DWORD src1_sel:WORD_1
	v_pk_add_f32 v[22:23], v[22:23], v[34:35]
	v_pk_add_f32 v[20:21], v[20:21], v[32:33]
	v_mfma_f32_16x16x32_bf16 v[16:19], v[86:89], v[98:101], v[16:19]
	global_store_dwordx2 v[76:77], v[24:25], off offset:64
	v_and_b32_sdwa v24, v22, v85 dst_sel:DWORD dst_unused:UNUSED_PAD src0_sel:WORD_1 src1_sel:DWORD
	v_and_b32_sdwa v25, v20, v85 dst_sel:DWORD dst_unused:UNUSED_PAD src0_sel:WORD_1 src1_sel:DWORD
	v_add3_u32 v20, v20, v25, s55
	v_add3_u32 v22, v22, v24, s55
	v_and_b32_sdwa v24, v23, v85 dst_sel:DWORD dst_unused:UNUSED_PAD src0_sel:WORD_1 src1_sel:DWORD
	v_and_b32_sdwa v25, v21, v85 dst_sel:DWORD dst_unused:UNUSED_PAD src0_sel:WORD_1 src1_sel:DWORD
	v_add3_u32 v23, v23, v24, s55
	v_add3_u32 v21, v21, v25, s55
	v_and_b32_e32 v23, 0xffff0000, v23
	v_and_b32_e32 v24, 0xffff0000, v21
	v_or_b32_sdwa v21, v23, v22 dst_sel:DWORD dst_unused:UNUSED_PAD src0_sel:DWORD src1_sel:WORD_1
	v_or_b32_sdwa v20, v24, v20 dst_sel:DWORD dst_unused:UNUSED_PAD src0_sel:DWORD src1_sel:WORD_1
	v_pk_add_f32 v[18:19], v[18:19], v[34:35]
	v_pk_add_f32 v[16:17], v[16:17], v[32:33]
	global_store_dwordx2 v[74:75], v[20:21], off offset:64
	v_and_b32_sdwa v20, v18, v85 dst_sel:DWORD dst_unused:UNUSED_PAD src0_sel:WORD_1 src1_sel:DWORD
	v_and_b32_sdwa v21, v16, v85 dst_sel:DWORD dst_unused:UNUSED_PAD src0_sel:WORD_1 src1_sel:DWORD
	v_add3_u32 v16, v16, v21, s55
	v_add3_u32 v18, v18, v20, s55
	v_and_b32_sdwa v20, v19, v85 dst_sel:DWORD dst_unused:UNUSED_PAD src0_sel:WORD_1 src1_sel:DWORD
	v_and_b32_sdwa v21, v17, v85 dst_sel:DWORD dst_unused:UNUSED_PAD src0_sel:WORD_1 src1_sel:DWORD
	v_add3_u32 v19, v19, v20, s55
	v_add3_u32 v17, v17, v21, s55
	v_and_b32_e32 v19, 0xffff0000, v19
	v_and_b32_e32 v20, 0xffff0000, v17
	v_or_b32_sdwa v17, v19, v18 dst_sel:DWORD dst_unused:UNUSED_PAD src0_sel:DWORD src1_sel:WORD_1
	v_or_b32_sdwa v16, v20, v16 dst_sel:DWORD dst_unused:UNUSED_PAD src0_sel:DWORD src1_sel:WORD_1
	global_store_dwordx2 v[72:73], v[16:17], off offset:64
	global_load_dwordx4 v[16:19], v[80:81], off offset:192
	s_waitcnt vmcnt(0)
; DEV unsigned pack2(float a, float b) { return (unsigned)f2bf(a) | ((unsigned)f2bf(b) << 16); }
; DEV void phase_ml_in(const Params& p, unsigned char* smem) {
;     ...
;           for (int n = 0; n < 4; ++n) {
;             const int col = nt * 128 + wc * 64 + n * 16 + fq * 4;
;             const float4 b4 = *reinterpret_cast<const float4*>(p.b_in + col);
; #pragma unroll
;             for (int m = 0; m < 4; ++m) {
;               const int row = mt * 128 + wr * 64 + m * 16 + fr;
;               *reinterpret_cast<uint2*>(obase + (size_t)row * 1024 + col) =
;                   make_uint2(pack2(acc[m][n][0] + b4.x, acc[m][n][1] + b4.y), pack2(acc[m][n][2] + b4.z, acc[m][n][3] + b4.w));
;             }
;           }
	v_pk_add_f32 v[14:15], v[14:15], v[18:19]
	v_pk_add_f32 v[12:13], v[12:13], v[16:17]
	v_and_b32_sdwa v20, v14, v85 dst_sel:DWORD dst_unused:UNUSED_PAD src0_sel:WORD_1 src1_sel:DWORD
	v_and_b32_sdwa v21, v12, v85 dst_sel:DWORD dst_unused:UNUSED_PAD src0_sel:WORD_1 src1_sel:DWORD
	v_add3_u32 v12, v12, v21, s55
	v_add3_u32 v14, v14, v20, s55
	v_and_b32_sdwa v20, v15, v85 dst_sel:DWORD dst_unused:UNUSED_PAD src0_sel:WORD_1 src1_sel:DWORD
	v_and_b32_sdwa v21, v13, v85 dst_sel:DWORD dst_unused:UNUSED_PAD src0_sel:WORD_1 src1_sel:DWORD
	v_add3_u32 v15, v15, v20, s55
	v_add3_u32 v13, v13, v21, s55
	v_and_b32_e32 v15, 0xffff0000, v15
	v_and_b32_e32 v20, 0xffff0000, v13
	v_or_b32_sdwa v13, v15, v14 dst_sel:DWORD dst_unused:UNUSED_PAD src0_sel:DWORD src1_sel:WORD_1
	v_or_b32_sdwa v12, v20, v12 dst_sel:DWORD dst_unused:UNUSED_PAD src0_sel:DWORD src1_sel:WORD_1
	v_pk_add_f32 v[10:11], v[10:11], v[18:19]
	v_pk_add_f32 v[8:9], v[8:9], v[16:17]
	global_store_dwordx2 v[78:79], v[12:13], off offset:96
	v_and_b32_sdwa v12, v10, v85 dst_sel:DWORD dst_unused:UNUSED_PAD src0_sel:WORD_1 src1_sel:DWORD
	v_and_b32_sdwa v13, v8, v85 dst_sel:DWORD dst_unused:UNUSED_PAD src0_sel:WORD_1 src1_sel:DWORD
	v_add3_u32 v8, v8, v13, s55
	v_add3_u32 v10, v10, v12, s55
	v_and_b32_sdwa v12, v11, v85 dst_sel:DWORD dst_unused:UNUSED_PAD src0_sel:WORD_1 src1_sel:DWORD
	v_and_b32_sdwa v13, v9, v85 dst_sel:DWORD dst_unused:UNUSED_PAD src0_sel:WORD_1 src1_sel:DWORD
	v_add3_u32 v11, v11, v12, s55
	v_add3_u32 v9, v9, v13, s55
	v_and_b32_e32 v11, 0xffff0000, v11
	v_and_b32_e32 v12, 0xffff0000, v9
	v_or_b32_sdwa v9, v11, v10 dst_sel:DWORD dst_unused:UNUSED_PAD src0_sel:DWORD src1_sel:WORD_1
	v_or_b32_sdwa v8, v12, v8 dst_sel:DWORD dst_unused:UNUSED_PAD src0_sel:DWORD src1_sel:WORD_1
	v_pk_add_f32 v[6:7], v[6:7], v[18:19]
	v_pk_add_f32 v[4:5], v[4:5], v[16:17]
	global_store_dwordx2 v[76:77], v[8:9], off offset:96
	v_and_b32_sdwa v8, v6, v85 dst_sel:DWORD dst_unused:UNUSED_PAD src0_sel:WORD_1 src1_sel:DWORD
	v_and_b32_sdwa v9, v4, v85 dst_sel:DWORD dst_unused:UNUSED_PAD src0_sel:WORD_1 src1_sel:DWORD
	v_add3_u32 v4, v4, v9, s55
	v_add3_u32 v6, v6, v8, s55
	v_and_b32_sdwa v8, v7, v85 dst_sel:DWORD dst_unused:UNUSED_PAD src0_sel:WORD_1 src1_sel:DWORD
	v_and_b32_sdwa v9, v5, v85 dst_sel:DWORD dst_unused:UNUSED_PAD src0_sel:WORD_1 src1_sel:DWORD
	v_add3_u32 v7, v7, v8, s55
	v_add3_u32 v5, v5, v9, s55
	v_and_b32_e32 v7, 0xffff0000, v7
	v_and_b32_e32 v8, 0xffff0000, v5
	v_or_b32_sdwa v5, v7, v6 dst_sel:DWORD dst_unused:UNUSED_PAD src0_sel:DWORD src1_sel:WORD_1
	v_or_b32_sdwa v4, v8, v4 dst_sel:DWORD dst_unused:UNUSED_PAD src0_sel:DWORD src1_sel:WORD_1
	v_pk_add_f32 v[2:3], v[2:3], v[18:19]
	v_pk_add_f32 v[0:1], v[0:1], v[16:17]
	global_store_dwordx2 v[74:75], v[4:5], off offset:96
	v_and_b32_sdwa v4, v2, v85 dst_sel:DWORD dst_unused:UNUSED_PAD src0_sel:WORD_1 src1_sel:DWORD
	v_and_b32_sdwa v5, v0, v85 dst_sel:DWORD dst_unused:UNUSED_PAD src0_sel:WORD_1 src1_sel:DWORD
	v_add3_u32 v0, v0, v5, s55
	v_add3_u32 v2, v2, v4, s55
	v_and_b32_sdwa v4, v3, v85 dst_sel:DWORD dst_unused:UNUSED_PAD src0_sel:WORD_1 src1_sel:DWORD
	v_and_b32_sdwa v5, v1, v85 dst_sel:DWORD dst_unused:UNUSED_PAD src0_sel:WORD_1 src1_sel:DWORD
	v_add3_u32 v3, v3, v4, s55
	v_add3_u32 v1, v1, v5, s55
	v_and_b32_e32 v3, 0xffff0000, v3
	v_and_b32_e32 v4, 0xffff0000, v1
	v_or_b32_sdwa v1, v3, v2 dst_sel:DWORD dst_unused:UNUSED_PAD src0_sel:DWORD src1_sel:WORD_1
	v_or_b32_sdwa v0, v4, v0 dst_sel:DWORD dst_unused:UNUSED_PAD src0_sel:DWORD src1_sel:WORD_1
	global_store_dwordx2 v[72:73], v[0:1], off offset:96
	s_barrier
	s_branch .LBB0_844

; DEV int otid() { int t = threadIdx.x; asm volatile("" : "+v"(t)); return t; }
; template <bool SWAP, class RowA, class Epi>
; DEV void gemm_tile(unsigned char* smem, RowA rowA, const bf16_t* Bt, int K, Epi epi) {
;   const int tid = otid(), lane = tid & 63, wid = tid >> 6, wr = wid >> 1, wc = wid & 1, fr = lane & 15, fq = lane >> 4;
;   const int r0 = tid >> 2;
;   const int a_w = (r0 >> 2) & 3, g_w = (((a_w ^ (a_w >> 1)) & 1) << 1) | (a_w >> 1);
;   const int cc = ((tid & 3) ^ g_w) * 8;
;   const int a_r = (fr >> 2) & 3, g_r = (((a_r ^ (a_r >> 1)) & 1) << 1) | (a_r >> 1);
;   const int rdoff = fr * 64 + ((fq ^ g_r) * 16);
;   const bf16_t* a0 = rowA(r0) + cc;
;   const bf16_t* a1 = rowA(r0 + 64) + cc;
;   const bf16_t* b0 = Bt + (size_t)r0 * K + cc;
;   const bf16_t* b1 = Bt + (size_t)(r0 + 64) * K + cc;
;   f32x4 acc[4][4];
; #pragma unroll
;   for (int m = 0; m < 4; ++m)
; #pragma unroll
;     for (int n = 0; n < 4; ++n) acc[m][n] = f32x4{0.f, 0.f, 0.f, 0.f};
;   const int nk = K / 32;
;   auto stage = [&](int kt, int buf) {
;     unsigned char* SA = smem + buf * 16384 + tid * 16;
;     unsigned char* SB = SA + 8192;
;     const int ko = kt * 32;
;     glds16(a0 + ko, SA); glds16(a1 + ko, SA + 4096);
;     glds16(b0 + ko, SB); glds16(b1 + ko, SB + 4096);
;   };
;   stage(0, 0);
; DEV void phase_proj_out(const Params& p, const bf16_t* Abuf, const bf16_t* Wt, const float* bias, int nrows, unsigned char* smem, bool drain) {
;     ...
;   for (int t = blockIdx.x; t < ntile; t += gridDim.x) {
;     int nt = t & 7, mt = t >> 3;
;     const bf16_t* A = Abuf + (size_t)mt * 128 * 1024;
;     gemm_tile<true>(smem, [&](int r) { return A + (size_t)r * 1024; }, Wt + (size_t)nt * 128 * 1024, 1024,
.LBB0_2055:
	v_mov_b32_e32 v10, v122
	s_ashr_i32 s10, s14, 3
	v_lshrrev_b32_e32 v1, 4, v10
	v_lshrrev_b32_e32 v2, 5, v10
	v_readlane_b32 s48, v165, 39
	v_xor_b32_e32 v1, v1, v2
	s_and_b32 s0, s3, 7
	s_ashr_i32 s11, s10, 31
	v_readlane_b32 s52, v165, 43
	v_readlane_b32 s53, v165, 44
	v_lshlrev_b32_e32 v1, 1, v1
	s_lshl_b32 s0, s0, 18
	s_and_b32 s15, s14, 7
	s_lshl_b64 s[12:13], s[10:11], 18
	v_readlane_b32 s54, v165, 45
	v_readlane_b32 s55, v165, 46
	v_readlane_b32 s56, v165, 47
	v_readlane_b32 s57, v165, 48
	v_readlane_b32 s58, v165, 49
	v_readlane_b32 s59, v165, 50
	v_readlane_b32 s60, v165, 51
	v_readlane_b32 s61, v165, 52
	v_readlane_b32 s62, v165, 53
	v_readlane_b32 s63, v165, 54
	s_mov_b64 s[16:17], s[52:53]
	v_ashrrev_i32_e32 v0, 2, v10
	v_bfe_u32 v3, v10, 5, 1
	v_and_b32_e32 v1, 2, v1
	v_and_b32_e32 v2, 3, v10
	v_readlane_b32 s49, v165, 40
	v_readlane_b32 s50, v165, 41
	v_readlane_b32 s51, v165, 42
	s_add_u32 s12, s16, s12
	v_bitop3_b32 v11, v1, v2, v3 bitop3:0x36
	v_ashrrev_i32_e32 v1, 31, v0
	s_mov_b64 s[18:19], s[54:55]
	s_mov_b64 s[20:21], s[56:57]
	s_mov_b64 s[22:23], s[58:59]
	s_mov_b64 s[24:25], s[60:61]
	s_mov_b64 s[26:27], s[62:63]
	s_addc_u32 s13, s17, s13
	v_readlane_b32 s48, v165, 7
	v_lshlrev_b64 v[0:1], 11, v[0:1]
	s_lshl_b32 s11, s15, 18
	v_readlane_b32 s62, v165, 21
	v_lshl_add_u64 v[8:9], s[12:13], 0, v[0:1]
	v_lshlrev_b32_e32 v64, 4, v11
	v_lshlrev_b32_e32 v74, 4, v10
	s_add_u32 s16, s62, s11
	v_lshl_add_u64 v[2:3], v[0:1], 0, s[4:5]
	v_lshl_add_u64 v[66:67], v[8:9], 0, v[64:65]
	v_readfirstlane_b32 s11, v74
	v_add_u32_e32 v9, 0x1000, v74
	v_readlane_b32 s63, v165, 22
	v_lshl_add_u64 v[4:5], s[12:13], 0, v[2:3]
	s_mov_b32 m0, s11
	v_readfirstlane_b32 s11, v9
	s_addc_u32 s17, s63, 0
	v_lshl_add_u64 v[4:5], v[4:5], 0, v[64:65]
	v_add_u32_e32 v8, 0x2000, v74
	s_mov_b32 m0, s11
	v_lshl_add_u64 v[6:7], s[16:17], 0, v[0:1]
	v_readfirstlane_b32 s11, v8
	v_add_u32_e32 v4, 0x3000, v74
	v_lshl_add_u64 v[2:3], s[16:17], 0, v[2:3]
	v_lshl_add_u64 v[6:7], v[6:7], 0, v[64:65]
	s_mov_b32 m0, s11
	v_readfirstlane_b32 s11, v4
	v_lshl_add_u64 v[2:3], v[2:3], 0, v[64:65]
	s_mov_b32 m0, s11
	v_lshrrev_b32_e32 v12, 2, v10
	v_lshrrev_b32_e32 v13, 3, v10
	v_xor_b32_e32 v2, v12, v13
	v_lshlrev_b32_e32 v2, 1, v2
	v_lshl_add_u64 v[0:1], s[0:1], 0, v[0:1]
	v_bfe_u32 v71, v10, 4, 2
	v_bfe_u32 v14, v10, 3, 1
	v_and_b32_e32 v2, 2, v2
	v_and_b32_e32 v73, 15, v10
	v_or_b32_e32 v0, v0, v64
	v_bfe_u32 v70, v10, 6, 1
	v_bitop3_b32 v2, v2, v71, v14 bitop3:0x36
	v_ashrrev_i32_e32 v72, 7, v10
	v_lshlrev_b32_e32 v3, 6, v73
	v_lshl_add_u64 v[68:69], s[62:63], 0, v[0:1]
	v_mov_b32_e32 v0, 0
	v_lshl_or_b32 v75, v2, 4, v3
	v_lshlrev_b32_e32 v76, 12, v72
	v_lshlrev_b32_e32 v77, 12, v70
	s_mov_b32 s0, 0
	s_mov_b64 s[12:13], 0
	v_mov_b32_e32 v1, v0
	v_mov_b32_e32 v2, v0
	v_mov_b32_e32 v3, v0
	v_mov_b32_e32 v4, v0
	v_mov_b32_e32 v5, v0
	v_mov_b32_e32 v6, v0
	v_mov_b32_e32 v7, v0
	v_mov_b32_e32 v8, v0
	v_mov_b32_e32 v9, v0
	v_mov_b32_e32 v10, v0
	v_mov_b32_e32 v11, v0
	v_mov_b32_e32 v12, v0
	v_mov_b32_e32 v13, v0
	v_mov_b32_e32 v14, v0
	v_mov_b32_e32 v15, v0
	v_mov_b32_e32 v16, v0
	v_mov_b32_e32 v17, v0
	v_mov_b32_e32 v18, v0
	v_mov_b32_e32 v19, v0
	v_mov_b32_e32 v20, v0
	v_mov_b32_e32 v21, v0
	v_mov_b32_e32 v22, v0
	v_mov_b32_e32 v23, v0
	v_mov_b32_e32 v24, v0
	v_mov_b32_e32 v25, v0
	v_mov_b32_e32 v26, v0
	v_mov_b32_e32 v27, v0
	v_mov_b32_e32 v28, v0
	v_mov_b32_e32 v29, v0
	v_mov_b32_e32 v30, v0
	v_mov_b32_e32 v31, v0
	v_mov_b32_e32 v32, v0
	v_mov_b32_e32 v33, v0
	v_mov_b32_e32 v34, v0
	v_mov_b32_e32 v35, v0
	v_mov_b32_e32 v36, v0
	v_mov_b32_e32 v37, v0
	v_mov_b32_e32 v38, v0
	v_mov_b32_e32 v39, v0
	v_mov_b32_e32 v40, v0
	v_mov_b32_e32 v41, v0
	v_mov_b32_e32 v42, v0
	v_mov_b32_e32 v43, v0
	v_mov_b32_e32 v44, v0
	v_mov_b32_e32 v45, v0
	v_mov_b32_e32 v46, v0
	v_mov_b32_e32 v47, v0
	v_mov_b32_e32 v48, v0
	v_mov_b32_e32 v49, v0
	v_mov_b32_e32 v50, v0
	v_mov_b32_e32 v51, v0
	v_mov_b32_e32 v52, v0
	v_mov_b32_e32 v53, v0
	v_mov_b32_e32 v54, v0
	v_mov_b32_e32 v55, v0
	v_mov_b32_e32 v56, v0
	v_mov_b32_e32 v57, v0
	v_mov_b32_e32 v58, v0
	v_mov_b32_e32 v59, v0
	v_mov_b32_e32 v60, v0
	v_mov_b32_e32 v61, v0
	v_mov_b32_e32 v62, v0
	v_mov_b32_e32 v63, v0
	v_readlane_b32 s49, v165, 8
	v_readlane_b32 s50, v165, 9
	v_readlane_b32 s51, v165, 10
	v_readlane_b32 s52, v165, 11
	v_readlane_b32 s53, v165, 12
	v_readlane_b32 s54, v165, 13
	v_readlane_b32 s55, v165, 14
	v_readlane_b32 s56, v165, 15
	v_readlane_b32 s57, v165, 16
	v_readlane_b32 s58, v165, 17
	v_readlane_b32 s59, v165, 18
	v_readlane_b32 s60, v165, 19
	v_readlane_b32 s61, v165, 20
	v_and_b32_e32 v78, 15, v122
	v_bfe_u32 v79, v122, 4, 2
	v_bfe_u32 v80, v122, 1, 3
	v_xor_b32_e32 v79, v79, v80
	v_lshlrev_b32_e32 v79, 4, v79
	v_lshl_or_b32 v75, v78, 7, v79
	v_lshlrev_b32_e32 v76, 1, v76
	v_lshlrev_b32_e32 v77, 1, v77
	v_and_b32_e32 v78, 7, v122
	v_bfe_u32 v79, v122, 4, 3
	v_xor_b32_e32 v78, v78, v79
	v_lshlrev_b32_e32 v78, 4, v78
	v_lshrrev_b32_e32 v79, 3, v122
	v_lshl_or_b32 v78, v79, 11, v78
	v_bfe_u32 v79, v122, 4, 2
	v_lshrrev_b32_e32 v80, 1, v79
	v_xor_b32_e32 v81, v79, v80
	v_and_b32_e32 v81, 1, v81
	v_lshl_or_b32 v80, v81, 1, v80
	v_and_b32_e32 v79, 3, v122
	v_xor_b32_e32 v79, v79, v80
	v_lshlrev_b32_e32 v79, 4, v79
	v_lshrrev_b32_e32 v80, 2, v122
	v_lshl_or_b32 v79, v80, 11, v79
	v_sub_u32_e32 v78, v78, v79
	v_ashrrev_i32_e32 v79, 31, v78
	v_lshl_add_u64 v[66:67], v[66:67], 0, v[78:79]
	v_lshl_add_u64 v[68:69], v[68:69], 0, v[78:79]
	v_mov_b32_e32 v140, 0x10000
	v_mov_b32_e32 v141, 0
; template <bool SWAP, class RowA, class Epi>
; DEV void gemm_tile(unsigned char* smem, RowA rowA, const bf16_t* Bt, int K, Epi epi) {
;     ...
;   auto stage = [&](int kt, int buf) {
;     unsigned char* SA = smem + buf * 16384 + tid * 16;
;     unsigned char* SB = SA + 8192;
;     const int ko = kt * 32;
;     glds16(a0 + ko, SA); glds16(a1 + ko, SA + 4096);
;     glds16(b0 + ko, SB); glds16(b1 + ko, SB + 4096);
;   };
;     ...
;   for (int t = 0; t < nk; ++t) {
;     asm volatile("s_waitcnt vmcnt(0)" ::: "memory");
;     __syncthreads();
;     if (t + 1 < nk) stage(t + 1, (t + 1) & 1);
.LBB0_2056:
	s_bitcmp1_b32 s12, 6
	s_cbranch_scc1 .Lpair_odd_2056
	s_waitcnt lgkmcnt(0)
	s_barrier
	v_readfirstlane_b32 s16, v74
	s_mov_b32 m0, s16
	v_lshl_add_u64 v[78:79], v[66:67], 0, s[12:13]
	global_load_lds_dwordx4 v[78:79], off
	s_add_i32 m0, m0, 0x1000
	v_lshl_add_u64 v[80:81], v[78:79], 0, v[140:141]
	global_load_lds_dwordx4 v[80:81], off
	s_add_i32 m0, m0, 0x1000
	v_lshl_add_u64 v[78:79], v[80:81], 0, v[140:141]
	global_load_lds_dwordx4 v[78:79], off
	s_add_i32 m0, m0, 0x1000
	v_lshl_add_u64 v[80:81], v[78:79], 0, v[140:141]
	global_load_lds_dwordx4 v[80:81], off
	s_add_i32 m0, m0, 0x1000
	v_lshl_add_u64 v[78:79], v[68:69], 0, s[12:13]
	global_load_lds_dwordx4 v[78:79], off
	s_add_i32 m0, m0, 0x1000
	v_lshl_add_u64 v[80:81], v[78:79], 0, v[140:141]
	global_load_lds_dwordx4 v[80:81], off
	s_add_i32 m0, m0, 0x1000
	v_lshl_add_u64 v[78:79], v[80:81], 0, v[140:141]
	global_load_lds_dwordx4 v[78:79], off
	s_add_i32 m0, m0, 0x1000
	v_lshl_add_u64 v[80:81], v[78:79], 0, v[140:141]
	global_load_lds_dwordx4 v[80:81], off
	s_waitcnt vmcnt(0)
	s_barrier
; template <bool SWAP, class RowA, class Epi>
; DEV void gemm_tile(unsigned char* smem, RowA rowA, const bf16_t* Bt, int K, Epi epi) {
;     ...
;     const unsigned char* SA = smem + (t & 1) * 16384;
;     const unsigned char* SB = SA + 8192;
;     bf16x8 At[4], Bl[4];
; #pragma unroll
;     for (int m = 0; m < 4; ++m) At[m] = *reinterpret_cast<const bf16x8*>(SA + (wr * 64 + m * 16) * 64 + rdoff);
; #pragma unroll
;     for (int n = 0; n < 4; ++n) Bl[n] = *reinterpret_cast<const bf16x8*>(SB + (wc * 64 + n * 16) * 64 + rdoff);
; #pragma unroll
;     for (int m = 0; m < 4; ++m)
; #pragma unroll
;       for (int n = 0; n < 4; ++n)
;         acc[m][n] = SWAP ? __builtin_amdgcn_mfma_f32_16x16x32_bf16(Bl[n], At[m], acc[m][n], 0, 0, 0)
;                          : __builtin_amdgcn_mfma_f32_16x16x32_bf16(At[m], Bl[n], acc[m][n], 0, 0, 0);
; DEV void phase_proj_out(const Params& p, const bf16_t* Abuf, const bf16_t* Wt, const float* bias, int nrows, unsigned char* smem, bool drain) {
;     ...
;       [&](f32x4 (&acc)[4][4], int wr, int wc, int fr, int fq) {
; #pragma unroll
;         for (int n = 0; n < 4; ++n) {
;           const int col = nt * 128 + wc * 64 + n * 16 + fq * 4;
;           float4 bv = make_float4(0.f, 0.f, 0.f, 0.f);
;           if (bias) bv = *reinterpret_cast<const float4*>(bias + col);
; #pragma unroll
;           for (int m = 0; m < 4; ++m) {
;             const int row = mt * 128 + wr * 64 + m * 16 + fr;
;             *reinterpret_cast<float4*>(p.yx + (size_t)row * 1024 + col) =
;                 make_float4(acc[m][n][0] + bv.x, acc[m][n][1] + bv.y, acc[m][n][2] + bv.z, acc[m][n][3] + bv.w);
;           }
;         }
.Lpair_odd_2056:
	s_and_b32 s0, s12, 64
	v_xor_b32_e32 v64, s0, v75
	v_add_u32_e32 v102, v64, v76
	v_add_u32_e32 v64, v64, v77
	ds_read_b128 v[78:81], v64 offset:16384
	ds_read_b128 v[82:85], v64 offset:18432
	ds_read_b128 v[86:89], v102
	ds_read_b128 v[90:93], v102 offset:2048
	ds_read_b128 v[94:97], v64 offset:20480
	ds_read_b128 v[98:101], v64 offset:22528
	s_waitcnt lgkmcnt(0)
	v_mfma_f32_16x16x32_bf16 v[60:63], v[78:81], v[86:89], v[60:63]
	s_add_u32 s12, s12, 64
	s_addc_u32 s13, s13, 0
	s_cmpk_eq_i32 s12, 0x7c0
	v_mfma_f32_16x16x32_bf16 v[56:59], v[82:85], v[86:89], v[56:59]
	v_mfma_f32_16x16x32_bf16 v[52:55], v[94:97], v[86:89], v[52:55]
	v_mfma_f32_16x16x32_bf16 v[48:51], v[98:101], v[86:89], v[48:51]
	v_mfma_f32_16x16x32_bf16 v[44:47], v[78:81], v[90:93], v[44:47]
	v_mfma_f32_16x16x32_bf16 v[40:43], v[82:85], v[90:93], v[40:43]
	v_mfma_f32_16x16x32_bf16 v[36:39], v[94:97], v[90:93], v[36:39]
	v_mfma_f32_16x16x32_bf16 v[32:35], v[98:101], v[90:93], v[32:35]
	ds_read_b128 v[86:89], v102 offset:4096
	ds_read_b128 v[90:93], v102 offset:6144
	s_waitcnt lgkmcnt(0)
	v_mfma_f32_16x16x32_bf16 v[28:31], v[78:81], v[86:89], v[28:31]
	v_mfma_f32_16x16x32_bf16 v[24:27], v[82:85], v[86:89], v[24:27]
	v_mfma_f32_16x16x32_bf16 v[20:23], v[94:97], v[86:89], v[20:23]
	v_mfma_f32_16x16x32_bf16 v[16:19], v[98:101], v[86:89], v[16:19]
	v_mfma_f32_16x16x32_bf16 v[12:15], v[78:81], v[90:93], v[12:15]
	v_mfma_f32_16x16x32_bf16 v[8:11], v[82:85], v[90:93], v[8:11]
	v_mfma_f32_16x16x32_bf16 v[4:7], v[94:97], v[90:93], v[4:7]
	v_mfma_f32_16x16x32_bf16 v[0:3], v[98:101], v[90:93], v[0:3]
	s_cbranch_scc0 .LBB0_2056
	v_xor_b32_e32 v142, 64, v75
	v_add_u32_e32 v64, v142, v77
	s_waitcnt vmcnt(0)
	s_waitcnt vmcnt(0)
	s_barrier
	ds_read_b128 v[66:69], v64 offset:16384
	ds_read_b128 v[78:81], v64 offset:18432
	ds_read_b128 v[82:85], v64 offset:20480
	ds_read_b128 v[86:89], v64 offset:22528
	v_add_u32_e32 v94, v142, v76
	ds_read_b128 v[74:77], v94
	s_lshl_b32 s0, s10, 7
	v_lshl_add_u32 v64, v72, 6, s0
	s_waitcnt lgkmcnt(0)
	v_mfma_f32_16x16x32_bf16 v[60:63], v[66:69], v[74:77], v[60:63]
	v_or_b32_e32 v72, v64, v73
	v_ashrrev_i32_e32 v73, 31, v72
	s_lshl_b32 s0, s15, 9
	v_mfma_f32_16x16x32_bf16 v[56:59], v[78:81], v[74:77], v[56:59]
	v_lshlrev_b64 v[98:99], 12, v[72:73]
	v_lshl_or_b32 v64, v70, 8, s0
	v_lshl_add_u64 v[98:99], s[44:45], 0, v[98:99]
	v_mfma_f32_16x16x32_bf16 v[52:55], v[82:85], v[74:77], v[52:55]
	v_lshl_or_b32 v64, v71, 4, v64
	v_lshl_add_u64 v[70:71], v[98:99], 0, v[64:65]
	v_pk_add_f32 v[60:61], v[60:61], 0 op_sel_hi:[1,0]
	v_mfma_f32_16x16x32_bf16 v[48:51], v[86:89], v[74:77], v[48:51]
	ds_read_b128 v[74:77], v94 offset:2048
	ds_read_b128 v[90:93], v94 offset:6144
	ds_read_b128 v[94:97], v94 offset:4096
	v_pk_add_f32 v[62:63], v[62:63], 0 op_sel_hi:[1,0]
	global_store_dwordx4 v[70:71], v[60:63], off
	s_waitcnt lgkmcnt(2)
	v_mfma_f32_16x16x32_bf16 v[44:47], v[66:69], v[74:77], v[44:47]
	s_add_i32 s14, s14, s33
	v_or_b32_e32 v60, 16, v72
	v_ashrrev_i32_e32 v61, 31, v60
	v_lshlrev_b64 v[60:61], 12, v[60:61]
	v_lshl_add_u64 v[60:61], s[44:45], 0, v[60:61]
	v_lshl_add_u64 v[60:61], v[60:61], 0, v[64:65]
	s_nop 1
	v_pk_add_f32 v[44:45], v[44:45], 0 op_sel_hi:[1,0]
	v_pk_add_f32 v[46:47], v[46:47], 0 op_sel_hi:[1,0]
	s_waitcnt lgkmcnt(0)
	v_mfma_f32_16x16x32_bf16 v[28:31], v[66:69], v[94:97], v[28:31]
	global_store_dwordx4 v[60:61], v[44:47], off
	s_add_i32 s3, s3, s33
	s_cmpk_gt_i32 s14, 0x3ff
	v_or_b32_e32 v44, 32, v72
	v_ashrrev_i32_e32 v45, 31, v44
	v_lshlrev_b64 v[44:45], 12, v[44:45]
	v_lshl_add_u64 v[44:45], s[44:45], 0, v[44:45]
	v_lshl_add_u64 v[44:45], v[44:45], 0, v[64:65]
	v_pk_add_f32 v[28:29], v[28:29], 0 op_sel_hi:[1,0]
	v_pk_add_f32 v[30:31], v[30:31], 0 op_sel_hi:[1,0]
	v_mfma_f32_16x16x32_bf16 v[12:15], v[66:69], v[90:93], v[12:15]
	global_store_dwordx4 v[44:45], v[28:31], off
	v_mfma_f32_16x16x32_bf16 v[8:11], v[78:81], v[90:93], v[8:11]
	s_nop 0
	v_or_b32_e32 v28, 48, v72
	v_ashrrev_i32_e32 v29, 31, v28
	v_lshlrev_b64 v[28:29], 12, v[28:29]
	v_mfma_f32_16x16x32_bf16 v[4:7], v[82:85], v[90:93], v[4:7]
	v_lshl_add_u64 v[28:29], s[44:45], 0, v[28:29]
	v_lshl_add_u64 v[28:29], v[28:29], 0, v[64:65]
	v_pk_add_f32 v[12:13], v[12:13], 0 op_sel_hi:[1,0]
	v_mfma_f32_16x16x32_bf16 v[40:43], v[78:81], v[74:77], v[40:43]
	v_add_f32_e64 v14, v14, 0
	v_add_f32_e64 v15, v15, 0
	v_pk_add_f32 v[8:9], v[8:9], 0 op_sel_hi:[1,0]
	v_pk_add_f32 v[10:11], v[10:11], 0 op_sel_hi:[1,0]
	v_mfma_f32_16x16x32_bf16 v[36:39], v[82:85], v[74:77], v[36:39]
	v_add_f32_e64 v4, v4, 0
	v_add_f32_e64 v5, v5, 0
	v_pk_add_f32 v[6:7], v[6:7], 0 op_sel_hi:[1,0]
	global_store_dwordx4 v[28:29], v[12:15], off
	v_mfma_f32_16x16x32_bf16 v[32:35], v[86:89], v[74:77], v[32:35]
	global_store_dwordx4 v[28:29], v[8:11], off offset:64
	v_pk_add_f32 v[12:13], v[56:57], 0 op_sel_hi:[1,0]
	v_pk_add_f32 v[14:15], v[58:59], 0 op_sel_hi:[1,0]
	v_mfma_f32_16x16x32_bf16 v[24:27], v[78:81], v[94:97], v[24:27]
	v_add_f32_e64 v8, v52, 0
	v_add_f32_e64 v9, v53, 0
	v_pk_add_f32 v[10:11], v[54:55], 0 op_sel_hi:[1,0]
	global_store_dwordx4 v[28:29], v[4:7], off offset:128
	v_mfma_f32_16x16x32_bf16 v[20:23], v[82:85], v[94:97], v[20:23]
	global_store_dwordx4 v[70:71], v[12:15], off offset:64
	v_pk_add_f32 v[4:5], v[48:49], 0 op_sel_hi:[1,0]
	v_pk_add_f32 v[6:7], v[50:51], 0 op_sel_hi:[1,0]
	v_mfma_f32_16x16x32_bf16 v[16:19], v[86:89], v[94:97], v[16:19]
	v_add_f32_e64 v12, v40, 0
	v_add_f32_e64 v13, v41, 0
	v_pk_add_f32 v[14:15], v[42:43], 0 op_sel_hi:[1,0]
	global_store_dwordx4 v[70:71], v[8:11], off offset:128
	v_mfma_f32_16x16x32_bf16 v[0:3], v[86:89], v[90:93], v[0:3]
	global_store_dwordx4 v[70:71], v[4:7], off offset:192
	v_pk_add_f32 v[8:9], v[36:37], 0 op_sel_hi:[1,0]
	v_pk_add_f32 v[10:11], v[38:39], 0 op_sel_hi:[1,0]
	v_pk_add_f32 v[4:5], v[32:33], 0 op_sel_hi:[1,0]
	v_pk_add_f32 v[6:7], v[34:35], 0 op_sel_hi:[1,0]
	global_store_dwordx4 v[60:61], v[12:15], off offset:64
	global_store_dwordx4 v[60:61], v[8:11], off offset:128
	global_store_dwordx4 v[60:61], v[4:7], off offset:192
	v_pk_add_f32 v[12:13], v[24:25], 0 op_sel_hi:[1,0]
	v_pk_add_f32 v[14:15], v[26:27], 0 op_sel_hi:[1,0]
	v_pk_add_f32 v[8:9], v[20:21], 0 op_sel_hi:[1,0]
	v_pk_add_f32 v[10:11], v[22:23], 0 op_sel_hi:[1,0]
	v_pk_add_f32 v[4:5], v[16:17], 0 op_sel_hi:[1,0]
	v_pk_add_f32 v[6:7], v[18:19], 0 op_sel_hi:[1,0]
	v_pk_add_f32 v[0:1], v[0:1], 0 op_sel_hi:[1,0]
	v_pk_add_f32 v[2:3], v[2:3], 0 op_sel_hi:[1,0]
	global_store_dwordx4 v[44:45], v[12:15], off offset:64
	global_store_dwordx4 v[44:45], v[8:11], off offset:128
	global_store_dwordx4 v[44:45], v[4:7], off offset:192
	global_store_dwordx4 v[28:29], v[0:3], off offset:192
	s_barrier
	s_cbranch_scc0 .LBB0_2055
	s_branch .LBB0_2053
